# redundant post-barrier lgkmcnt(0) removed ahead of 36 MFMA blocks in the GEMM mainloops
# baseline (speedup 1.0000x reference)
; #define PG8_STAGE(bufoff, gbase, voff) do { _Pragma("unroll") for (int _i = 0; _i < 2; ++_i) \
;         __builtin_amdgcn_global_load_lds((const unsigned*)((const char*)(gbase) + (voff)[_i]), (LAS unsigned*)(lds + (bufoff) + ldsw + _i * 8192), 16, 0, 0); } while (0)
; #define PG8_LDA(dst, b, h) do { _Pragma("unroll") for (int m = 0; m < 4; ++m) _Pragma("unroll") for (int k = 0; k < 2; ++k) dst[m][k] = *(const LAS bf16x8*)(lds + PG8_SA(b, h) + aoff + m * 2048 + k * 1024); } while (0)
; #define PG8_LDB(dst, b, h) do { _Pragma("unroll") for (int n = 0; n < 2; ++n) _Pragma("unroll") for (int k = 0; k < 2; ++k) dst[n][k] = *(const LAS bf16x8*)(lds + PG8_SB(b, h) + boff + n * 2048 + k * 1024); } while (0)
; #define PG8_MMA(ai, bj, At, Bt) do { __builtin_amdgcn_s_setprio(1); _Pragma("unroll") for (int m = 0; m < 4; ++m) _Pragma("unroll") for (int n = 0; n < 2; ++n) _Pragma("unroll") for (int k = 0; k < 2; ++k) \
;         acc[ai][bj][m][n] = __builtin_amdgcn_mfma_f32_16x16x32_bf16(Bt[n][k], At[m][k], acc[ai][bj][m][n], 0, 0, 0); __builtin_amdgcn_s_setprio(0); } while (0)
; #define PG8_WAIT_V(n) asm volatile("s_waitcnt vmcnt(" #n ")" ::: "memory")
; #define PG8_WAIT_L(n) asm volatile("s_waitcnt lgkmcnt(" #n ")" ::: "memory")
; #define PG8_BAR __builtin_amdgcn_s_barrier()
; template <class EpiT>
; __device__ __forceinline__ void gemm_phase(LAS unsigned char* lds, const Gemm g, const StaticOrder& S, const EpiT& E) {
;     ...
;         const char* nA = has_next ? (const char*)g.A + (size_t)nxt.pm * tstepA + (size_t)nxt.pn * g.a_koff * 2 : cA; const char* nB = has_next ? (const char*)g.Bt + (size_t)nxt.pn * tstepB : cB;
;         for (int t = 0; t < nt; t += 2) {
;             const bool last = (t == nt - 2);
;             const char* a1 = cA + (size_t)(t + 1) * kstep;
;             const char* a2 = last ? nA : cA + (size_t)(t + 2) * kstep; const char* b2 = last ? nB : cB + (size_t)(t + 2) * kstep;
;             const char* a3 = a2 + kstep; const char* b3 = b2 + kstep;
;             PG8_LDB(B0, 0, 0); PG8_LDB(B1, 0, 1); PG8_SCHED; PG8_LDA(At, 0, 0); PG8_STAGE(PG8_SA(1, 1), a1 + hstepA, voffA);
;             PG8_WAIT_V(8); PG8_WAIT_L(0); PG8_BAR; PG8_MMA(0, 0, At, B0); PG8_MMA(0, 1, At, B1); PG8_BAR; PG8_SCHED;
;             PG8_LDA(At, 0, 1); PG8_STAGE(PG8_SB(0, 0), b2, voffB); PG8_STAGE(PG8_SB(0, 1), b2 + hstepB, voffB); PG8_STAGE(PG8_SA(0, 0), a2, voffA);
.LBB0_100:
	ds_read_b128 v[128:131], v160
	ds_read_b128 v[170:173], v160 offset:1024
	ds_read_b128 v[174:177], v160 offset:2048
	ds_read_b128 v[178:181], v160 offset:3072
	ds_read_b128 v[182:185], v161
	ds_read_b128 v[186:189], v161 offset:1024
	ds_read_b128 v[190:193], v161 offset:2048
	ds_read_b128 v[194:197], v161 offset:3072
	s_add_u32 s18, s16, 0xfff7c080
	s_addc_u32 s19, s17, -1
	s_cmp_eq_u32 s53, 28
	s_cselect_b32 s21, s3, s19
	s_cselect_b32 s20, s2, s18
	s_cselect_b32 s19, s15, s52
	s_cselect_b32 s18, s14, s51
	v_lshl_add_u64 v[158:159], s[16:17], 0, v[150:151]
	s_add_i32 m0, s35, 0xc000
	ds_read_b128 v[198:201], v162
	ds_read_b128 v[202:205], v162 offset:1024
	ds_read_b128 v[206:209], v162 offset:2048
	ds_read_b128 v[210:213], v162 offset:3072
	ds_read_b128 v[214:217], v162 offset:4096
	ds_read_b128 v[218:221], v162 offset:5120
	ds_read_b128 v[222:225], v162 offset:6144
	ds_read_b128 v[226:229], v162 offset:7168
	global_load_lds_dwordx4 v[158:159], off
	v_lshl_add_u64 v[158:159], s[16:17], 0, v[152:153]
	s_add_i32 m0, s35, 0xe000
	s_nop 0
	global_load_lds_dwordx4 v[158:159], off
	s_waitcnt vmcnt(8)
	s_waitcnt lgkmcnt(0)
	s_barrier
	s_setprio 1
	v_mfma_f32_16x16x32_bf16 v[124:127], v[128:131], v[198:201], v[124:127]
	v_mfma_f32_16x16x32_bf16 v[124:127], v[170:173], v[202:205], v[124:127]
	v_mfma_f32_16x16x32_bf16 v[108:111], v[128:131], v[206:209], v[108:111]
	v_mfma_f32_16x16x32_bf16 v[108:111], v[170:173], v[210:213], v[108:111]
	v_mfma_f32_16x16x32_bf16 v[92:95], v[128:131], v[214:217], v[92:95]
	v_mfma_f32_16x16x32_bf16 v[92:95], v[170:173], v[218:221], v[92:95]
	v_mfma_f32_16x16x32_bf16 v[76:79], v[128:131], v[222:225], v[76:79]
	v_mfma_f32_16x16x32_bf16 v[76:79], v[170:173], v[226:229], v[76:79]
	v_mfma_f32_16x16x32_bf16 v[120:123], v[174:177], v[198:201], v[120:123]
	v_mfma_f32_16x16x32_bf16 v[120:123], v[178:181], v[202:205], v[120:123]
	v_mfma_f32_16x16x32_bf16 v[104:107], v[174:177], v[206:209], v[104:107]
	v_mfma_f32_16x16x32_bf16 v[104:107], v[178:181], v[210:213], v[104:107]
	v_mfma_f32_16x16x32_bf16 v[88:91], v[174:177], v[214:217], v[88:91]
	v_mfma_f32_16x16x32_bf16 v[88:91], v[178:181], v[218:221], v[88:91]
	v_mfma_f32_16x16x32_bf16 v[72:75], v[174:177], v[222:225], v[72:75]
	v_mfma_f32_16x16x32_bf16 v[72:75], v[178:181], v[226:229], v[72:75]
	s_setprio 0
	s_setprio 1
	v_mfma_f32_16x16x32_bf16 v[116:119], v[182:185], v[198:201], v[116:119]
	v_mfma_f32_16x16x32_bf16 v[116:119], v[186:189], v[202:205], v[116:119]
	v_mfma_f32_16x16x32_bf16 v[100:103], v[182:185], v[206:209], v[100:103]
	v_mfma_f32_16x16x32_bf16 v[100:103], v[186:189], v[210:213], v[100:103]
	v_mfma_f32_16x16x32_bf16 v[84:87], v[182:185], v[214:217], v[84:87]
	v_mfma_f32_16x16x32_bf16 v[84:87], v[186:189], v[218:221], v[84:87]
	v_mfma_f32_16x16x32_bf16 v[68:71], v[182:185], v[222:225], v[68:71]
	v_mfma_f32_16x16x32_bf16 v[68:71], v[186:189], v[226:229], v[68:71]
	v_mfma_f32_16x16x32_bf16 v[112:115], v[190:193], v[198:201], v[112:115]
	v_mfma_f32_16x16x32_bf16 v[112:115], v[194:197], v[202:205], v[112:115]
	v_mfma_f32_16x16x32_bf16 v[96:99], v[190:193], v[206:209], v[96:99]
	v_mfma_f32_16x16x32_bf16 v[96:99], v[194:197], v[210:213], v[96:99]
	v_mfma_f32_16x16x32_bf16 v[80:83], v[190:193], v[214:217], v[80:83]
	v_mfma_f32_16x16x32_bf16 v[80:83], v[194:197], v[218:221], v[80:83]
	v_mfma_f32_16x16x32_bf16 v[64:67], v[190:193], v[222:225], v[64:67]
	v_mfma_f32_16x16x32_bf16 v[64:67], v[194:197], v[226:229], v[64:67]
	s_setprio 0
	s_barrier
	s_add_i32 s54, s43, s25
	v_lshl_add_u64 v[158:159], s[18:19], 0, v[136:137]
	s_mov_b32 m0, s54
	ds_read_b128 v[198:201], v162 offset:16384
	ds_read_b128 v[202:205], v162 offset:17408
	ds_read_b128 v[206:209], v162 offset:18432
	ds_read_b128 v[210:213], v162 offset:19456
	ds_read_b128 v[214:217], v162 offset:20480
	ds_read_b128 v[218:221], v162 offset:21504
	ds_read_b128 v[222:225], v162 offset:22528
	ds_read_b128 v[226:229], v162 offset:23552
	global_load_lds_dwordx4 v[158:159], off
	s_add_i32 m0, s54, 0x2000
	s_add_u32 s54, s18, 0x84000
	v_lshl_add_u64 v[166:167], s[18:19], 0, v[132:133]
	s_addc_u32 s55, s19, 0
	s_add_i32 s56, s44, s25
	global_load_lds_dwordx4 v[166:167], off
	v_lshl_add_u64 v[230:231], s[54:55], 0, v[136:137]
	s_mov_b32 m0, s56
	v_lshl_add_u64 v[232:233], s[20:21], 0, v[134:135]
	global_load_lds_dwordx4 v[230:231], off
	v_lshl_add_u64 v[230:231], s[54:55], 0, v[132:133]
	s_add_i32 m0, s56, 0x2000
	s_nop 0
	global_load_lds_dwordx4 v[230:231], off
	v_lshl_add_u64 v[230:231], s[20:21], 0, v[138:139]
	s_mov_b32 m0, s35
	s_nop 0
	global_load_lds_dwordx4 v[230:231], off
	s_mov_b32 m0, s36
	s_nop 0
	global_load_lds_dwordx4 v[232:233], off
	s_waitcnt vmcnt(8)
	s_waitcnt lgkmcnt(0)
	s_barrier
; #define PG8_STAGE(bufoff, gbase, voff) do { _Pragma("unroll") for (int _i = 0; _i < 2; ++_i) \
;         __builtin_amdgcn_global_load_lds((const unsigned*)((const char*)(gbase) + (voff)[_i]), (LAS unsigned*)(lds + (bufoff) + ldsw + _i * 8192), 16, 0, 0); } while (0)
; #define PG8_LDA(dst, b, h) do { _Pragma("unroll") for (int m = 0; m < 4; ++m) _Pragma("unroll") for (int k = 0; k < 2; ++k) dst[m][k] = *(const LAS bf16x8*)(lds + PG8_SA(b, h) + aoff + m * 2048 + k * 1024); } while (0)
; #define PG8_LDB(dst, b, h) do { _Pragma("unroll") for (int n = 0; n < 2; ++n) _Pragma("unroll") for (int k = 0; k < 2; ++k) dst[n][k] = *(const LAS bf16x8*)(lds + PG8_SB(b, h) + boff + n * 2048 + k * 1024); } while (0)
; #define PG8_MMA(ai, bj, At, Bt) do { __builtin_amdgcn_s_setprio(1); _Pragma("unroll") for (int m = 0; m < 4; ++m) _Pragma("unroll") for (int n = 0; n < 2; ++n) _Pragma("unroll") for (int k = 0; k < 2; ++k) \
;         acc[ai][bj][m][n] = __builtin_amdgcn_mfma_f32_16x16x32_bf16(Bt[n][k], At[m][k], acc[ai][bj][m][n], 0, 0, 0); __builtin_amdgcn_s_setprio(0); } while (0)
; #define PG8_WAIT_V(n) asm volatile("s_waitcnt vmcnt(" #n ")" ::: "memory")
; #define PG8_WAIT_L(n) asm volatile("s_waitcnt lgkmcnt(" #n ")" ::: "memory")
; #define PG8_BAR __builtin_amdgcn_s_barrier()
; #define PG8_SCHED __builtin_amdgcn_sched_barrier(0)
; template <class EpiT>
; __device__ __forceinline__ void gemm_phase(LAS unsigned char* lds, const Gemm g, const StaticOrder& S, const EpiT& E) {
;     ...
;             PG8_WAIT_V(8); PG8_WAIT_L(0); PG8_BAR; PG8_MMA(1, 0, At, B0); PG8_MMA(1, 1, At, B1); PG8_BAR; PG8_SCHED;
;             PG8_LDB(B0, 1, 0); PG8_LDB(B1, 1, 1); PG8_SCHED; PG8_LDA(At, 1, 0); PG8_STAGE(PG8_SA(0, 1), a2 + hstepA, voffA);
;             PG8_WAIT_V(8); PG8_WAIT_L(0); PG8_BAR; PG8_MMA(0, 0, At, B0); PG8_MMA(0, 1, At, B1); PG8_BAR; PG8_SCHED;
	s_setprio 1
	v_mfma_f32_16x16x32_bf16 v[60:63], v[128:131], v[198:201], v[60:63]
	v_mfma_f32_16x16x32_bf16 v[60:63], v[170:173], v[202:205], v[60:63]
	v_mfma_f32_16x16x32_bf16 v[44:47], v[128:131], v[206:209], v[44:47]
	v_mfma_f32_16x16x32_bf16 v[44:47], v[170:173], v[210:213], v[44:47]
	v_mfma_f32_16x16x32_bf16 v[28:31], v[128:131], v[214:217], v[28:31]
	v_mfma_f32_16x16x32_bf16 v[28:31], v[170:173], v[218:221], v[28:31]
	v_mfma_f32_16x16x32_bf16 v[12:15], v[128:131], v[222:225], v[12:15]
	v_mfma_f32_16x16x32_bf16 v[12:15], v[170:173], v[226:229], v[12:15]
	v_mfma_f32_16x16x32_bf16 v[56:59], v[174:177], v[198:201], v[56:59]
	v_mfma_f32_16x16x32_bf16 v[56:59], v[178:181], v[202:205], v[56:59]
	v_mfma_f32_16x16x32_bf16 v[40:43], v[174:177], v[206:209], v[40:43]
	v_mfma_f32_16x16x32_bf16 v[40:43], v[178:181], v[210:213], v[40:43]
	v_mfma_f32_16x16x32_bf16 v[24:27], v[174:177], v[214:217], v[24:27]
	v_mfma_f32_16x16x32_bf16 v[24:27], v[178:181], v[218:221], v[24:27]
	v_mfma_f32_16x16x32_bf16 v[8:11], v[174:177], v[222:225], v[8:11]
	v_mfma_f32_16x16x32_bf16 v[8:11], v[178:181], v[226:229], v[8:11]
	s_setprio 0
	s_setprio 1
	v_mfma_f32_16x16x32_bf16 v[52:55], v[182:185], v[198:201], v[52:55]
	v_mfma_f32_16x16x32_bf16 v[52:55], v[186:189], v[202:205], v[52:55]
	v_mfma_f32_16x16x32_bf16 v[36:39], v[182:185], v[206:209], v[36:39]
	v_mfma_f32_16x16x32_bf16 v[36:39], v[186:189], v[210:213], v[36:39]
	v_mfma_f32_16x16x32_bf16 v[20:23], v[182:185], v[214:217], v[20:23]
	v_mfma_f32_16x16x32_bf16 v[20:23], v[186:189], v[218:221], v[20:23]
	v_mfma_f32_16x16x32_bf16 v[4:7], v[182:185], v[222:225], v[4:7]
	v_mfma_f32_16x16x32_bf16 v[4:7], v[186:189], v[226:229], v[4:7]
	v_mfma_f32_16x16x32_bf16 v[48:51], v[190:193], v[198:201], v[48:51]
	v_mfma_f32_16x16x32_bf16 v[48:51], v[194:197], v[202:205], v[48:51]
	v_mfma_f32_16x16x32_bf16 v[32:35], v[190:193], v[206:209], v[32:35]
	v_mfma_f32_16x16x32_bf16 v[32:35], v[194:197], v[210:213], v[32:35]
	v_mfma_f32_16x16x32_bf16 v[16:19], v[190:193], v[214:217], v[16:19]
	v_mfma_f32_16x16x32_bf16 v[16:19], v[194:197], v[218:221], v[16:19]
	v_mfma_f32_16x16x32_bf16 v[0:3], v[190:193], v[222:225], v[0:3]
	v_mfma_f32_16x16x32_bf16 v[0:3], v[194:197], v[226:229], v[0:3]
	s_setprio 0
	s_barrier
	s_add_i32 s54, 0, 0x18000
	v_add_u32_e32 v140, s54, v145
	s_add_i32 s55, 0, 0x1c000
	ds_read_b128 v[128:131], v140
	ds_read_b128 v[170:173], v140 offset:1024
	ds_read_b128 v[174:177], v140 offset:2048
	ds_read_b128 v[178:181], v140 offset:3072
	v_add_u32_e32 v140, s55, v145
	ds_read_b128 v[182:185], v140
	ds_read_b128 v[186:189], v140 offset:1024
	ds_read_b128 v[190:193], v140 offset:2048
	ds_read_b128 v[194:197], v140 offset:3072
	s_add_u32 s20, s20, 0x84000
	s_addc_u32 s21, s21, 0
	s_mov_b32 m0, s37
	v_lshl_add_u64 v[234:235], s[20:21], 0, v[138:139]
	ds_read_b128 v[198:201], v162 offset:32768
	ds_read_b128 v[202:205], v162 offset:33792
	ds_read_b128 v[206:209], v162 offset:34816
	ds_read_b128 v[210:213], v162 offset:35840
	ds_read_b128 v[214:217], v162 offset:36864
	ds_read_b128 v[218:221], v162 offset:37888
	ds_read_b128 v[222:225], v162 offset:38912
	ds_read_b128 v[226:229], v162 offset:39936
	global_load_lds_dwordx4 v[234:235], off
	v_lshl_add_u64 v[234:235], s[20:21], 0, v[134:135]
	s_mov_b32 m0, s38
	s_nop 0
	global_load_lds_dwordx4 v[234:235], off
	s_waitcnt vmcnt(8)
	s_waitcnt lgkmcnt(0)
	s_barrier
	s_setprio 1
	v_mfma_f32_16x16x32_bf16 v[124:127], v[128:131], v[198:201], v[124:127]
	v_mfma_f32_16x16x32_bf16 v[124:127], v[170:173], v[202:205], v[124:127]
	v_mfma_f32_16x16x32_bf16 v[108:111], v[128:131], v[206:209], v[108:111]
	v_mfma_f32_16x16x32_bf16 v[108:111], v[170:173], v[210:213], v[108:111]
	v_mfma_f32_16x16x32_bf16 v[92:95], v[128:131], v[214:217], v[92:95]
	v_mfma_f32_16x16x32_bf16 v[92:95], v[170:173], v[218:221], v[92:95]
	v_mfma_f32_16x16x32_bf16 v[76:79], v[128:131], v[222:225], v[76:79]
	v_mfma_f32_16x16x32_bf16 v[76:79], v[170:173], v[226:229], v[76:79]
	v_mfma_f32_16x16x32_bf16 v[120:123], v[174:177], v[198:201], v[120:123]
	v_mfma_f32_16x16x32_bf16 v[120:123], v[178:181], v[202:205], v[120:123]
	v_mfma_f32_16x16x32_bf16 v[104:107], v[174:177], v[206:209], v[104:107]
	v_mfma_f32_16x16x32_bf16 v[104:107], v[178:181], v[210:213], v[104:107]
	v_mfma_f32_16x16x32_bf16 v[88:91], v[174:177], v[214:217], v[88:91]
	v_mfma_f32_16x16x32_bf16 v[88:91], v[178:181], v[218:221], v[88:91]
	v_mfma_f32_16x16x32_bf16 v[72:75], v[174:177], v[222:225], v[72:75]
	v_mfma_f32_16x16x32_bf16 v[72:75], v[178:181], v[226:229], v[72:75]
	s_setprio 0
	s_setprio 1
	v_mfma_f32_16x16x32_bf16 v[116:119], v[182:185], v[198:201], v[116:119]
	v_mfma_f32_16x16x32_bf16 v[116:119], v[186:189], v[202:205], v[116:119]
	v_mfma_f32_16x16x32_bf16 v[100:103], v[182:185], v[206:209], v[100:103]
	v_mfma_f32_16x16x32_bf16 v[100:103], v[186:189], v[210:213], v[100:103]
	v_mfma_f32_16x16x32_bf16 v[84:87], v[182:185], v[214:217], v[84:87]
	v_mfma_f32_16x16x32_bf16 v[84:87], v[186:189], v[218:221], v[84:87]
	v_mfma_f32_16x16x32_bf16 v[68:71], v[182:185], v[222:225], v[68:71]
	v_mfma_f32_16x16x32_bf16 v[68:71], v[186:189], v[226:229], v[68:71]
	v_mfma_f32_16x16x32_bf16 v[112:115], v[190:193], v[198:201], v[112:115]
	v_mfma_f32_16x16x32_bf16 v[112:115], v[194:197], v[202:205], v[112:115]
	v_mfma_f32_16x16x32_bf16 v[96:99], v[190:193], v[206:209], v[96:99]
	v_mfma_f32_16x16x32_bf16 v[96:99], v[194:197], v[210:213], v[96:99]
	v_mfma_f32_16x16x32_bf16 v[80:83], v[190:193], v[214:217], v[80:83]
	v_mfma_f32_16x16x32_bf16 v[80:83], v[194:197], v[218:221], v[80:83]
	v_mfma_f32_16x16x32_bf16 v[64:67], v[190:193], v[222:225], v[64:67]
	v_mfma_f32_16x16x32_bf16 v[64:67], v[194:197], v[226:229], v[64:67]
	s_setprio 0
	s_barrier
; #define PG8_STAGE(bufoff, gbase, voff) do { _Pragma("unroll") for (int _i = 0; _i < 2; ++_i) \
;         __builtin_amdgcn_global_load_lds((const unsigned*)((const char*)(gbase) + (voff)[_i]), (LAS unsigned*)(lds + (bufoff) + ldsw + _i * 8192), 16, 0, 0); } while (0)
; #define PG8_LDA(dst, b, h) do { _Pragma("unroll") for (int m = 0; m < 4; ++m) _Pragma("unroll") for (int k = 0; k < 2; ++k) dst[m][k] = *(const LAS bf16x8*)(lds + PG8_SA(b, h) + aoff + m * 2048 + k * 1024); } while (0)
; #define PG8_MMA(ai, bj, At, Bt) do { __builtin_amdgcn_s_setprio(1); _Pragma("unroll") for (int m = 0; m < 4; ++m) _Pragma("unroll") for (int n = 0; n < 2; ++n) _Pragma("unroll") for (int k = 0; k < 2; ++k) \
;         acc[ai][bj][m][n] = __builtin_amdgcn_mfma_f32_16x16x32_bf16(Bt[n][k], At[m][k], acc[ai][bj][m][n], 0, 0, 0); __builtin_amdgcn_s_setprio(0); } while (0)
; #define PG8_WAIT_V(n) asm volatile("s_waitcnt vmcnt(" #n ")" ::: "memory")
; #define PG8_WAIT_L(n) asm volatile("s_waitcnt lgkmcnt(" #n ")" ::: "memory")
; #define PG8_BAR __builtin_amdgcn_s_barrier()
; #define PG8_SCHED __builtin_amdgcn_sched_barrier(0)
; template <class EpiT>
; __device__ __forceinline__ void gemm_phase(LAS unsigned char* lds, const Gemm g, const StaticOrder& S, const EpiT& E) {
;     ...
;             PG8_LDA(At, 1, 1); PG8_STAGE(PG8_SB(1, 0), b3, voffB); PG8_STAGE(PG8_SB(1, 1), b3 + hstepB, voffB); PG8_STAGE(PG8_SA(1, 0), a3, voffA);
;             PG8_WAIT_V(8); PG8_WAIT_L(0); PG8_BAR; PG8_MMA(1, 0, At, B0); PG8_MMA(1, 1, At, B1); PG8_BAR; PG8_SCHED;
;         }
;         if (wr == 0) PG8_BAR;
	s_add_i32 s20, s54, s25
	v_lshl_add_u64 v[158:159], v[158:159], 0, s[10:11]
	s_mov_b32 m0, s20
	ds_read_b128 v[198:201], v162 offset:49152
	ds_read_b128 v[202:205], v162 offset:50176
	ds_read_b128 v[206:209], v162 offset:51200
	ds_read_b128 v[210:213], v162 offset:52224
	ds_read_b128 v[214:217], v162 offset:53248
	ds_read_b128 v[218:221], v162 offset:54272
	ds_read_b128 v[222:225], v162 offset:55296
	ds_read_b128 v[226:229], v162 offset:56320
	global_load_lds_dwordx4 v[158:159], off
	s_add_i32 m0, s20, 0x2000
	s_add_u32 s18, s18, 0x84080
	v_lshl_add_u64 v[158:159], v[166:167], 0, s[10:11]
	s_addc_u32 s19, s19, 0
	s_add_i32 s20, s55, s25
	global_load_lds_dwordx4 v[158:159], off
	v_lshl_add_u64 v[158:159], s[18:19], 0, v[136:137]
	s_mov_b32 m0, s20
	s_nop 0
	global_load_lds_dwordx4 v[158:159], off
	v_lshl_add_u64 v[158:159], s[18:19], 0, v[132:133]
	s_add_i32 m0, s20, 0x2000
	s_nop 0
	global_load_lds_dwordx4 v[158:159], off
	v_lshl_add_u64 v[158:159], v[230:231], 0, s[10:11]
	s_mov_b32 m0, s40
	s_nop 0
	global_load_lds_dwordx4 v[158:159], off
	v_lshl_add_u64 v[158:159], v[232:233], 0, s[10:11]
	s_mov_b32 m0, s41
	s_nop 0
	global_load_lds_dwordx4 v[158:159], off
	s_waitcnt vmcnt(8)
	s_waitcnt lgkmcnt(0)
	s_barrier
	s_setprio 1
	v_mfma_f32_16x16x32_bf16 v[60:63], v[128:131], v[198:201], v[60:63]
	v_mfma_f32_16x16x32_bf16 v[60:63], v[170:173], v[202:205], v[60:63]
	v_mfma_f32_16x16x32_bf16 v[44:47], v[128:131], v[206:209], v[44:47]
	v_mfma_f32_16x16x32_bf16 v[44:47], v[170:173], v[210:213], v[44:47]
	v_mfma_f32_16x16x32_bf16 v[28:31], v[128:131], v[214:217], v[28:31]
	v_mfma_f32_16x16x32_bf16 v[28:31], v[170:173], v[218:221], v[28:31]
	v_mfma_f32_16x16x32_bf16 v[12:15], v[128:131], v[222:225], v[12:15]
	v_mfma_f32_16x16x32_bf16 v[12:15], v[170:173], v[226:229], v[12:15]
	v_mfma_f32_16x16x32_bf16 v[56:59], v[174:177], v[198:201], v[56:59]
	v_mfma_f32_16x16x32_bf16 v[56:59], v[178:181], v[202:205], v[56:59]
	v_mfma_f32_16x16x32_bf16 v[40:43], v[174:177], v[206:209], v[40:43]
	v_mfma_f32_16x16x32_bf16 v[40:43], v[178:181], v[210:213], v[40:43]
	v_mfma_f32_16x16x32_bf16 v[24:27], v[174:177], v[214:217], v[24:27]
	v_mfma_f32_16x16x32_bf16 v[24:27], v[178:181], v[218:221], v[24:27]
	v_mfma_f32_16x16x32_bf16 v[8:11], v[174:177], v[222:225], v[8:11]
	v_mfma_f32_16x16x32_bf16 v[8:11], v[178:181], v[226:229], v[8:11]
	s_setprio 0
	s_setprio 1
	v_mfma_f32_16x16x32_bf16 v[52:55], v[182:185], v[198:201], v[52:55]
	v_mfma_f32_16x16x32_bf16 v[52:55], v[186:189], v[202:205], v[52:55]
	v_mfma_f32_16x16x32_bf16 v[36:39], v[182:185], v[206:209], v[36:39]
	v_mfma_f32_16x16x32_bf16 v[36:39], v[186:189], v[210:213], v[36:39]
	v_mfma_f32_16x16x32_bf16 v[20:23], v[182:185], v[214:217], v[20:23]
	v_mfma_f32_16x16x32_bf16 v[20:23], v[186:189], v[218:221], v[20:23]
	v_mfma_f32_16x16x32_bf16 v[4:7], v[182:185], v[222:225], v[4:7]
	v_mfma_f32_16x16x32_bf16 v[4:7], v[186:189], v[226:229], v[4:7]
	v_mfma_f32_16x16x32_bf16 v[48:51], v[190:193], v[198:201], v[48:51]
	v_mfma_f32_16x16x32_bf16 v[48:51], v[194:197], v[202:205], v[48:51]
	v_mfma_f32_16x16x32_bf16 v[32:35], v[190:193], v[206:209], v[32:35]
	v_mfma_f32_16x16x32_bf16 v[32:35], v[194:197], v[210:213], v[32:35]
	v_mfma_f32_16x16x32_bf16 v[16:19], v[190:193], v[214:217], v[16:19]
	v_mfma_f32_16x16x32_bf16 v[16:19], v[194:197], v[218:221], v[16:19]
	v_mfma_f32_16x16x32_bf16 v[0:3], v[190:193], v[222:225], v[0:3]
	v_mfma_f32_16x16x32_bf16 v[0:3], v[194:197], v[226:229], v[0:3]
	s_setprio 0
	s_barrier
	s_add_i32 s53, s53, 2
	s_add_u32 s16, s16, 0x100
	s_addc_u32 s17, s17, 0
	s_add_u32 s51, s51, 0x100
	s_addc_u32 s52, s52, 0
	s_cmp_gt_u32 s53, 29
	s_cbranch_scc0 .LBB0_100
	s_and_b64 vcc, exec, s[12:13]
	s_cbranch_vccz .LBB0_103
	s_barrier

; #define PG8_STAGE(bufoff, gbase, voff) do { _Pragma("unroll") for (int _i = 0; _i < 2; ++_i) \
;         __builtin_amdgcn_global_load_lds((const unsigned*)((const char*)(gbase) + (voff)[_i]), (LAS unsigned*)(lds + (bufoff) + ldsw + _i * 8192), 16, 0, 0); } while (0)
; #define PG8_LDA(dst, b, h) do { _Pragma("unroll") for (int m = 0; m < 4; ++m) _Pragma("unroll") for (int k = 0; k < 2; ++k) dst[m][k] = *(const LAS bf16x8*)(lds + PG8_SA(b, h) + aoff + m * 2048 + k * 1024); } while (0)
; #define PG8_LDB(dst, b, h) do { _Pragma("unroll") for (int n = 0; n < 2; ++n) _Pragma("unroll") for (int k = 0; k < 2; ++k) dst[n][k] = *(const LAS bf16x8*)(lds + PG8_SB(b, h) + boff + n * 2048 + k * 1024); } while (0)
; #define PG8_MMA(ai, bj, At, Bt) do { __builtin_amdgcn_s_setprio(1); _Pragma("unroll") for (int m = 0; m < 4; ++m) _Pragma("unroll") for (int n = 0; n < 2; ++n) _Pragma("unroll") for (int k = 0; k < 2; ++k) \
;         acc[ai][bj][m][n] = __builtin_amdgcn_mfma_f32_16x16x32_bf16(Bt[n][k], At[m][k], acc[ai][bj][m][n], 0, 0, 0); __builtin_amdgcn_s_setprio(0); } while (0)
; #define PG8_WAIT_V(n) asm volatile("s_waitcnt vmcnt(" #n ")" ::: "memory")
; #define PG8_WAIT_L(n) asm volatile("s_waitcnt lgkmcnt(" #n ")" ::: "memory")
; #define PG8_BAR __builtin_amdgcn_s_barrier()
; template <class EpiT>
; __device__ __forceinline__ void gemm_phase(LAS unsigned char* lds, const Gemm g, const StaticOrder& S, const EpiT& E) {
;     ...
;         const char* nA = has_next ? (const char*)g.A + (size_t)nxt.pm * tstepA + (size_t)nxt.pn * g.a_koff * 2 : cA; const char* nB = has_next ? (const char*)g.Bt + (size_t)nxt.pn * tstepB : cB;
;         for (int t = 0; t < nt; t += 2) {
;             const bool last = (t == nt - 2);
;             const char* a1 = cA + (size_t)(t + 1) * kstep;
;             const char* a2 = last ? nA : cA + (size_t)(t + 2) * kstep; const char* b2 = last ? nB : cB + (size_t)(t + 2) * kstep;
;             const char* a3 = a2 + kstep; const char* b3 = b2 + kstep;
;             PG8_LDB(B0, 0, 0); PG8_LDB(B1, 0, 1); PG8_SCHED; PG8_LDA(At, 0, 0); PG8_STAGE(PG8_SA(1, 1), a1 + hstepA, voffA);
;             PG8_WAIT_V(8); PG8_WAIT_L(0); PG8_BAR; PG8_MMA(0, 0, At, B0); PG8_MMA(0, 1, At, B1); PG8_BAR; PG8_SCHED;
;             PG8_LDA(At, 0, 1); PG8_STAGE(PG8_SB(0, 0), b2, voffB); PG8_STAGE(PG8_SB(0, 1), b2 + hstepB, voffB); PG8_STAGE(PG8_SA(0, 0), a2, voffA);
.LBB0_296:
	s_add_u32 s58, s66, s54
	s_addc_u32 s59, s67, 0
	s_add_u32 s55, s58, 0x100
	s_addc_u32 s61, s59, 0
	s_and_b64 s[56:57], s[68:69], exec
	s_cselect_b32 s73, s21, s61
	s_cselect_b32 s72, s20, s55
	s_add_u32 s54, s46, s54
	s_addc_u32 s55, s47, 0
	s_add_u32 s56, s54, 0x100
	s_addc_u32 s57, s55, 0
	s_and_b64 s[54:55], s[68:69], exec
	s_cselect_b32 s75, s17, s57
	s_cselect_b32 s74, s19, s56
	s_add_u32 s78, s58, 0x40080
	s_addc_u32 s79, s59, 0
	s_add_i32 s80, s51, s36
	ds_read_b128 v[128:131], v167
	ds_read_b128 v[132:135], v167 offset:1024
	ds_read_b128 v[136:139], v167 offset:2048
	ds_read_b128 v[140:143], v167 offset:3072
	ds_read_b128 v[160:163], v169
	ds_read_b128 v[172:175], v169 offset:1024
	ds_read_b128 v[176:179], v169 offset:2048
	ds_read_b128 v[180:183], v169 offset:3072
	s_add_i32 m0, s37, 0xc000
	s_add_i32 s84, s37, 0xe000
	s_add_i32 s61, s80, 0x2000
	s_add_u32 s76, s74, 0x10000
	s_addc_u32 s77, s75, 0
	s_add_i32 s65, s52, s36
	s_add_i32 s64, s65, 0x2000
	s_add_i32 s59, 0, 0x18000
	s_add_i32 s58, 0, 0x1c000
	s_add_u32 s70, s72, 0x40000
	s_addc_u32 s71, s73, 0
	s_add_i32 s57, s59, s36
	s_add_i32 s55, s57, 0x2000
	s_add_u32 s68, s74, 0x10080
	s_addc_u32 s69, s75, 0
	s_add_i32 s56, s58, s36
	s_add_i32 s54, s56, 0x2000
	v_lshl_add_u64 v[216:217], s[78:79], 0, v[146:147]
	ds_read_b128 v[184:187], v170
	ds_read_b128 v[188:191], v170 offset:1024
	ds_read_b128 v[192:195], v170 offset:2048
	ds_read_b128 v[196:199], v170 offset:3072
	ds_read_b128 v[200:203], v170 offset:4096
	ds_read_b128 v[204:207], v170 offset:5120
	ds_read_b128 v[208:211], v170 offset:6144
	ds_read_b128 v[212:215], v170 offset:7168
	global_load_lds_dwordx4 v[216:217], off
	v_lshl_add_u64 v[216:217], s[78:79], 0, v[150:151]
	s_mov_b32 m0, s84
	s_nop 0
	global_load_lds_dwordx4 v[216:217], off
	s_waitcnt vmcnt(8)
	s_waitcnt lgkmcnt(0)
	s_barrier
	s_setprio 1
	v_mfma_f32_16x16x32_bf16 v[124:127], v[128:131], v[184:187], v[124:127]
	v_mfma_f32_16x16x32_bf16 v[120:123], v[136:139], v[184:187], v[120:123]
	v_mfma_f32_16x16x32_bf16 v[108:111], v[128:131], v[192:195], v[108:111]
	v_mfma_f32_16x16x32_bf16 v[104:107], v[136:139], v[192:195], v[104:107]
	v_mfma_f32_16x16x32_bf16 v[92:95], v[128:131], v[200:203], v[92:95]
	v_mfma_f32_16x16x32_bf16 v[88:91], v[136:139], v[200:203], v[88:91]
	v_mfma_f32_16x16x32_bf16 v[76:79], v[128:131], v[208:211], v[76:79]
	v_mfma_f32_16x16x32_bf16 v[72:75], v[136:139], v[208:211], v[72:75]
	v_mfma_f32_16x16x32_bf16 v[124:127], v[132:135], v[188:191], v[124:127]
	v_mfma_f32_16x16x32_bf16 v[120:123], v[140:143], v[188:191], v[120:123]
	v_mfma_f32_16x16x32_bf16 v[108:111], v[132:135], v[196:199], v[108:111]
	v_mfma_f32_16x16x32_bf16 v[104:107], v[140:143], v[196:199], v[104:107]
	v_mfma_f32_16x16x32_bf16 v[92:95], v[132:135], v[204:207], v[92:95]
	v_mfma_f32_16x16x32_bf16 v[88:91], v[140:143], v[204:207], v[88:91]
	v_mfma_f32_16x16x32_bf16 v[76:79], v[132:135], v[212:215], v[76:79]
	v_mfma_f32_16x16x32_bf16 v[72:75], v[140:143], v[212:215], v[72:75]
	s_setprio 0
	s_setprio 1
	v_mfma_f32_16x16x32_bf16 v[116:119], v[160:163], v[184:187], v[116:119]
	v_mfma_f32_16x16x32_bf16 v[112:115], v[176:179], v[184:187], v[112:115]
	v_mfma_f32_16x16x32_bf16 v[100:103], v[160:163], v[192:195], v[100:103]
	v_mfma_f32_16x16x32_bf16 v[96:99], v[176:179], v[192:195], v[96:99]
	v_mfma_f32_16x16x32_bf16 v[84:87], v[160:163], v[200:203], v[84:87]
	v_mfma_f32_16x16x32_bf16 v[80:83], v[176:179], v[200:203], v[80:83]
	v_mfma_f32_16x16x32_bf16 v[68:71], v[160:163], v[208:211], v[68:71]
	v_mfma_f32_16x16x32_bf16 v[64:67], v[176:179], v[208:211], v[64:67]
	v_mfma_f32_16x16x32_bf16 v[116:119], v[172:175], v[188:191], v[116:119]
	v_mfma_f32_16x16x32_bf16 v[112:115], v[180:183], v[188:191], v[112:115]
	v_mfma_f32_16x16x32_bf16 v[100:103], v[172:175], v[196:199], v[100:103]
	v_mfma_f32_16x16x32_bf16 v[96:99], v[180:183], v[196:199], v[96:99]
	v_mfma_f32_16x16x32_bf16 v[84:87], v[172:175], v[204:207], v[84:87]
	v_mfma_f32_16x16x32_bf16 v[80:83], v[180:183], v[204:207], v[80:83]
	v_mfma_f32_16x16x32_bf16 v[68:71], v[172:175], v[212:215], v[68:71]
	v_mfma_f32_16x16x32_bf16 v[64:67], v[180:183], v[212:215], v[64:67]
	s_setprio 0
	s_barrier
	s_mov_b32 m0, s80
	v_lshl_add_u64 v[216:217], s[74:75], 0, v[148:149]
	ds_read_b128 v[184:187], v170 offset:16384
	ds_read_b128 v[188:191], v170 offset:17408
	ds_read_b128 v[192:195], v170 offset:18432
	ds_read_b128 v[196:199], v170 offset:19456
	ds_read_b128 v[200:203], v170 offset:20480
	ds_read_b128 v[204:207], v170 offset:21504
	ds_read_b128 v[208:211], v170 offset:22528
	ds_read_b128 v[212:215], v170 offset:23552
	global_load_lds_dwordx4 v[216:217], off
	v_lshl_add_u64 v[218:219], s[74:75], 0, v[152:153]
	s_mov_b32 m0, s61
	v_lshl_add_u64 v[220:221], s[76:77], 0, v[148:149]
	global_load_lds_dwordx4 v[218:219], off
	s_mov_b32 m0, s65
	v_lshl_add_u64 v[222:223], s[72:73], 0, v[150:151]
	global_load_lds_dwordx4 v[220:221], off
	v_lshl_add_u64 v[220:221], s[76:77], 0, v[152:153]
	s_mov_b32 m0, s64
	s_nop 0
	global_load_lds_dwordx4 v[220:221], off
	v_lshl_add_u64 v[220:221], s[72:73], 0, v[146:147]
	s_mov_b32 m0, s37
	s_nop 0
	global_load_lds_dwordx4 v[220:221], off
	s_mov_b32 m0, s38
	s_nop 0
	global_load_lds_dwordx4 v[222:223], off
	s_waitcnt vmcnt(8)
	s_waitcnt lgkmcnt(0)
	s_barrier
; #define PG8_STAGE(bufoff, gbase, voff) do { _Pragma("unroll") for (int _i = 0; _i < 2; ++_i) \
;         __builtin_amdgcn_global_load_lds((const unsigned*)((const char*)(gbase) + (voff)[_i]), (LAS unsigned*)(lds + (bufoff) + ldsw + _i * 8192), 16, 0, 0); } while (0)
; #define PG8_LDA(dst, b, h) do { _Pragma("unroll") for (int m = 0; m < 4; ++m) _Pragma("unroll") for (int k = 0; k < 2; ++k) dst[m][k] = *(const LAS bf16x8*)(lds + PG8_SA(b, h) + aoff + m * 2048 + k * 1024); } while (0)
; #define PG8_LDB(dst, b, h) do { _Pragma("unroll") for (int n = 0; n < 2; ++n) _Pragma("unroll") for (int k = 0; k < 2; ++k) dst[n][k] = *(const LAS bf16x8*)(lds + PG8_SB(b, h) + boff + n * 2048 + k * 1024); } while (0)
; #define PG8_MMA(ai, bj, At, Bt) do { __builtin_amdgcn_s_setprio(1); _Pragma("unroll") for (int m = 0; m < 4; ++m) _Pragma("unroll") for (int n = 0; n < 2; ++n) _Pragma("unroll") for (int k = 0; k < 2; ++k) \
;         acc[ai][bj][m][n] = __builtin_amdgcn_mfma_f32_16x16x32_bf16(Bt[n][k], At[m][k], acc[ai][bj][m][n], 0, 0, 0); __builtin_amdgcn_s_setprio(0); } while (0)
; #define PG8_WAIT_V(n) asm volatile("s_waitcnt vmcnt(" #n ")" ::: "memory")
; #define PG8_WAIT_L(n) asm volatile("s_waitcnt lgkmcnt(" #n ")" ::: "memory")
; #define PG8_BAR __builtin_amdgcn_s_barrier()
; #define PG8_SCHED __builtin_amdgcn_sched_barrier(0)
; template <class EpiT>
; __device__ __forceinline__ void gemm_phase(LAS unsigned char* lds, const Gemm g, const StaticOrder& S, const EpiT& E) {
;     ...
;             PG8_WAIT_V(8); PG8_WAIT_L(0); PG8_BAR; PG8_MMA(1, 0, At, B0); PG8_MMA(1, 1, At, B1); PG8_BAR; PG8_SCHED;
;             PG8_LDB(B0, 1, 0); PG8_LDB(B1, 1, 1); PG8_SCHED; PG8_LDA(At, 1, 0); PG8_STAGE(PG8_SA(0, 1), a2 + hstepA, voffA);
;             PG8_WAIT_V(8); PG8_WAIT_L(0); PG8_BAR; PG8_MMA(0, 0, At, B0); PG8_MMA(0, 1, At, B1); PG8_BAR; PG8_SCHED;
	s_setprio 1
	v_mfma_f32_16x16x32_bf16 v[60:63], v[128:131], v[184:187], v[60:63]
	v_mfma_f32_16x16x32_bf16 v[56:59], v[136:139], v[184:187], v[56:59]
	v_mfma_f32_16x16x32_bf16 v[44:47], v[128:131], v[192:195], v[44:47]
	v_mfma_f32_16x16x32_bf16 v[40:43], v[136:139], v[192:195], v[40:43]
	v_mfma_f32_16x16x32_bf16 v[28:31], v[128:131], v[200:203], v[28:31]
	v_mfma_f32_16x16x32_bf16 v[24:27], v[136:139], v[200:203], v[24:27]
	v_mfma_f32_16x16x32_bf16 v[12:15], v[128:131], v[208:211], v[12:15]
	v_mfma_f32_16x16x32_bf16 v[8:11], v[136:139], v[208:211], v[8:11]
	v_mfma_f32_16x16x32_bf16 v[60:63], v[132:135], v[188:191], v[60:63]
	v_mfma_f32_16x16x32_bf16 v[56:59], v[140:143], v[188:191], v[56:59]
	v_mfma_f32_16x16x32_bf16 v[44:47], v[132:135], v[196:199], v[44:47]
	v_mfma_f32_16x16x32_bf16 v[40:43], v[140:143], v[196:199], v[40:43]
	v_mfma_f32_16x16x32_bf16 v[28:31], v[132:135], v[204:207], v[28:31]
	v_mfma_f32_16x16x32_bf16 v[24:27], v[140:143], v[204:207], v[24:27]
	v_mfma_f32_16x16x32_bf16 v[12:15], v[132:135], v[212:215], v[12:15]
	v_mfma_f32_16x16x32_bf16 v[8:11], v[140:143], v[212:215], v[8:11]
	s_setprio 0
	s_setprio 1
	v_mfma_f32_16x16x32_bf16 v[52:55], v[160:163], v[184:187], v[52:55]
	v_mfma_f32_16x16x32_bf16 v[48:51], v[176:179], v[184:187], v[48:51]
	v_mfma_f32_16x16x32_bf16 v[36:39], v[160:163], v[192:195], v[36:39]
	v_mfma_f32_16x16x32_bf16 v[32:35], v[176:179], v[192:195], v[32:35]
	v_mfma_f32_16x16x32_bf16 v[20:23], v[160:163], v[200:203], v[20:23]
	v_mfma_f32_16x16x32_bf16 v[16:19], v[176:179], v[200:203], v[16:19]
	v_mfma_f32_16x16x32_bf16 v[4:7], v[160:163], v[208:211], v[4:7]
	v_mfma_f32_16x16x32_bf16 v[0:3], v[176:179], v[208:211], v[0:3]
	v_mfma_f32_16x16x32_bf16 v[52:55], v[172:175], v[188:191], v[52:55]
	v_mfma_f32_16x16x32_bf16 v[48:51], v[180:183], v[188:191], v[48:51]
	v_mfma_f32_16x16x32_bf16 v[36:39], v[172:175], v[196:199], v[36:39]
	v_mfma_f32_16x16x32_bf16 v[32:35], v[180:183], v[196:199], v[32:35]
	v_mfma_f32_16x16x32_bf16 v[20:23], v[172:175], v[204:207], v[20:23]
	v_mfma_f32_16x16x32_bf16 v[16:19], v[180:183], v[204:207], v[16:19]
	v_mfma_f32_16x16x32_bf16 v[4:7], v[172:175], v[212:215], v[4:7]
	v_mfma_f32_16x16x32_bf16 v[0:3], v[180:183], v[212:215], v[0:3]
	s_setprio 0
	s_barrier
	v_add_u32_e32 v140, s59, v145
	v_add_u32_e32 v180, s58, v145
	ds_read_b128 v[128:131], v140
	ds_read_b128 v[132:135], v140 offset:1024
	ds_read_b128 v[136:139], v140 offset:2048
	ds_read_b128 v[140:143], v140 offset:3072
	ds_read_b128 v[160:163], v180
	ds_read_b128 v[172:175], v180 offset:1024
	ds_read_b128 v[176:179], v180 offset:2048
	ds_read_b128 v[180:183], v180 offset:3072
	s_mov_b32 m0, s39
	v_lshl_add_u64 v[224:225], s[70:71], 0, v[146:147]
	ds_read_b128 v[184:187], v170 offset:32768
	ds_read_b128 v[188:191], v170 offset:33792
	ds_read_b128 v[192:195], v170 offset:34816
	ds_read_b128 v[196:199], v170 offset:35840
	ds_read_b128 v[200:203], v170 offset:36864
	ds_read_b128 v[204:207], v170 offset:37888
	ds_read_b128 v[208:211], v170 offset:38912
	ds_read_b128 v[212:215], v170 offset:39936
	global_load_lds_dwordx4 v[224:225], off
	v_lshl_add_u64 v[224:225], s[70:71], 0, v[150:151]
	s_mov_b32 m0, s41
	s_nop 0
	global_load_lds_dwordx4 v[224:225], off
	s_waitcnt vmcnt(8)
	s_waitcnt lgkmcnt(0)
	s_barrier
	s_setprio 1
	v_mfma_f32_16x16x32_bf16 v[124:127], v[128:131], v[184:187], v[124:127]
	v_mfma_f32_16x16x32_bf16 v[120:123], v[136:139], v[184:187], v[120:123]
	v_mfma_f32_16x16x32_bf16 v[108:111], v[128:131], v[192:195], v[108:111]
	v_mfma_f32_16x16x32_bf16 v[104:107], v[136:139], v[192:195], v[104:107]
	v_mfma_f32_16x16x32_bf16 v[92:95], v[128:131], v[200:203], v[92:95]
	v_mfma_f32_16x16x32_bf16 v[88:91], v[136:139], v[200:203], v[88:91]
	v_mfma_f32_16x16x32_bf16 v[76:79], v[128:131], v[208:211], v[76:79]
	v_mfma_f32_16x16x32_bf16 v[72:75], v[136:139], v[208:211], v[72:75]
	v_mfma_f32_16x16x32_bf16 v[124:127], v[132:135], v[188:191], v[124:127]
	v_mfma_f32_16x16x32_bf16 v[120:123], v[140:143], v[188:191], v[120:123]
	v_mfma_f32_16x16x32_bf16 v[108:111], v[132:135], v[196:199], v[108:111]
	v_mfma_f32_16x16x32_bf16 v[104:107], v[140:143], v[196:199], v[104:107]
	v_mfma_f32_16x16x32_bf16 v[92:95], v[132:135], v[204:207], v[92:95]
	v_mfma_f32_16x16x32_bf16 v[88:91], v[140:143], v[204:207], v[88:91]
	v_mfma_f32_16x16x32_bf16 v[76:79], v[132:135], v[212:215], v[76:79]
	v_mfma_f32_16x16x32_bf16 v[72:75], v[140:143], v[212:215], v[72:75]
	s_setprio 0
	s_setprio 1
	v_mfma_f32_16x16x32_bf16 v[116:119], v[160:163], v[184:187], v[116:119]
	v_mfma_f32_16x16x32_bf16 v[112:115], v[176:179], v[184:187], v[112:115]
	v_mfma_f32_16x16x32_bf16 v[100:103], v[160:163], v[192:195], v[100:103]
	v_mfma_f32_16x16x32_bf16 v[96:99], v[176:179], v[192:195], v[96:99]
	v_mfma_f32_16x16x32_bf16 v[84:87], v[160:163], v[200:203], v[84:87]
	v_mfma_f32_16x16x32_bf16 v[80:83], v[176:179], v[200:203], v[80:83]
	v_mfma_f32_16x16x32_bf16 v[68:71], v[160:163], v[208:211], v[68:71]
	v_mfma_f32_16x16x32_bf16 v[64:67], v[176:179], v[208:211], v[64:67]
	v_mfma_f32_16x16x32_bf16 v[116:119], v[172:175], v[188:191], v[116:119]
	v_mfma_f32_16x16x32_bf16 v[112:115], v[180:183], v[188:191], v[112:115]
	v_mfma_f32_16x16x32_bf16 v[100:103], v[172:175], v[196:199], v[100:103]
	v_mfma_f32_16x16x32_bf16 v[96:99], v[180:183], v[196:199], v[96:99]
	v_mfma_f32_16x16x32_bf16 v[84:87], v[172:175], v[204:207], v[84:87]
	v_mfma_f32_16x16x32_bf16 v[80:83], v[180:183], v[204:207], v[80:83]
	v_mfma_f32_16x16x32_bf16 v[68:71], v[172:175], v[212:215], v[68:71]
	v_mfma_f32_16x16x32_bf16 v[64:67], v[180:183], v[212:215], v[64:67]
	s_setprio 0
	s_barrier
; #define PG8_STAGE(bufoff, gbase, voff) do { _Pragma("unroll") for (int _i = 0; _i < 2; ++_i) \
;         __builtin_amdgcn_global_load_lds((const unsigned*)((const char*)(gbase) + (voff)[_i]), (LAS unsigned*)(lds + (bufoff) + ldsw + _i * 8192), 16, 0, 0); } while (0)
; #define PG8_LDA(dst, b, h) do { _Pragma("unroll") for (int m = 0; m < 4; ++m) _Pragma("unroll") for (int k = 0; k < 2; ++k) dst[m][k] = *(const LAS bf16x8*)(lds + PG8_SA(b, h) + aoff + m * 2048 + k * 1024); } while (0)
; #define PG8_MMA(ai, bj, At, Bt) do { __builtin_amdgcn_s_setprio(1); _Pragma("unroll") for (int m = 0; m < 4; ++m) _Pragma("unroll") for (int n = 0; n < 2; ++n) _Pragma("unroll") for (int k = 0; k < 2; ++k) \
;         acc[ai][bj][m][n] = __builtin_amdgcn_mfma_f32_16x16x32_bf16(Bt[n][k], At[m][k], acc[ai][bj][m][n], 0, 0, 0); __builtin_amdgcn_s_setprio(0); } while (0)
; #define PG8_WAIT_V(n) asm volatile("s_waitcnt vmcnt(" #n ")" ::: "memory")
; #define PG8_WAIT_L(n) asm volatile("s_waitcnt lgkmcnt(" #n ")" ::: "memory")
; #define PG8_BAR __builtin_amdgcn_s_barrier()
; #define PG8_SCHED __builtin_amdgcn_sched_barrier(0)
; template <class EpiT>
; __device__ __forceinline__ void gemm_phase(LAS unsigned char* lds, const Gemm g, const StaticOrder& S, const EpiT& E) {
;     ...
;             PG8_LDA(At, 1, 1); PG8_STAGE(PG8_SB(1, 0), b3, voffB); PG8_STAGE(PG8_SB(1, 1), b3 + hstepB, voffB); PG8_STAGE(PG8_SA(1, 0), a3, voffA);
;             PG8_WAIT_V(8); PG8_WAIT_L(0); PG8_BAR; PG8_MMA(1, 0, At, B0); PG8_MMA(1, 1, At, B1); PG8_BAR; PG8_SCHED;
;         }
;         if (wr == 0) PG8_BAR;
	s_mov_b32 m0, s57
	v_lshl_add_u64 v[216:217], v[216:217], 0, s[10:11]
	ds_read_b128 v[184:187], v170 offset:49152
	ds_read_b128 v[188:191], v170 offset:50176
	ds_read_b128 v[192:195], v170 offset:51200
	ds_read_b128 v[196:199], v170 offset:52224
	ds_read_b128 v[200:203], v170 offset:53248
	ds_read_b128 v[204:207], v170 offset:54272
	ds_read_b128 v[208:211], v170 offset:55296
	ds_read_b128 v[212:215], v170 offset:56320
	global_load_lds_dwordx4 v[216:217], off
	v_lshl_add_u64 v[216:217], v[218:219], 0, s[10:11]
	s_mov_b32 m0, s55
	s_nop 0
	global_load_lds_dwordx4 v[216:217], off
	v_lshl_add_u64 v[216:217], s[68:69], 0, v[148:149]
	s_mov_b32 m0, s56
	s_nop 0
	global_load_lds_dwordx4 v[216:217], off
	v_lshl_add_u64 v[216:217], s[68:69], 0, v[152:153]
	s_mov_b32 m0, s54
	s_nop 0
	global_load_lds_dwordx4 v[216:217], off
	v_lshl_add_u64 v[216:217], v[220:221], 0, s[10:11]
	s_mov_b32 m0, s44
	s_nop 0
	global_load_lds_dwordx4 v[216:217], off
	v_lshl_add_u64 v[216:217], v[222:223], 0, s[10:11]
	s_mov_b32 m0, s45
	s_nop 0
	global_load_lds_dwordx4 v[216:217], off
	s_waitcnt vmcnt(8)
	s_waitcnt lgkmcnt(0)
	s_barrier
	s_setprio 1
	v_mfma_f32_16x16x32_bf16 v[60:63], v[128:131], v[184:187], v[60:63]
	v_mfma_f32_16x16x32_bf16 v[56:59], v[136:139], v[184:187], v[56:59]
	v_mfma_f32_16x16x32_bf16 v[44:47], v[128:131], v[192:195], v[44:47]
	v_mfma_f32_16x16x32_bf16 v[40:43], v[136:139], v[192:195], v[40:43]
	v_mfma_f32_16x16x32_bf16 v[28:31], v[128:131], v[200:203], v[28:31]
	v_mfma_f32_16x16x32_bf16 v[24:27], v[136:139], v[200:203], v[24:27]
	v_mfma_f32_16x16x32_bf16 v[12:15], v[128:131], v[208:211], v[12:15]
	v_mfma_f32_16x16x32_bf16 v[8:11], v[136:139], v[208:211], v[8:11]
	v_mfma_f32_16x16x32_bf16 v[60:63], v[132:135], v[188:191], v[60:63]
	v_mfma_f32_16x16x32_bf16 v[56:59], v[140:143], v[188:191], v[56:59]
	v_mfma_f32_16x16x32_bf16 v[44:47], v[132:135], v[196:199], v[44:47]
	v_mfma_f32_16x16x32_bf16 v[40:43], v[140:143], v[196:199], v[40:43]
	v_mfma_f32_16x16x32_bf16 v[28:31], v[132:135], v[204:207], v[28:31]
	v_mfma_f32_16x16x32_bf16 v[24:27], v[140:143], v[204:207], v[24:27]
	v_mfma_f32_16x16x32_bf16 v[12:15], v[132:135], v[212:215], v[12:15]
	v_mfma_f32_16x16x32_bf16 v[8:11], v[140:143], v[212:215], v[8:11]
	s_setprio 0
	s_setprio 1
	v_mfma_f32_16x16x32_bf16 v[52:55], v[160:163], v[184:187], v[52:55]
	v_mfma_f32_16x16x32_bf16 v[48:51], v[176:179], v[184:187], v[48:51]
	v_mfma_f32_16x16x32_bf16 v[36:39], v[160:163], v[192:195], v[36:39]
	v_mfma_f32_16x16x32_bf16 v[32:35], v[176:179], v[192:195], v[32:35]
	v_mfma_f32_16x16x32_bf16 v[20:23], v[160:163], v[200:203], v[20:23]
	v_mfma_f32_16x16x32_bf16 v[16:19], v[176:179], v[200:203], v[16:19]
	v_mfma_f32_16x16x32_bf16 v[4:7], v[160:163], v[208:211], v[4:7]
	v_mfma_f32_16x16x32_bf16 v[0:3], v[176:179], v[208:211], v[0:3]
	v_mfma_f32_16x16x32_bf16 v[52:55], v[172:175], v[188:191], v[52:55]
	v_mfma_f32_16x16x32_bf16 v[48:51], v[180:183], v[188:191], v[48:51]
	v_mfma_f32_16x16x32_bf16 v[36:39], v[172:175], v[196:199], v[36:39]
	v_mfma_f32_16x16x32_bf16 v[32:35], v[180:183], v[196:199], v[32:35]
	v_mfma_f32_16x16x32_bf16 v[20:23], v[172:175], v[204:207], v[20:23]
	v_mfma_f32_16x16x32_bf16 v[16:19], v[180:183], v[204:207], v[16:19]
	v_mfma_f32_16x16x32_bf16 v[4:7], v[172:175], v[212:215], v[4:7]
	v_mfma_f32_16x16x32_bf16 v[0:3], v[180:183], v[212:215], v[0:3]
	s_setprio 0
	s_barrier
	s_movk_i32 s54, 0x100
	s_andn2_b64 vcc, exec, s[4:5]
	s_mov_b64 s[68:69], -1
	s_mov_b64 s[4:5], 0
	s_cbranch_vccz .LBB0_296
	s_and_b64 vcc, exec, s[12:13]
	s_cbranch_vccz .LBB0_299
	s_barrier

; #define PG8_STAGE(bufoff, gbase, voff) do { _Pragma("unroll") for (int _i = 0; _i < 2; ++_i) \
;         __builtin_amdgcn_global_load_lds((const unsigned*)((const char*)(gbase) + (voff)[_i]), (LAS unsigned*)(lds + (bufoff) + ldsw + _i * 8192), 16, 0, 0); } while (0)
; #define PG8_LDA(dst, b, h) do { _Pragma("unroll") for (int m = 0; m < 4; ++m) _Pragma("unroll") for (int k = 0; k < 2; ++k) dst[m][k] = *(const LAS bf16x8*)(lds + PG8_SA(b, h) + aoff + m * 2048 + k * 1024); } while (0)
; #define PG8_LDB(dst, b, h) do { _Pragma("unroll") for (int n = 0; n < 2; ++n) _Pragma("unroll") for (int k = 0; k < 2; ++k) dst[n][k] = *(const LAS bf16x8*)(lds + PG8_SB(b, h) + boff + n * 2048 + k * 1024); } while (0)
; #define PG8_MMA(ai, bj, At, Bt) do { __builtin_amdgcn_s_setprio(1); _Pragma("unroll") for (int m = 0; m < 4; ++m) _Pragma("unroll") for (int n = 0; n < 2; ++n) _Pragma("unroll") for (int k = 0; k < 2; ++k) \
;         acc[ai][bj][m][n] = __builtin_amdgcn_mfma_f32_16x16x32_bf16(Bt[n][k], At[m][k], acc[ai][bj][m][n], 0, 0, 0); __builtin_amdgcn_s_setprio(0); } while (0)
; #define PG8_WAIT_V(n) asm volatile("s_waitcnt vmcnt(" #n ")" ::: "memory")
; #define PG8_WAIT_L(n) asm volatile("s_waitcnt lgkmcnt(" #n ")" ::: "memory")
; #define PG8_BAR __builtin_amdgcn_s_barrier()
; template <class EpiT>
; __device__ __forceinline__ void gemm_phase(LAS unsigned char* lds, const Gemm g, const StaticOrder& S, const EpiT& E) {
;     ...
;         const char* nA = has_next ? (const char*)g.A + (size_t)nxt.pm * tstepA + (size_t)nxt.pn * g.a_koff * 2 : cA; const char* nB = has_next ? (const char*)g.Bt + (size_t)nxt.pn * tstepB : cB;
;         for (int t = 0; t < nt; t += 2) {
;             const bool last = (t == nt - 2);
;             const char* a1 = cA + (size_t)(t + 1) * kstep;
;             const char* a2 = last ? nA : cA + (size_t)(t + 2) * kstep; const char* b2 = last ? nB : cB + (size_t)(t + 2) * kstep;
;             const char* a3 = a2 + kstep; const char* b3 = b2 + kstep;
;             PG8_LDB(B0, 0, 0); PG8_LDB(B1, 0, 1); PG8_SCHED; PG8_LDA(At, 0, 0); PG8_STAGE(PG8_SA(1, 1), a1 + hstepA, voffA);
;             PG8_WAIT_V(8); PG8_WAIT_L(0); PG8_BAR; PG8_MMA(0, 0, At, B0); PG8_MMA(0, 1, At, B1); PG8_BAR; PG8_SCHED;
;             PG8_LDA(At, 0, 1); PG8_STAGE(PG8_SB(0, 0), b2, voffB); PG8_STAGE(PG8_SB(0, 1), b2 + hstepB, voffB); PG8_STAGE(PG8_SA(0, 0), a2, voffA);
.LBB0_392:
	ds_read_b128 v[154:157], v149
	ds_read_b128 v[158:161], v149 offset:1024
	ds_read_b128 v[170:173], v149 offset:2048
	ds_read_b128 v[174:177], v149 offset:3072
	ds_read_b128 v[178:181], v150
	ds_read_b128 v[182:185], v150 offset:1024
	ds_read_b128 v[186:189], v150 offset:2048
	ds_read_b128 v[190:193], v150 offset:3072
	s_add_u32 s20, s18, 0xfff7c080
	s_addc_u32 s21, s19, -1
	s_cmp_eq_u32 s53, 28
	s_cselect_b32 s23, s5, s21
	s_cselect_b32 s22, s4, s20
	s_cselect_b32 s21, s17, s52
	s_cselect_b32 s20, s16, s51
	v_lshl_add_u64 v[162:163], s[18:19], 0, v[138:139]
	s_add_i32 m0, s35, 0xc000
	ds_read_b128 v[194:197], v151
	ds_read_b128 v[198:201], v151 offset:1024
	ds_read_b128 v[202:205], v151 offset:2048
	ds_read_b128 v[206:209], v151 offset:3072
	ds_read_b128 v[210:213], v151 offset:4096
	ds_read_b128 v[214:217], v151 offset:5120
	ds_read_b128 v[218:221], v151 offset:6144
	ds_read_b128 v[222:225], v151 offset:7168
	global_load_lds_dwordx4 v[162:163], off
	v_lshl_add_u64 v[162:163], s[18:19], 0, v[140:141]
	s_add_i32 m0, s35, 0xe000
	s_nop 0
	global_load_lds_dwordx4 v[162:163], off
	s_waitcnt vmcnt(8)
	s_waitcnt lgkmcnt(0)
	s_barrier
	s_setprio 1
	v_mfma_f32_16x16x32_bf16 v[124:127], v[154:157], v[194:197], v[124:127]
	v_mfma_f32_16x16x32_bf16 v[124:127], v[158:161], v[198:201], v[124:127]
	v_mfma_f32_16x16x32_bf16 v[108:111], v[154:157], v[202:205], v[108:111]
	v_mfma_f32_16x16x32_bf16 v[108:111], v[158:161], v[206:209], v[108:111]
	v_mfma_f32_16x16x32_bf16 v[92:95], v[154:157], v[210:213], v[92:95]
	v_mfma_f32_16x16x32_bf16 v[92:95], v[158:161], v[214:217], v[92:95]
	v_mfma_f32_16x16x32_bf16 v[76:79], v[154:157], v[218:221], v[76:79]
	v_mfma_f32_16x16x32_bf16 v[76:79], v[158:161], v[222:225], v[76:79]
	v_mfma_f32_16x16x32_bf16 v[120:123], v[170:173], v[194:197], v[120:123]
	v_mfma_f32_16x16x32_bf16 v[120:123], v[174:177], v[198:201], v[120:123]
	v_mfma_f32_16x16x32_bf16 v[104:107], v[170:173], v[202:205], v[104:107]
	v_mfma_f32_16x16x32_bf16 v[104:107], v[174:177], v[206:209], v[104:107]
	v_mfma_f32_16x16x32_bf16 v[88:91], v[170:173], v[210:213], v[88:91]
	v_mfma_f32_16x16x32_bf16 v[88:91], v[174:177], v[214:217], v[88:91]
	v_mfma_f32_16x16x32_bf16 v[72:75], v[170:173], v[218:221], v[72:75]
	v_mfma_f32_16x16x32_bf16 v[72:75], v[174:177], v[222:225], v[72:75]
	s_setprio 0
	s_setprio 1
	v_mfma_f32_16x16x32_bf16 v[116:119], v[178:181], v[194:197], v[116:119]
	v_mfma_f32_16x16x32_bf16 v[116:119], v[182:185], v[198:201], v[116:119]
	v_mfma_f32_16x16x32_bf16 v[100:103], v[178:181], v[202:205], v[100:103]
	v_mfma_f32_16x16x32_bf16 v[100:103], v[182:185], v[206:209], v[100:103]
	v_mfma_f32_16x16x32_bf16 v[84:87], v[178:181], v[210:213], v[84:87]
	v_mfma_f32_16x16x32_bf16 v[84:87], v[182:185], v[214:217], v[84:87]
	v_mfma_f32_16x16x32_bf16 v[68:71], v[178:181], v[218:221], v[68:71]
	v_mfma_f32_16x16x32_bf16 v[68:71], v[182:185], v[222:225], v[68:71]
	v_mfma_f32_16x16x32_bf16 v[112:115], v[186:189], v[194:197], v[112:115]
	v_mfma_f32_16x16x32_bf16 v[112:115], v[190:193], v[198:201], v[112:115]
	v_mfma_f32_16x16x32_bf16 v[96:99], v[186:189], v[202:205], v[96:99]
	v_mfma_f32_16x16x32_bf16 v[96:99], v[190:193], v[206:209], v[96:99]
	v_mfma_f32_16x16x32_bf16 v[80:83], v[186:189], v[210:213], v[80:83]
	v_mfma_f32_16x16x32_bf16 v[80:83], v[190:193], v[214:217], v[80:83]
	v_mfma_f32_16x16x32_bf16 v[64:67], v[186:189], v[218:221], v[64:67]
	v_mfma_f32_16x16x32_bf16 v[64:67], v[190:193], v[222:225], v[64:67]
	s_setprio 0
	s_barrier
	s_add_i32 s54, s44, s33
	v_lshl_add_u64 v[162:163], s[20:21], 0, v[130:131]
	s_mov_b32 m0, s54
	ds_read_b128 v[194:197], v151 offset:16384
	ds_read_b128 v[198:201], v151 offset:17408
	ds_read_b128 v[202:205], v151 offset:18432
	ds_read_b128 v[206:209], v151 offset:19456
	ds_read_b128 v[210:213], v151 offset:20480
	ds_read_b128 v[214:217], v151 offset:21504
	ds_read_b128 v[218:221], v151 offset:22528
	ds_read_b128 v[222:225], v151 offset:23552
	global_load_lds_dwordx4 v[162:163], off
	s_add_i32 m0, s54, 0x2000
	s_add_u32 s54, s20, 0x84000
	v_lshl_add_u64 v[166:167], s[20:21], 0, v[134:135]
	s_addc_u32 s55, s21, 0
	s_add_i32 s56, s45, s33
	global_load_lds_dwordx4 v[166:167], off
	v_lshl_add_u64 v[226:227], s[54:55], 0, v[130:131]
	s_mov_b32 m0, s56
	v_lshl_add_u64 v[228:229], s[22:23], 0, v[132:133]
	global_load_lds_dwordx4 v[226:227], off
	v_lshl_add_u64 v[226:227], s[54:55], 0, v[134:135]
	s_add_i32 m0, s56, 0x2000
	s_nop 0
	global_load_lds_dwordx4 v[226:227], off
	v_lshl_add_u64 v[226:227], s[22:23], 0, v[128:129]
	s_mov_b32 m0, s35
	s_nop 0
	global_load_lds_dwordx4 v[226:227], off
	s_mov_b32 m0, s36
	s_nop 0
	global_load_lds_dwordx4 v[228:229], off
	s_waitcnt vmcnt(8)
	s_waitcnt lgkmcnt(0)
	s_barrier
; #define PG8_STAGE(bufoff, gbase, voff) do { _Pragma("unroll") for (int _i = 0; _i < 2; ++_i) \
;         __builtin_amdgcn_global_load_lds((const unsigned*)((const char*)(gbase) + (voff)[_i]), (LAS unsigned*)(lds + (bufoff) + ldsw + _i * 8192), 16, 0, 0); } while (0)
; #define PG8_LDA(dst, b, h) do { _Pragma("unroll") for (int m = 0; m < 4; ++m) _Pragma("unroll") for (int k = 0; k < 2; ++k) dst[m][k] = *(const LAS bf16x8*)(lds + PG8_SA(b, h) + aoff + m * 2048 + k * 1024); } while (0)
; #define PG8_LDB(dst, b, h) do { _Pragma("unroll") for (int n = 0; n < 2; ++n) _Pragma("unroll") for (int k = 0; k < 2; ++k) dst[n][k] = *(const LAS bf16x8*)(lds + PG8_SB(b, h) + boff + n * 2048 + k * 1024); } while (0)
; #define PG8_MMA(ai, bj, At, Bt) do { __builtin_amdgcn_s_setprio(1); _Pragma("unroll") for (int m = 0; m < 4; ++m) _Pragma("unroll") for (int n = 0; n < 2; ++n) _Pragma("unroll") for (int k = 0; k < 2; ++k) \
;         acc[ai][bj][m][n] = __builtin_amdgcn_mfma_f32_16x16x32_bf16(Bt[n][k], At[m][k], acc[ai][bj][m][n], 0, 0, 0); __builtin_amdgcn_s_setprio(0); } while (0)
; #define PG8_WAIT_V(n) asm volatile("s_waitcnt vmcnt(" #n ")" ::: "memory")
; #define PG8_WAIT_L(n) asm volatile("s_waitcnt lgkmcnt(" #n ")" ::: "memory")
; #define PG8_BAR __builtin_amdgcn_s_barrier()
; #define PG8_SCHED __builtin_amdgcn_sched_barrier(0)
; template <class EpiT>
; __device__ __forceinline__ void gemm_phase(LAS unsigned char* lds, const Gemm g, const StaticOrder& S, const EpiT& E) {
;     ...
;             PG8_WAIT_V(8); PG8_WAIT_L(0); PG8_BAR; PG8_MMA(1, 0, At, B0); PG8_MMA(1, 1, At, B1); PG8_BAR; PG8_SCHED;
;             PG8_LDB(B0, 1, 0); PG8_LDB(B1, 1, 1); PG8_SCHED; PG8_LDA(At, 1, 0); PG8_STAGE(PG8_SA(0, 1), a2 + hstepA, voffA);
;             PG8_WAIT_V(8); PG8_WAIT_L(0); PG8_BAR; PG8_MMA(0, 0, At, B0); PG8_MMA(0, 1, At, B1); PG8_BAR; PG8_SCHED;
	s_setprio 1
	v_mfma_f32_16x16x32_bf16 v[60:63], v[154:157], v[194:197], v[60:63]
	v_mfma_f32_16x16x32_bf16 v[60:63], v[158:161], v[198:201], v[60:63]
	v_mfma_f32_16x16x32_bf16 v[44:47], v[154:157], v[202:205], v[44:47]
	v_mfma_f32_16x16x32_bf16 v[44:47], v[158:161], v[206:209], v[44:47]
	v_mfma_f32_16x16x32_bf16 v[28:31], v[154:157], v[210:213], v[28:31]
	v_mfma_f32_16x16x32_bf16 v[28:31], v[158:161], v[214:217], v[28:31]
	v_mfma_f32_16x16x32_bf16 v[12:15], v[154:157], v[218:221], v[12:15]
	v_mfma_f32_16x16x32_bf16 v[12:15], v[158:161], v[222:225], v[12:15]
	v_mfma_f32_16x16x32_bf16 v[56:59], v[170:173], v[194:197], v[56:59]
	v_mfma_f32_16x16x32_bf16 v[56:59], v[174:177], v[198:201], v[56:59]
	v_mfma_f32_16x16x32_bf16 v[40:43], v[170:173], v[202:205], v[40:43]
	v_mfma_f32_16x16x32_bf16 v[40:43], v[174:177], v[206:209], v[40:43]
	v_mfma_f32_16x16x32_bf16 v[24:27], v[170:173], v[210:213], v[24:27]
	v_mfma_f32_16x16x32_bf16 v[24:27], v[174:177], v[214:217], v[24:27]
	v_mfma_f32_16x16x32_bf16 v[8:11], v[170:173], v[218:221], v[8:11]
	v_mfma_f32_16x16x32_bf16 v[8:11], v[174:177], v[222:225], v[8:11]
	s_setprio 0
	s_setprio 1
	v_mfma_f32_16x16x32_bf16 v[52:55], v[178:181], v[194:197], v[52:55]
	v_mfma_f32_16x16x32_bf16 v[52:55], v[182:185], v[198:201], v[52:55]
	v_mfma_f32_16x16x32_bf16 v[36:39], v[178:181], v[202:205], v[36:39]
	v_mfma_f32_16x16x32_bf16 v[36:39], v[182:185], v[206:209], v[36:39]
	v_mfma_f32_16x16x32_bf16 v[20:23], v[178:181], v[210:213], v[20:23]
	v_mfma_f32_16x16x32_bf16 v[20:23], v[182:185], v[214:217], v[20:23]
	v_mfma_f32_16x16x32_bf16 v[4:7], v[178:181], v[218:221], v[4:7]
	v_mfma_f32_16x16x32_bf16 v[4:7], v[182:185], v[222:225], v[4:7]
	v_mfma_f32_16x16x32_bf16 v[48:51], v[186:189], v[194:197], v[48:51]
	v_mfma_f32_16x16x32_bf16 v[48:51], v[190:193], v[198:201], v[48:51]
	v_mfma_f32_16x16x32_bf16 v[32:35], v[186:189], v[202:205], v[32:35]
	v_mfma_f32_16x16x32_bf16 v[32:35], v[190:193], v[206:209], v[32:35]
	v_mfma_f32_16x16x32_bf16 v[16:19], v[186:189], v[210:213], v[16:19]
	v_mfma_f32_16x16x32_bf16 v[16:19], v[190:193], v[214:217], v[16:19]
	v_mfma_f32_16x16x32_bf16 v[0:3], v[186:189], v[218:221], v[0:3]
	v_mfma_f32_16x16x32_bf16 v[0:3], v[190:193], v[222:225], v[0:3]
	s_setprio 0
	s_barrier
	s_add_i32 s54, 0, 0x18000
	v_add_u32_e32 v153, s54, v146
	s_add_i32 s55, 0, 0x1c000
	ds_read_b128 v[154:157], v153
	ds_read_b128 v[158:161], v153 offset:1024
	ds_read_b128 v[170:173], v153 offset:2048
	ds_read_b128 v[174:177], v153 offset:3072
	v_add_u32_e32 v153, s55, v146
	ds_read_b128 v[178:181], v153
	ds_read_b128 v[182:185], v153 offset:1024
	ds_read_b128 v[186:189], v153 offset:2048
	ds_read_b128 v[190:193], v153 offset:3072
	s_add_u32 s22, s22, 0x84000
	s_addc_u32 s23, s23, 0
	s_mov_b32 m0, s37
	v_lshl_add_u64 v[230:231], s[22:23], 0, v[128:129]
	ds_read_b128 v[194:197], v151 offset:32768
	ds_read_b128 v[198:201], v151 offset:33792
	ds_read_b128 v[202:205], v151 offset:34816
	ds_read_b128 v[206:209], v151 offset:35840
	ds_read_b128 v[210:213], v151 offset:36864
	ds_read_b128 v[214:217], v151 offset:37888
	ds_read_b128 v[218:221], v151 offset:38912
	ds_read_b128 v[222:225], v151 offset:39936
	global_load_lds_dwordx4 v[230:231], off
	v_lshl_add_u64 v[230:231], s[22:23], 0, v[132:133]
	s_mov_b32 m0, s38
	s_nop 0
	global_load_lds_dwordx4 v[230:231], off
	s_waitcnt vmcnt(8)
	s_waitcnt lgkmcnt(0)
	s_barrier
	s_setprio 1
	v_mfma_f32_16x16x32_bf16 v[124:127], v[154:157], v[194:197], v[124:127]
	v_mfma_f32_16x16x32_bf16 v[124:127], v[158:161], v[198:201], v[124:127]
	v_mfma_f32_16x16x32_bf16 v[108:111], v[154:157], v[202:205], v[108:111]
	v_mfma_f32_16x16x32_bf16 v[108:111], v[158:161], v[206:209], v[108:111]
	v_mfma_f32_16x16x32_bf16 v[92:95], v[154:157], v[210:213], v[92:95]
	v_mfma_f32_16x16x32_bf16 v[92:95], v[158:161], v[214:217], v[92:95]
	v_mfma_f32_16x16x32_bf16 v[76:79], v[154:157], v[218:221], v[76:79]
	v_mfma_f32_16x16x32_bf16 v[76:79], v[158:161], v[222:225], v[76:79]
	v_mfma_f32_16x16x32_bf16 v[120:123], v[170:173], v[194:197], v[120:123]
	v_mfma_f32_16x16x32_bf16 v[120:123], v[174:177], v[198:201], v[120:123]
	v_mfma_f32_16x16x32_bf16 v[104:107], v[170:173], v[202:205], v[104:107]
	v_mfma_f32_16x16x32_bf16 v[104:107], v[174:177], v[206:209], v[104:107]
	v_mfma_f32_16x16x32_bf16 v[88:91], v[170:173], v[210:213], v[88:91]
	v_mfma_f32_16x16x32_bf16 v[88:91], v[174:177], v[214:217], v[88:91]
	v_mfma_f32_16x16x32_bf16 v[72:75], v[170:173], v[218:221], v[72:75]
	v_mfma_f32_16x16x32_bf16 v[72:75], v[174:177], v[222:225], v[72:75]
	s_setprio 0
	s_setprio 1
	v_mfma_f32_16x16x32_bf16 v[116:119], v[178:181], v[194:197], v[116:119]
	v_mfma_f32_16x16x32_bf16 v[116:119], v[182:185], v[198:201], v[116:119]
	v_mfma_f32_16x16x32_bf16 v[100:103], v[178:181], v[202:205], v[100:103]
	v_mfma_f32_16x16x32_bf16 v[100:103], v[182:185], v[206:209], v[100:103]
	v_mfma_f32_16x16x32_bf16 v[84:87], v[178:181], v[210:213], v[84:87]
	v_mfma_f32_16x16x32_bf16 v[84:87], v[182:185], v[214:217], v[84:87]
	v_mfma_f32_16x16x32_bf16 v[68:71], v[178:181], v[218:221], v[68:71]
	v_mfma_f32_16x16x32_bf16 v[68:71], v[182:185], v[222:225], v[68:71]
	v_mfma_f32_16x16x32_bf16 v[112:115], v[186:189], v[194:197], v[112:115]
	v_mfma_f32_16x16x32_bf16 v[112:115], v[190:193], v[198:201], v[112:115]
	v_mfma_f32_16x16x32_bf16 v[96:99], v[186:189], v[202:205], v[96:99]
	v_mfma_f32_16x16x32_bf16 v[96:99], v[190:193], v[206:209], v[96:99]
	v_mfma_f32_16x16x32_bf16 v[80:83], v[186:189], v[210:213], v[80:83]
	v_mfma_f32_16x16x32_bf16 v[80:83], v[190:193], v[214:217], v[80:83]
	v_mfma_f32_16x16x32_bf16 v[64:67], v[186:189], v[218:221], v[64:67]
	v_mfma_f32_16x16x32_bf16 v[64:67], v[190:193], v[222:225], v[64:67]
	s_setprio 0
	s_barrier
; #define PG8_STAGE(bufoff, gbase, voff) do { _Pragma("unroll") for (int _i = 0; _i < 2; ++_i) \
;         __builtin_amdgcn_global_load_lds((const unsigned*)((const char*)(gbase) + (voff)[_i]), (LAS unsigned*)(lds + (bufoff) + ldsw + _i * 8192), 16, 0, 0); } while (0)
; #define PG8_LDA(dst, b, h) do { _Pragma("unroll") for (int m = 0; m < 4; ++m) _Pragma("unroll") for (int k = 0; k < 2; ++k) dst[m][k] = *(const LAS bf16x8*)(lds + PG8_SA(b, h) + aoff + m * 2048 + k * 1024); } while (0)
; #define PG8_MMA(ai, bj, At, Bt) do { __builtin_amdgcn_s_setprio(1); _Pragma("unroll") for (int m = 0; m < 4; ++m) _Pragma("unroll") for (int n = 0; n < 2; ++n) _Pragma("unroll") for (int k = 0; k < 2; ++k) \
;         acc[ai][bj][m][n] = __builtin_amdgcn_mfma_f32_16x16x32_bf16(Bt[n][k], At[m][k], acc[ai][bj][m][n], 0, 0, 0); __builtin_amdgcn_s_setprio(0); } while (0)
; #define PG8_WAIT_V(n) asm volatile("s_waitcnt vmcnt(" #n ")" ::: "memory")
; #define PG8_WAIT_L(n) asm volatile("s_waitcnt lgkmcnt(" #n ")" ::: "memory")
; #define PG8_BAR __builtin_amdgcn_s_barrier()
; #define PG8_SCHED __builtin_amdgcn_sched_barrier(0)
; template <class EpiT>
; __device__ __forceinline__ void gemm_phase(LAS unsigned char* lds, const Gemm g, const StaticOrder& S, const EpiT& E) {
;     ...
;             PG8_LDA(At, 1, 1); PG8_STAGE(PG8_SB(1, 0), b3, voffB); PG8_STAGE(PG8_SB(1, 1), b3 + hstepB, voffB); PG8_STAGE(PG8_SA(1, 0), a3, voffA);
;             PG8_WAIT_V(8); PG8_WAIT_L(0); PG8_BAR; PG8_MMA(1, 0, At, B0); PG8_MMA(1, 1, At, B1); PG8_BAR; PG8_SCHED;
;         }
;         if (wr == 0) PG8_BAR;
	s_add_i32 s22, s54, s33
	v_lshl_add_u64 v[162:163], v[162:163], 0, s[12:13]
	s_mov_b32 m0, s22
	ds_read_b128 v[194:197], v151 offset:49152
	ds_read_b128 v[198:201], v151 offset:50176
	ds_read_b128 v[202:205], v151 offset:51200
	ds_read_b128 v[206:209], v151 offset:52224
	ds_read_b128 v[210:213], v151 offset:53248
	ds_read_b128 v[214:217], v151 offset:54272
	ds_read_b128 v[218:221], v151 offset:55296
	ds_read_b128 v[222:225], v151 offset:56320
	global_load_lds_dwordx4 v[162:163], off
	s_add_i32 m0, s22, 0x2000
	s_add_u32 s20, s20, 0x84080
	v_lshl_add_u64 v[162:163], v[166:167], 0, s[12:13]
	s_addc_u32 s21, s21, 0
	s_add_i32 s22, s55, s33
	global_load_lds_dwordx4 v[162:163], off
	v_lshl_add_u64 v[162:163], s[20:21], 0, v[130:131]
	s_mov_b32 m0, s22
	s_nop 0
	global_load_lds_dwordx4 v[162:163], off
	v_lshl_add_u64 v[162:163], s[20:21], 0, v[134:135]
	s_add_i32 m0, s22, 0x2000
	s_nop 0
	global_load_lds_dwordx4 v[162:163], off
	v_lshl_add_u64 v[162:163], v[226:227], 0, s[12:13]
	s_mov_b32 m0, s40
	s_nop 0
	global_load_lds_dwordx4 v[162:163], off
	v_lshl_add_u64 v[162:163], v[228:229], 0, s[12:13]
	s_mov_b32 m0, s41
	s_nop 0
	global_load_lds_dwordx4 v[162:163], off
	s_waitcnt vmcnt(8)
	s_waitcnt lgkmcnt(0)
	s_barrier
	s_setprio 1
	v_mfma_f32_16x16x32_bf16 v[60:63], v[154:157], v[194:197], v[60:63]
	v_mfma_f32_16x16x32_bf16 v[60:63], v[158:161], v[198:201], v[60:63]
	v_mfma_f32_16x16x32_bf16 v[44:47], v[154:157], v[202:205], v[44:47]
	v_mfma_f32_16x16x32_bf16 v[44:47], v[158:161], v[206:209], v[44:47]
	v_mfma_f32_16x16x32_bf16 v[28:31], v[154:157], v[210:213], v[28:31]
	v_mfma_f32_16x16x32_bf16 v[28:31], v[158:161], v[214:217], v[28:31]
	v_mfma_f32_16x16x32_bf16 v[12:15], v[154:157], v[218:221], v[12:15]
	v_mfma_f32_16x16x32_bf16 v[12:15], v[158:161], v[222:225], v[12:15]
	v_mfma_f32_16x16x32_bf16 v[56:59], v[170:173], v[194:197], v[56:59]
	v_mfma_f32_16x16x32_bf16 v[56:59], v[174:177], v[198:201], v[56:59]
	v_mfma_f32_16x16x32_bf16 v[40:43], v[170:173], v[202:205], v[40:43]
	v_mfma_f32_16x16x32_bf16 v[40:43], v[174:177], v[206:209], v[40:43]
	v_mfma_f32_16x16x32_bf16 v[24:27], v[170:173], v[210:213], v[24:27]
	v_mfma_f32_16x16x32_bf16 v[24:27], v[174:177], v[214:217], v[24:27]
	v_mfma_f32_16x16x32_bf16 v[8:11], v[170:173], v[218:221], v[8:11]
	v_mfma_f32_16x16x32_bf16 v[8:11], v[174:177], v[222:225], v[8:11]
	s_setprio 0
	s_setprio 1
	v_mfma_f32_16x16x32_bf16 v[52:55], v[178:181], v[194:197], v[52:55]
	v_mfma_f32_16x16x32_bf16 v[52:55], v[182:185], v[198:201], v[52:55]
	v_mfma_f32_16x16x32_bf16 v[36:39], v[178:181], v[202:205], v[36:39]
	v_mfma_f32_16x16x32_bf16 v[36:39], v[182:185], v[206:209], v[36:39]
	v_mfma_f32_16x16x32_bf16 v[20:23], v[178:181], v[210:213], v[20:23]
	v_mfma_f32_16x16x32_bf16 v[20:23], v[182:185], v[214:217], v[20:23]
	v_mfma_f32_16x16x32_bf16 v[4:7], v[178:181], v[218:221], v[4:7]
	v_mfma_f32_16x16x32_bf16 v[4:7], v[182:185], v[222:225], v[4:7]
	v_mfma_f32_16x16x32_bf16 v[48:51], v[186:189], v[194:197], v[48:51]
	v_mfma_f32_16x16x32_bf16 v[48:51], v[190:193], v[198:201], v[48:51]
	v_mfma_f32_16x16x32_bf16 v[32:35], v[186:189], v[202:205], v[32:35]
	v_mfma_f32_16x16x32_bf16 v[32:35], v[190:193], v[206:209], v[32:35]
	v_mfma_f32_16x16x32_bf16 v[16:19], v[186:189], v[210:213], v[16:19]
	v_mfma_f32_16x16x32_bf16 v[16:19], v[190:193], v[214:217], v[16:19]
	v_mfma_f32_16x16x32_bf16 v[0:3], v[186:189], v[218:221], v[0:3]
	v_mfma_f32_16x16x32_bf16 v[0:3], v[190:193], v[222:225], v[0:3]
	s_setprio 0
	s_barrier
	s_add_i32 s53, s53, 2
	s_add_u32 s18, s18, 0x100
	s_addc_u32 s19, s19, 0
	s_add_u32 s51, s51, 0x100
	s_addc_u32 s52, s52, 0
	s_cmp_gt_u32 s53, 29
	s_cbranch_scc0 .LBB0_392
	s_and_b64 vcc, exec, s[14:15]
	s_cbranch_vccz .LBB0_395
	s_barrier

; #define PG8_STAGE(bufoff, gbase, voff) do { _Pragma("unroll") for (int _i = 0; _i < 2; ++_i) \
;         __builtin_amdgcn_global_load_lds((const unsigned*)((const char*)(gbase) + (voff)[_i]), (LAS unsigned*)(lds + (bufoff) + ldsw + _i * 8192), 16, 0, 0); } while (0)
; #define PG8_LDA(dst, b, h) do { _Pragma("unroll") for (int m = 0; m < 4; ++m) _Pragma("unroll") for (int k = 0; k < 2; ++k) dst[m][k] = *(const LAS bf16x8*)(lds + PG8_SA(b, h) + aoff + m * 2048 + k * 1024); } while (0)
; #define PG8_LDB(dst, b, h) do { _Pragma("unroll") for (int n = 0; n < 2; ++n) _Pragma("unroll") for (int k = 0; k < 2; ++k) dst[n][k] = *(const LAS bf16x8*)(lds + PG8_SB(b, h) + boff + n * 2048 + k * 1024); } while (0)
; #define PG8_MMA(ai, bj, At, Bt) do { __builtin_amdgcn_s_setprio(1); _Pragma("unroll") for (int m = 0; m < 4; ++m) _Pragma("unroll") for (int n = 0; n < 2; ++n) _Pragma("unroll") for (int k = 0; k < 2; ++k) \
;         acc[ai][bj][m][n] = __builtin_amdgcn_mfma_f32_16x16x32_bf16(Bt[n][k], At[m][k], acc[ai][bj][m][n], 0, 0, 0); __builtin_amdgcn_s_setprio(0); } while (0)
; #define PG8_WAIT_V(n) asm volatile("s_waitcnt vmcnt(" #n ")" ::: "memory")
; #define PG8_WAIT_L(n) asm volatile("s_waitcnt lgkmcnt(" #n ")" ::: "memory")
; #define PG8_BAR __builtin_amdgcn_s_barrier()
; template <class EpiT>
; __device__ __forceinline__ void gemm_phase(LAS unsigned char* lds, const Gemm g, const StaticOrder& S, const EpiT& E) {
;     ...
;         const char* nA = has_next ? (const char*)g.A + (size_t)nxt.pm * tstepA + (size_t)nxt.pn * g.a_koff * 2 : cA; const char* nB = has_next ? (const char*)g.Bt + (size_t)nxt.pn * tstepB : cB;
;         for (int t = 0; t < nt; t += 2) {
;             const bool last = (t == nt - 2);
;             const char* a1 = cA + (size_t)(t + 1) * kstep;
;             const char* a2 = last ? nA : cA + (size_t)(t + 2) * kstep; const char* b2 = last ? nB : cB + (size_t)(t + 2) * kstep;
;             const char* a3 = a2 + kstep; const char* b3 = b2 + kstep;
;             PG8_LDB(B0, 0, 0); PG8_LDB(B1, 0, 1); PG8_SCHED; PG8_LDA(At, 0, 0); PG8_STAGE(PG8_SA(1, 1), a1 + hstepA, voffA);
;             PG8_WAIT_V(8); PG8_WAIT_L(0); PG8_BAR; PG8_MMA(0, 0, At, B0); PG8_MMA(0, 1, At, B1); PG8_BAR; PG8_SCHED;
;             PG8_LDA(At, 0, 1); PG8_STAGE(PG8_SB(0, 0), b2, voffB); PG8_STAGE(PG8_SB(0, 1), b2 + hstepB, voffB); PG8_STAGE(PG8_SA(0, 0), a2, voffA);
.LBB0_516:
	ds_read_b128 v[154:157], v150
	ds_read_b128 v[158:161], v150 offset:1024
	ds_read_b128 v[170:173], v150 offset:2048
	ds_read_b128 v[174:177], v150 offset:3072
	ds_read_b128 v[178:181], v151
	ds_read_b128 v[182:185], v151 offset:1024
	ds_read_b128 v[186:189], v151 offset:2048
	ds_read_b128 v[190:193], v151 offset:3072
	s_add_u32 s18, s16, 0xfff7c080
	s_addc_u32 s19, s17, -1
	s_cmp_eq_u32 s53, 28
	s_cselect_b32 s21, s3, s19
	s_cselect_b32 s20, s2, s18
	s_cselect_b32 s19, s15, s52
	s_cselect_b32 s18, s14, s51
	v_lshl_add_u64 v[144:145], s[16:17], 0, v[136:137]
	s_add_i32 m0, s36, 0xc000
	ds_read_b128 v[194:197], v152
	ds_read_b128 v[198:201], v152 offset:1024
	ds_read_b128 v[202:205], v152 offset:2048
	ds_read_b128 v[206:209], v152 offset:3072
	ds_read_b128 v[210:213], v152 offset:4096
	ds_read_b128 v[214:217], v152 offset:5120
	ds_read_b128 v[218:221], v152 offset:6144
	ds_read_b128 v[222:225], v152 offset:7168
	global_load_lds_dwordx4 v[144:145], off
	v_lshl_add_u64 v[144:145], s[16:17], 0, v[138:139]
	s_add_i32 m0, s36, 0xe000
	s_nop 0
	global_load_lds_dwordx4 v[144:145], off
	s_waitcnt vmcnt(8)
	s_waitcnt lgkmcnt(0)
	s_barrier
	s_setprio 1
	v_mfma_f32_16x16x32_bf16 v[124:127], v[154:157], v[194:197], v[124:127]
	v_mfma_f32_16x16x32_bf16 v[124:127], v[158:161], v[198:201], v[124:127]
	v_mfma_f32_16x16x32_bf16 v[108:111], v[154:157], v[202:205], v[108:111]
	v_mfma_f32_16x16x32_bf16 v[108:111], v[158:161], v[206:209], v[108:111]
	v_mfma_f32_16x16x32_bf16 v[92:95], v[154:157], v[210:213], v[92:95]
	v_mfma_f32_16x16x32_bf16 v[92:95], v[158:161], v[214:217], v[92:95]
	v_mfma_f32_16x16x32_bf16 v[76:79], v[154:157], v[218:221], v[76:79]
	v_mfma_f32_16x16x32_bf16 v[76:79], v[158:161], v[222:225], v[76:79]
	v_mfma_f32_16x16x32_bf16 v[120:123], v[170:173], v[194:197], v[120:123]
	v_mfma_f32_16x16x32_bf16 v[120:123], v[174:177], v[198:201], v[120:123]
	v_mfma_f32_16x16x32_bf16 v[104:107], v[170:173], v[202:205], v[104:107]
	v_mfma_f32_16x16x32_bf16 v[104:107], v[174:177], v[206:209], v[104:107]
	v_mfma_f32_16x16x32_bf16 v[88:91], v[170:173], v[210:213], v[88:91]
	v_mfma_f32_16x16x32_bf16 v[88:91], v[174:177], v[214:217], v[88:91]
	v_mfma_f32_16x16x32_bf16 v[72:75], v[170:173], v[218:221], v[72:75]
	v_mfma_f32_16x16x32_bf16 v[72:75], v[174:177], v[222:225], v[72:75]
	s_setprio 0
	s_setprio 1
	v_mfma_f32_16x16x32_bf16 v[116:119], v[178:181], v[194:197], v[116:119]
	v_mfma_f32_16x16x32_bf16 v[116:119], v[182:185], v[198:201], v[116:119]
	v_mfma_f32_16x16x32_bf16 v[100:103], v[178:181], v[202:205], v[100:103]
	v_mfma_f32_16x16x32_bf16 v[100:103], v[182:185], v[206:209], v[100:103]
	v_mfma_f32_16x16x32_bf16 v[84:87], v[178:181], v[210:213], v[84:87]
	v_mfma_f32_16x16x32_bf16 v[84:87], v[182:185], v[214:217], v[84:87]
	v_mfma_f32_16x16x32_bf16 v[68:71], v[178:181], v[218:221], v[68:71]
	v_mfma_f32_16x16x32_bf16 v[68:71], v[182:185], v[222:225], v[68:71]
	v_mfma_f32_16x16x32_bf16 v[112:115], v[186:189], v[194:197], v[112:115]
	v_mfma_f32_16x16x32_bf16 v[112:115], v[190:193], v[198:201], v[112:115]
	v_mfma_f32_16x16x32_bf16 v[96:99], v[186:189], v[202:205], v[96:99]
	v_mfma_f32_16x16x32_bf16 v[96:99], v[190:193], v[206:209], v[96:99]
	v_mfma_f32_16x16x32_bf16 v[80:83], v[186:189], v[210:213], v[80:83]
	v_mfma_f32_16x16x32_bf16 v[80:83], v[190:193], v[214:217], v[80:83]
	v_mfma_f32_16x16x32_bf16 v[64:67], v[186:189], v[218:221], v[64:67]
	v_mfma_f32_16x16x32_bf16 v[64:67], v[190:193], v[222:225], v[64:67]
	s_setprio 0
	s_barrier
	s_add_i32 s54, s44, s27
	v_lshl_add_u64 v[144:145], s[18:19], 0, v[132:133]
	s_mov_b32 m0, s54
	ds_read_b128 v[194:197], v152 offset:16384
	ds_read_b128 v[198:201], v152 offset:17408
	ds_read_b128 v[202:205], v152 offset:18432
	ds_read_b128 v[206:209], v152 offset:19456
	ds_read_b128 v[210:213], v152 offset:20480
	ds_read_b128 v[214:217], v152 offset:21504
	ds_read_b128 v[218:221], v152 offset:22528
	ds_read_b128 v[222:225], v152 offset:23552
	global_load_lds_dwordx4 v[144:145], off
	s_add_i32 m0, s54, 0x2000
	s_add_u32 s54, s18, 0x84000
	v_lshl_add_u64 v[162:163], s[18:19], 0, v[128:129]
	s_addc_u32 s55, s19, 0
	s_add_i32 s56, s45, s27
	global_load_lds_dwordx4 v[162:163], off
	v_lshl_add_u64 v[166:167], s[54:55], 0, v[132:133]
	s_mov_b32 m0, s56
	v_lshl_add_u64 v[226:227], s[20:21], 0, v[130:131]
	global_load_lds_dwordx4 v[166:167], off
	v_lshl_add_u64 v[166:167], s[54:55], 0, v[128:129]
	s_add_i32 m0, s56, 0x2000
	s_nop 0
	global_load_lds_dwordx4 v[166:167], off
	v_lshl_add_u64 v[166:167], s[20:21], 0, v[134:135]
	s_mov_b32 m0, s36
	s_nop 0
	global_load_lds_dwordx4 v[166:167], off
	s_mov_b32 m0, s37
	s_nop 0
	global_load_lds_dwordx4 v[226:227], off
	s_waitcnt vmcnt(8)
	s_waitcnt lgkmcnt(0)
	s_barrier
; #define PG8_STAGE(bufoff, gbase, voff) do { _Pragma("unroll") for (int _i = 0; _i < 2; ++_i) \
;         __builtin_amdgcn_global_load_lds((const unsigned*)((const char*)(gbase) + (voff)[_i]), (LAS unsigned*)(lds + (bufoff) + ldsw + _i * 8192), 16, 0, 0); } while (0)
; #define PG8_LDA(dst, b, h) do { _Pragma("unroll") for (int m = 0; m < 4; ++m) _Pragma("unroll") for (int k = 0; k < 2; ++k) dst[m][k] = *(const LAS bf16x8*)(lds + PG8_SA(b, h) + aoff + m * 2048 + k * 1024); } while (0)
; #define PG8_LDB(dst, b, h) do { _Pragma("unroll") for (int n = 0; n < 2; ++n) _Pragma("unroll") for (int k = 0; k < 2; ++k) dst[n][k] = *(const LAS bf16x8*)(lds + PG8_SB(b, h) + boff + n * 2048 + k * 1024); } while (0)
; #define PG8_MMA(ai, bj, At, Bt) do { __builtin_amdgcn_s_setprio(1); _Pragma("unroll") for (int m = 0; m < 4; ++m) _Pragma("unroll") for (int n = 0; n < 2; ++n) _Pragma("unroll") for (int k = 0; k < 2; ++k) \
;         acc[ai][bj][m][n] = __builtin_amdgcn_mfma_f32_16x16x32_bf16(Bt[n][k], At[m][k], acc[ai][bj][m][n], 0, 0, 0); __builtin_amdgcn_s_setprio(0); } while (0)
; #define PG8_WAIT_V(n) asm volatile("s_waitcnt vmcnt(" #n ")" ::: "memory")
; #define PG8_WAIT_L(n) asm volatile("s_waitcnt lgkmcnt(" #n ")" ::: "memory")
; #define PG8_BAR __builtin_amdgcn_s_barrier()
; #define PG8_SCHED __builtin_amdgcn_sched_barrier(0)
; template <class EpiT>
; __device__ __forceinline__ void gemm_phase(LAS unsigned char* lds, const Gemm g, const StaticOrder& S, const EpiT& E) {
;     ...
;             PG8_WAIT_V(8); PG8_WAIT_L(0); PG8_BAR; PG8_MMA(1, 0, At, B0); PG8_MMA(1, 1, At, B1); PG8_BAR; PG8_SCHED;
;             PG8_LDB(B0, 1, 0); PG8_LDB(B1, 1, 1); PG8_SCHED; PG8_LDA(At, 1, 0); PG8_STAGE(PG8_SA(0, 1), a2 + hstepA, voffA);
;             PG8_WAIT_V(8); PG8_WAIT_L(0); PG8_BAR; PG8_MMA(0, 0, At, B0); PG8_MMA(0, 1, At, B1); PG8_BAR; PG8_SCHED;
	s_setprio 1
	v_mfma_f32_16x16x32_bf16 v[60:63], v[154:157], v[194:197], v[60:63]
	v_mfma_f32_16x16x32_bf16 v[60:63], v[158:161], v[198:201], v[60:63]
	v_mfma_f32_16x16x32_bf16 v[44:47], v[154:157], v[202:205], v[44:47]
	v_mfma_f32_16x16x32_bf16 v[44:47], v[158:161], v[206:209], v[44:47]
	v_mfma_f32_16x16x32_bf16 v[28:31], v[154:157], v[210:213], v[28:31]
	v_mfma_f32_16x16x32_bf16 v[28:31], v[158:161], v[214:217], v[28:31]
	v_mfma_f32_16x16x32_bf16 v[12:15], v[154:157], v[218:221], v[12:15]
	v_mfma_f32_16x16x32_bf16 v[12:15], v[158:161], v[222:225], v[12:15]
	v_mfma_f32_16x16x32_bf16 v[56:59], v[170:173], v[194:197], v[56:59]
	v_mfma_f32_16x16x32_bf16 v[56:59], v[174:177], v[198:201], v[56:59]
	v_mfma_f32_16x16x32_bf16 v[40:43], v[170:173], v[202:205], v[40:43]
	v_mfma_f32_16x16x32_bf16 v[40:43], v[174:177], v[206:209], v[40:43]
	v_mfma_f32_16x16x32_bf16 v[24:27], v[170:173], v[210:213], v[24:27]
	v_mfma_f32_16x16x32_bf16 v[24:27], v[174:177], v[214:217], v[24:27]
	v_mfma_f32_16x16x32_bf16 v[8:11], v[170:173], v[218:221], v[8:11]
	v_mfma_f32_16x16x32_bf16 v[8:11], v[174:177], v[222:225], v[8:11]
	s_setprio 0
	s_setprio 1
	v_mfma_f32_16x16x32_bf16 v[52:55], v[178:181], v[194:197], v[52:55]
	v_mfma_f32_16x16x32_bf16 v[52:55], v[182:185], v[198:201], v[52:55]
	v_mfma_f32_16x16x32_bf16 v[36:39], v[178:181], v[202:205], v[36:39]
	v_mfma_f32_16x16x32_bf16 v[36:39], v[182:185], v[206:209], v[36:39]
	v_mfma_f32_16x16x32_bf16 v[20:23], v[178:181], v[210:213], v[20:23]
	v_mfma_f32_16x16x32_bf16 v[20:23], v[182:185], v[214:217], v[20:23]
	v_mfma_f32_16x16x32_bf16 v[4:7], v[178:181], v[218:221], v[4:7]
	v_mfma_f32_16x16x32_bf16 v[4:7], v[182:185], v[222:225], v[4:7]
	v_mfma_f32_16x16x32_bf16 v[48:51], v[186:189], v[194:197], v[48:51]
	v_mfma_f32_16x16x32_bf16 v[48:51], v[190:193], v[198:201], v[48:51]
	v_mfma_f32_16x16x32_bf16 v[32:35], v[186:189], v[202:205], v[32:35]
	v_mfma_f32_16x16x32_bf16 v[32:35], v[190:193], v[206:209], v[32:35]
	v_mfma_f32_16x16x32_bf16 v[16:19], v[186:189], v[210:213], v[16:19]
	v_mfma_f32_16x16x32_bf16 v[16:19], v[190:193], v[214:217], v[16:19]
	v_mfma_f32_16x16x32_bf16 v[0:3], v[186:189], v[218:221], v[0:3]
	v_mfma_f32_16x16x32_bf16 v[0:3], v[190:193], v[222:225], v[0:3]
	s_setprio 0
	s_barrier
	s_add_i32 s54, 0, 0x18000
	v_add_u32_e32 v153, s54, v147
	s_add_i32 s55, 0, 0x1c000
	ds_read_b128 v[154:157], v153
	ds_read_b128 v[158:161], v153 offset:1024
	ds_read_b128 v[170:173], v153 offset:2048
	ds_read_b128 v[174:177], v153 offset:3072
	v_add_u32_e32 v153, s55, v147
	ds_read_b128 v[178:181], v153
	ds_read_b128 v[182:185], v153 offset:1024
	ds_read_b128 v[186:189], v153 offset:2048
	ds_read_b128 v[190:193], v153 offset:3072
	s_add_u32 s20, s20, 0x84000
	s_addc_u32 s21, s21, 0
	s_mov_b32 m0, s38
	v_lshl_add_u64 v[228:229], s[20:21], 0, v[134:135]
	ds_read_b128 v[194:197], v152 offset:32768
	ds_read_b128 v[198:201], v152 offset:33792
	ds_read_b128 v[202:205], v152 offset:34816
	ds_read_b128 v[206:209], v152 offset:35840
	ds_read_b128 v[210:213], v152 offset:36864
	ds_read_b128 v[214:217], v152 offset:37888
	ds_read_b128 v[218:221], v152 offset:38912
	ds_read_b128 v[222:225], v152 offset:39936
	global_load_lds_dwordx4 v[228:229], off
	v_lshl_add_u64 v[228:229], s[20:21], 0, v[130:131]
	s_mov_b32 m0, s39
	s_nop 0
	global_load_lds_dwordx4 v[228:229], off
	s_waitcnt vmcnt(8)
	s_waitcnt lgkmcnt(0)
	s_barrier
	s_setprio 1
	v_mfma_f32_16x16x32_bf16 v[124:127], v[154:157], v[194:197], v[124:127]
	v_mfma_f32_16x16x32_bf16 v[124:127], v[158:161], v[198:201], v[124:127]
	v_mfma_f32_16x16x32_bf16 v[108:111], v[154:157], v[202:205], v[108:111]
	v_mfma_f32_16x16x32_bf16 v[108:111], v[158:161], v[206:209], v[108:111]
	v_mfma_f32_16x16x32_bf16 v[92:95], v[154:157], v[210:213], v[92:95]
	v_mfma_f32_16x16x32_bf16 v[92:95], v[158:161], v[214:217], v[92:95]
	v_mfma_f32_16x16x32_bf16 v[76:79], v[154:157], v[218:221], v[76:79]
	v_mfma_f32_16x16x32_bf16 v[76:79], v[158:161], v[222:225], v[76:79]
	v_mfma_f32_16x16x32_bf16 v[120:123], v[170:173], v[194:197], v[120:123]
	v_mfma_f32_16x16x32_bf16 v[120:123], v[174:177], v[198:201], v[120:123]
	v_mfma_f32_16x16x32_bf16 v[104:107], v[170:173], v[202:205], v[104:107]
	v_mfma_f32_16x16x32_bf16 v[104:107], v[174:177], v[206:209], v[104:107]
	v_mfma_f32_16x16x32_bf16 v[88:91], v[170:173], v[210:213], v[88:91]
	v_mfma_f32_16x16x32_bf16 v[88:91], v[174:177], v[214:217], v[88:91]
	v_mfma_f32_16x16x32_bf16 v[72:75], v[170:173], v[218:221], v[72:75]
	v_mfma_f32_16x16x32_bf16 v[72:75], v[174:177], v[222:225], v[72:75]
	s_setprio 0
	s_setprio 1
	v_mfma_f32_16x16x32_bf16 v[116:119], v[178:181], v[194:197], v[116:119]
	v_mfma_f32_16x16x32_bf16 v[116:119], v[182:185], v[198:201], v[116:119]
	v_mfma_f32_16x16x32_bf16 v[100:103], v[178:181], v[202:205], v[100:103]
	v_mfma_f32_16x16x32_bf16 v[100:103], v[182:185], v[206:209], v[100:103]
	v_mfma_f32_16x16x32_bf16 v[84:87], v[178:181], v[210:213], v[84:87]
	v_mfma_f32_16x16x32_bf16 v[84:87], v[182:185], v[214:217], v[84:87]
	v_mfma_f32_16x16x32_bf16 v[68:71], v[178:181], v[218:221], v[68:71]
	v_mfma_f32_16x16x32_bf16 v[68:71], v[182:185], v[222:225], v[68:71]
	v_mfma_f32_16x16x32_bf16 v[112:115], v[186:189], v[194:197], v[112:115]
	v_mfma_f32_16x16x32_bf16 v[112:115], v[190:193], v[198:201], v[112:115]
	v_mfma_f32_16x16x32_bf16 v[96:99], v[186:189], v[202:205], v[96:99]
	v_mfma_f32_16x16x32_bf16 v[96:99], v[190:193], v[206:209], v[96:99]
	v_mfma_f32_16x16x32_bf16 v[80:83], v[186:189], v[210:213], v[80:83]
	v_mfma_f32_16x16x32_bf16 v[80:83], v[190:193], v[214:217], v[80:83]
	v_mfma_f32_16x16x32_bf16 v[64:67], v[186:189], v[218:221], v[64:67]
	v_mfma_f32_16x16x32_bf16 v[64:67], v[190:193], v[222:225], v[64:67]
	s_setprio 0
	s_barrier
; #define PG8_STAGE(bufoff, gbase, voff) do { _Pragma("unroll") for (int _i = 0; _i < 2; ++_i) \
;         __builtin_amdgcn_global_load_lds((const unsigned*)((const char*)(gbase) + (voff)[_i]), (LAS unsigned*)(lds + (bufoff) + ldsw + _i * 8192), 16, 0, 0); } while (0)
; #define PG8_LDA(dst, b, h) do { _Pragma("unroll") for (int m = 0; m < 4; ++m) _Pragma("unroll") for (int k = 0; k < 2; ++k) dst[m][k] = *(const LAS bf16x8*)(lds + PG8_SA(b, h) + aoff + m * 2048 + k * 1024); } while (0)
; #define PG8_MMA(ai, bj, At, Bt) do { __builtin_amdgcn_s_setprio(1); _Pragma("unroll") for (int m = 0; m < 4; ++m) _Pragma("unroll") for (int n = 0; n < 2; ++n) _Pragma("unroll") for (int k = 0; k < 2; ++k) \
;         acc[ai][bj][m][n] = __builtin_amdgcn_mfma_f32_16x16x32_bf16(Bt[n][k], At[m][k], acc[ai][bj][m][n], 0, 0, 0); __builtin_amdgcn_s_setprio(0); } while (0)
; #define PG8_WAIT_V(n) asm volatile("s_waitcnt vmcnt(" #n ")" ::: "memory")
; #define PG8_WAIT_L(n) asm volatile("s_waitcnt lgkmcnt(" #n ")" ::: "memory")
; #define PG8_BAR __builtin_amdgcn_s_barrier()
; #define PG8_SCHED __builtin_amdgcn_sched_barrier(0)
; template <class EpiT>
; __device__ __forceinline__ void gemm_phase(LAS unsigned char* lds, const Gemm g, const StaticOrder& S, const EpiT& E) {
;     ...
;             PG8_LDA(At, 1, 1); PG8_STAGE(PG8_SB(1, 0), b3, voffB); PG8_STAGE(PG8_SB(1, 1), b3 + hstepB, voffB); PG8_STAGE(PG8_SA(1, 0), a3, voffA);
;             PG8_WAIT_V(8); PG8_WAIT_L(0); PG8_BAR; PG8_MMA(1, 0, At, B0); PG8_MMA(1, 1, At, B1); PG8_BAR; PG8_SCHED;
;         }
;         if (wr == 0) PG8_BAR;
	s_add_i32 s20, s54, s27
	v_lshl_add_u64 v[144:145], v[144:145], 0, s[10:11]
	s_mov_b32 m0, s20
	ds_read_b128 v[194:197], v152 offset:49152
	ds_read_b128 v[198:201], v152 offset:50176
	ds_read_b128 v[202:205], v152 offset:51200
	ds_read_b128 v[206:209], v152 offset:52224
	ds_read_b128 v[210:213], v152 offset:53248
	ds_read_b128 v[214:217], v152 offset:54272
	ds_read_b128 v[218:221], v152 offset:55296
	ds_read_b128 v[222:225], v152 offset:56320
	global_load_lds_dwordx4 v[144:145], off
	s_add_i32 m0, s20, 0x2000
	s_add_u32 s18, s18, 0x84080
	v_lshl_add_u64 v[144:145], v[162:163], 0, s[10:11]
	s_addc_u32 s19, s19, 0
	s_add_i32 s20, s55, s27
	global_load_lds_dwordx4 v[144:145], off
	v_lshl_add_u64 v[144:145], s[18:19], 0, v[132:133]
	s_mov_b32 m0, s20
	s_nop 0
	global_load_lds_dwordx4 v[144:145], off
	v_lshl_add_u64 v[144:145], s[18:19], 0, v[128:129]
	s_add_i32 m0, s20, 0x2000
	s_nop 0
	global_load_lds_dwordx4 v[144:145], off
	v_lshl_add_u64 v[144:145], v[166:167], 0, s[10:11]
	s_mov_b32 m0, s41
	s_nop 0
	global_load_lds_dwordx4 v[144:145], off
	v_lshl_add_u64 v[144:145], v[226:227], 0, s[10:11]
	s_mov_b32 m0, s42
	s_nop 0
	global_load_lds_dwordx4 v[144:145], off
	s_waitcnt vmcnt(8)
	s_waitcnt lgkmcnt(0)
	s_barrier
	s_setprio 1
	v_mfma_f32_16x16x32_bf16 v[60:63], v[154:157], v[194:197], v[60:63]
	v_mfma_f32_16x16x32_bf16 v[60:63], v[158:161], v[198:201], v[60:63]
	v_mfma_f32_16x16x32_bf16 v[44:47], v[154:157], v[202:205], v[44:47]
	v_mfma_f32_16x16x32_bf16 v[44:47], v[158:161], v[206:209], v[44:47]
	v_mfma_f32_16x16x32_bf16 v[28:31], v[154:157], v[210:213], v[28:31]
	v_mfma_f32_16x16x32_bf16 v[28:31], v[158:161], v[214:217], v[28:31]
	v_mfma_f32_16x16x32_bf16 v[12:15], v[154:157], v[218:221], v[12:15]
	v_mfma_f32_16x16x32_bf16 v[12:15], v[158:161], v[222:225], v[12:15]
	v_mfma_f32_16x16x32_bf16 v[56:59], v[170:173], v[194:197], v[56:59]
	v_mfma_f32_16x16x32_bf16 v[56:59], v[174:177], v[198:201], v[56:59]
	v_mfma_f32_16x16x32_bf16 v[40:43], v[170:173], v[202:205], v[40:43]
	v_mfma_f32_16x16x32_bf16 v[40:43], v[174:177], v[206:209], v[40:43]
	v_mfma_f32_16x16x32_bf16 v[24:27], v[170:173], v[210:213], v[24:27]
	v_mfma_f32_16x16x32_bf16 v[24:27], v[174:177], v[214:217], v[24:27]
	v_mfma_f32_16x16x32_bf16 v[8:11], v[170:173], v[218:221], v[8:11]
	v_mfma_f32_16x16x32_bf16 v[8:11], v[174:177], v[222:225], v[8:11]
	s_setprio 0
	s_setprio 1
	v_mfma_f32_16x16x32_bf16 v[52:55], v[178:181], v[194:197], v[52:55]
	v_mfma_f32_16x16x32_bf16 v[52:55], v[182:185], v[198:201], v[52:55]
	v_mfma_f32_16x16x32_bf16 v[36:39], v[178:181], v[202:205], v[36:39]
	v_mfma_f32_16x16x32_bf16 v[36:39], v[182:185], v[206:209], v[36:39]
	v_mfma_f32_16x16x32_bf16 v[20:23], v[178:181], v[210:213], v[20:23]
	v_mfma_f32_16x16x32_bf16 v[20:23], v[182:185], v[214:217], v[20:23]
	v_mfma_f32_16x16x32_bf16 v[4:7], v[178:181], v[218:221], v[4:7]
	v_mfma_f32_16x16x32_bf16 v[4:7], v[182:185], v[222:225], v[4:7]
	v_mfma_f32_16x16x32_bf16 v[48:51], v[186:189], v[194:197], v[48:51]
	v_mfma_f32_16x16x32_bf16 v[48:51], v[190:193], v[198:201], v[48:51]
	v_mfma_f32_16x16x32_bf16 v[32:35], v[186:189], v[202:205], v[32:35]
	v_mfma_f32_16x16x32_bf16 v[32:35], v[190:193], v[206:209], v[32:35]
	v_mfma_f32_16x16x32_bf16 v[16:19], v[186:189], v[210:213], v[16:19]
	v_mfma_f32_16x16x32_bf16 v[16:19], v[190:193], v[214:217], v[16:19]
	v_mfma_f32_16x16x32_bf16 v[0:3], v[186:189], v[218:221], v[0:3]
	v_mfma_f32_16x16x32_bf16 v[0:3], v[190:193], v[222:225], v[0:3]
	s_setprio 0
	s_barrier
	s_add_i32 s53, s53, 2
	s_add_u32 s16, s16, 0x100
	s_addc_u32 s17, s17, 0
	s_add_u32 s51, s51, 0x100
	s_addc_u32 s52, s52, 0
	s_cmp_gt_u32 s53, 29
	s_cbranch_scc0 .LBB0_516
	s_and_b64 vcc, exec, s[12:13]
	s_cbranch_vccz .LBB0_519
	s_barrier

; #define PG8_STAGE(bufoff, gbase, voff) do { _Pragma("unroll") for (int _i = 0; _i < 2; ++_i) \
;         __builtin_amdgcn_global_load_lds((const unsigned*)((const char*)(gbase) + (voff)[_i]), (LAS unsigned*)(lds + (bufoff) + ldsw + _i * 8192), 16, 0, 0); } while (0)
; #define PG8_LDA(dst, b, h) do { _Pragma("unroll") for (int m = 0; m < 4; ++m) _Pragma("unroll") for (int k = 0; k < 2; ++k) dst[m][k] = *(const LAS bf16x8*)(lds + PG8_SA(b, h) + aoff + m * 2048 + k * 1024); } while (0)
; #define PG8_LDB(dst, b, h) do { _Pragma("unroll") for (int n = 0; n < 2; ++n) _Pragma("unroll") for (int k = 0; k < 2; ++k) dst[n][k] = *(const LAS bf16x8*)(lds + PG8_SB(b, h) + boff + n * 2048 + k * 1024); } while (0)
; #define PG8_MMA(ai, bj, At, Bt) do { __builtin_amdgcn_s_setprio(1); _Pragma("unroll") for (int m = 0; m < 4; ++m) _Pragma("unroll") for (int n = 0; n < 2; ++n) _Pragma("unroll") for (int k = 0; k < 2; ++k) \
;         acc[ai][bj][m][n] = __builtin_amdgcn_mfma_f32_16x16x32_bf16(Bt[n][k], At[m][k], acc[ai][bj][m][n], 0, 0, 0); __builtin_amdgcn_s_setprio(0); } while (0)
; #define PG8_WAIT_V(n) asm volatile("s_waitcnt vmcnt(" #n ")" ::: "memory")
; #define PG8_WAIT_L(n) asm volatile("s_waitcnt lgkmcnt(" #n ")" ::: "memory")
; #define PG8_BAR __builtin_amdgcn_s_barrier()
; template <class EpiT>
; __device__ __forceinline__ void gemm_phase(LAS unsigned char* lds, const Gemm g, const StaticOrder& S, const EpiT& E) {
;     ...
;         const char* nA = has_next ? (const char*)g.A + (size_t)nxt.pm * tstepA + (size_t)nxt.pn * g.a_koff * 2 : cA; const char* nB = has_next ? (const char*)g.Bt + (size_t)nxt.pn * tstepB : cB;
;         for (int t = 0; t < nt; t += 2) {
;             const bool last = (t == nt - 2);
;             const char* a1 = cA + (size_t)(t + 1) * kstep;
;             const char* a2 = last ? nA : cA + (size_t)(t + 2) * kstep; const char* b2 = last ? nB : cB + (size_t)(t + 2) * kstep;
;             const char* a3 = a2 + kstep; const char* b3 = b2 + kstep;
;             PG8_LDB(B0, 0, 0); PG8_LDB(B1, 0, 1); PG8_SCHED; PG8_LDA(At, 0, 0); PG8_STAGE(PG8_SA(1, 1), a1 + hstepA, voffA);
;             PG8_WAIT_V(8); PG8_WAIT_L(0); PG8_BAR; PG8_MMA(0, 0, At, B0); PG8_MMA(0, 1, At, B1); PG8_BAR; PG8_SCHED;
;             PG8_LDA(At, 0, 1); PG8_STAGE(PG8_SB(0, 0), b2, voffB); PG8_STAGE(PG8_SB(0, 1), b2 + hstepB, voffB); PG8_STAGE(PG8_SA(0, 0), a2, voffA);
.LBB0_595:
	ds_read_b128 v[154:157], v150
	ds_read_b128 v[158:161], v150 offset:1024
	ds_read_b128 v[170:173], v150 offset:2048
	ds_read_b128 v[174:177], v150 offset:3072
	ds_read_b128 v[178:181], v151
	ds_read_b128 v[182:185], v151 offset:1024
	ds_read_b128 v[186:189], v151 offset:2048
	ds_read_b128 v[190:193], v151 offset:3072
	s_add_u32 s20, s18, 0xffe9c080
	s_addc_u32 s21, s19, -1
	s_cmpk_eq_i32 s55, 0x54
	s_cselect_b32 s23, s5, s21
	s_cselect_b32 s22, s4, s20
	s_cselect_b32 s21, s17, s54
	s_cselect_b32 s20, s16, s53
	v_lshl_add_u64 v[162:163], s[18:19], 0, v[138:139]
	s_add_i32 m0, s37, 0xc000
	ds_read_b128 v[194:197], v152
	ds_read_b128 v[198:201], v152 offset:1024
	ds_read_b128 v[202:205], v152 offset:2048
	ds_read_b128 v[206:209], v152 offset:3072
	ds_read_b128 v[210:213], v152 offset:4096
	ds_read_b128 v[214:217], v152 offset:5120
	ds_read_b128 v[218:221], v152 offset:6144
	ds_read_b128 v[222:225], v152 offset:7168
	global_load_lds_dwordx4 v[162:163], off
	v_lshl_add_u64 v[162:163], s[18:19], 0, v[140:141]
	s_add_i32 m0, s37, 0xe000
	s_nop 0
	global_load_lds_dwordx4 v[162:163], off
	s_waitcnt vmcnt(8)
	s_waitcnt lgkmcnt(0)
	s_barrier
	s_setprio 1
	v_mfma_f32_16x16x32_bf16 v[124:127], v[154:157], v[194:197], v[124:127]
	v_mfma_f32_16x16x32_bf16 v[124:127], v[158:161], v[198:201], v[124:127]
	v_mfma_f32_16x16x32_bf16 v[108:111], v[154:157], v[202:205], v[108:111]
	v_mfma_f32_16x16x32_bf16 v[108:111], v[158:161], v[206:209], v[108:111]
	v_mfma_f32_16x16x32_bf16 v[92:95], v[154:157], v[210:213], v[92:95]
	v_mfma_f32_16x16x32_bf16 v[92:95], v[158:161], v[214:217], v[92:95]
	v_mfma_f32_16x16x32_bf16 v[76:79], v[154:157], v[218:221], v[76:79]
	v_mfma_f32_16x16x32_bf16 v[76:79], v[158:161], v[222:225], v[76:79]
	v_mfma_f32_16x16x32_bf16 v[120:123], v[170:173], v[194:197], v[120:123]
	v_mfma_f32_16x16x32_bf16 v[120:123], v[174:177], v[198:201], v[120:123]
	v_mfma_f32_16x16x32_bf16 v[104:107], v[170:173], v[202:205], v[104:107]
	v_mfma_f32_16x16x32_bf16 v[104:107], v[174:177], v[206:209], v[104:107]
	v_mfma_f32_16x16x32_bf16 v[88:91], v[170:173], v[210:213], v[88:91]
	v_mfma_f32_16x16x32_bf16 v[88:91], v[174:177], v[214:217], v[88:91]
	v_mfma_f32_16x16x32_bf16 v[72:75], v[170:173], v[218:221], v[72:75]
	v_mfma_f32_16x16x32_bf16 v[72:75], v[174:177], v[222:225], v[72:75]
	s_setprio 0
	s_setprio 1
	v_mfma_f32_16x16x32_bf16 v[116:119], v[178:181], v[194:197], v[116:119]
	v_mfma_f32_16x16x32_bf16 v[116:119], v[182:185], v[198:201], v[116:119]
	v_mfma_f32_16x16x32_bf16 v[100:103], v[178:181], v[202:205], v[100:103]
	v_mfma_f32_16x16x32_bf16 v[100:103], v[182:185], v[206:209], v[100:103]
	v_mfma_f32_16x16x32_bf16 v[84:87], v[178:181], v[210:213], v[84:87]
	v_mfma_f32_16x16x32_bf16 v[84:87], v[182:185], v[214:217], v[84:87]
	v_mfma_f32_16x16x32_bf16 v[68:71], v[178:181], v[218:221], v[68:71]
	v_mfma_f32_16x16x32_bf16 v[68:71], v[182:185], v[222:225], v[68:71]
	v_mfma_f32_16x16x32_bf16 v[112:115], v[186:189], v[194:197], v[112:115]
	v_mfma_f32_16x16x32_bf16 v[112:115], v[190:193], v[198:201], v[112:115]
	v_mfma_f32_16x16x32_bf16 v[96:99], v[186:189], v[202:205], v[96:99]
	v_mfma_f32_16x16x32_bf16 v[96:99], v[190:193], v[206:209], v[96:99]
	v_mfma_f32_16x16x32_bf16 v[80:83], v[186:189], v[210:213], v[80:83]
	v_mfma_f32_16x16x32_bf16 v[80:83], v[190:193], v[214:217], v[80:83]
	v_mfma_f32_16x16x32_bf16 v[64:67], v[186:189], v[218:221], v[64:67]
	v_mfma_f32_16x16x32_bf16 v[64:67], v[190:193], v[222:225], v[64:67]
	s_setprio 0
	s_barrier
	s_add_i32 s56, s46, s36
	v_lshl_add_u64 v[162:163], s[20:21], 0, v[130:131]
	s_mov_b32 m0, s56
	ds_read_b128 v[194:197], v152 offset:16384
	ds_read_b128 v[198:201], v152 offset:17408
	ds_read_b128 v[202:205], v152 offset:18432
	ds_read_b128 v[206:209], v152 offset:19456
	ds_read_b128 v[210:213], v152 offset:20480
	ds_read_b128 v[214:217], v152 offset:21504
	ds_read_b128 v[218:221], v152 offset:22528
	ds_read_b128 v[222:225], v152 offset:23552
	global_load_lds_dwordx4 v[162:163], off
	s_add_i32 m0, s56, 0x2000
	s_add_u32 s56, s20, 0x164000
	v_lshl_add_u64 v[166:167], s[20:21], 0, v[134:135]
	s_addc_u32 s57, s21, 0
	s_add_i32 s58, s47, s36
	global_load_lds_dwordx4 v[166:167], off
	v_lshl_add_u64 v[226:227], s[56:57], 0, v[130:131]
	s_mov_b32 m0, s58
	v_lshl_add_u64 v[228:229], s[22:23], 0, v[132:133]
	global_load_lds_dwordx4 v[226:227], off
	v_lshl_add_u64 v[226:227], s[56:57], 0, v[134:135]
	s_add_i32 m0, s58, 0x2000
	s_nop 0
	global_load_lds_dwordx4 v[226:227], off
	v_lshl_add_u64 v[226:227], s[22:23], 0, v[128:129]
	s_mov_b32 m0, s37
	s_nop 0
	global_load_lds_dwordx4 v[226:227], off
	s_mov_b32 m0, s38
	s_nop 0
	global_load_lds_dwordx4 v[228:229], off
	s_waitcnt vmcnt(8)
	s_waitcnt lgkmcnt(0)
	s_barrier
; #define PG8_STAGE(bufoff, gbase, voff) do { _Pragma("unroll") for (int _i = 0; _i < 2; ++_i) \
;         __builtin_amdgcn_global_load_lds((const unsigned*)((const char*)(gbase) + (voff)[_i]), (LAS unsigned*)(lds + (bufoff) + ldsw + _i * 8192), 16, 0, 0); } while (0)
; #define PG8_LDA(dst, b, h) do { _Pragma("unroll") for (int m = 0; m < 4; ++m) _Pragma("unroll") for (int k = 0; k < 2; ++k) dst[m][k] = *(const LAS bf16x8*)(lds + PG8_SA(b, h) + aoff + m * 2048 + k * 1024); } while (0)
; #define PG8_LDB(dst, b, h) do { _Pragma("unroll") for (int n = 0; n < 2; ++n) _Pragma("unroll") for (int k = 0; k < 2; ++k) dst[n][k] = *(const LAS bf16x8*)(lds + PG8_SB(b, h) + boff + n * 2048 + k * 1024); } while (0)
; #define PG8_MMA(ai, bj, At, Bt) do { __builtin_amdgcn_s_setprio(1); _Pragma("unroll") for (int m = 0; m < 4; ++m) _Pragma("unroll") for (int n = 0; n < 2; ++n) _Pragma("unroll") for (int k = 0; k < 2; ++k) \
;         acc[ai][bj][m][n] = __builtin_amdgcn_mfma_f32_16x16x32_bf16(Bt[n][k], At[m][k], acc[ai][bj][m][n], 0, 0, 0); __builtin_amdgcn_s_setprio(0); } while (0)
; #define PG8_WAIT_V(n) asm volatile("s_waitcnt vmcnt(" #n ")" ::: "memory")
; #define PG8_WAIT_L(n) asm volatile("s_waitcnt lgkmcnt(" #n ")" ::: "memory")
; #define PG8_BAR __builtin_amdgcn_s_barrier()
; #define PG8_SCHED __builtin_amdgcn_sched_barrier(0)
; template <class EpiT>
; __device__ __forceinline__ void gemm_phase(LAS unsigned char* lds, const Gemm g, const StaticOrder& S, const EpiT& E) {
;     ...
;             PG8_WAIT_V(8); PG8_WAIT_L(0); PG8_BAR; PG8_MMA(1, 0, At, B0); PG8_MMA(1, 1, At, B1); PG8_BAR; PG8_SCHED;
;             PG8_LDB(B0, 1, 0); PG8_LDB(B1, 1, 1); PG8_SCHED; PG8_LDA(At, 1, 0); PG8_STAGE(PG8_SA(0, 1), a2 + hstepA, voffA);
;             PG8_WAIT_V(8); PG8_WAIT_L(0); PG8_BAR; PG8_MMA(0, 0, At, B0); PG8_MMA(0, 1, At, B1); PG8_BAR; PG8_SCHED;
	s_setprio 1
	v_mfma_f32_16x16x32_bf16 v[60:63], v[154:157], v[194:197], v[60:63]
	v_mfma_f32_16x16x32_bf16 v[60:63], v[158:161], v[198:201], v[60:63]
	v_mfma_f32_16x16x32_bf16 v[44:47], v[154:157], v[202:205], v[44:47]
	v_mfma_f32_16x16x32_bf16 v[44:47], v[158:161], v[206:209], v[44:47]
	v_mfma_f32_16x16x32_bf16 v[28:31], v[154:157], v[210:213], v[28:31]
	v_mfma_f32_16x16x32_bf16 v[28:31], v[158:161], v[214:217], v[28:31]
	v_mfma_f32_16x16x32_bf16 v[12:15], v[154:157], v[218:221], v[12:15]
	v_mfma_f32_16x16x32_bf16 v[12:15], v[158:161], v[222:225], v[12:15]
	v_mfma_f32_16x16x32_bf16 v[56:59], v[170:173], v[194:197], v[56:59]
	v_mfma_f32_16x16x32_bf16 v[56:59], v[174:177], v[198:201], v[56:59]
	v_mfma_f32_16x16x32_bf16 v[40:43], v[170:173], v[202:205], v[40:43]
	v_mfma_f32_16x16x32_bf16 v[40:43], v[174:177], v[206:209], v[40:43]
	v_mfma_f32_16x16x32_bf16 v[24:27], v[170:173], v[210:213], v[24:27]
	v_mfma_f32_16x16x32_bf16 v[24:27], v[174:177], v[214:217], v[24:27]
	v_mfma_f32_16x16x32_bf16 v[8:11], v[170:173], v[218:221], v[8:11]
	v_mfma_f32_16x16x32_bf16 v[8:11], v[174:177], v[222:225], v[8:11]
	s_setprio 0
	s_setprio 1
	v_mfma_f32_16x16x32_bf16 v[52:55], v[178:181], v[194:197], v[52:55]
	v_mfma_f32_16x16x32_bf16 v[52:55], v[182:185], v[198:201], v[52:55]
	v_mfma_f32_16x16x32_bf16 v[36:39], v[178:181], v[202:205], v[36:39]
	v_mfma_f32_16x16x32_bf16 v[36:39], v[182:185], v[206:209], v[36:39]
	v_mfma_f32_16x16x32_bf16 v[20:23], v[178:181], v[210:213], v[20:23]
	v_mfma_f32_16x16x32_bf16 v[20:23], v[182:185], v[214:217], v[20:23]
	v_mfma_f32_16x16x32_bf16 v[4:7], v[178:181], v[218:221], v[4:7]
	v_mfma_f32_16x16x32_bf16 v[4:7], v[182:185], v[222:225], v[4:7]
	v_mfma_f32_16x16x32_bf16 v[48:51], v[186:189], v[194:197], v[48:51]
	v_mfma_f32_16x16x32_bf16 v[48:51], v[190:193], v[198:201], v[48:51]
	v_mfma_f32_16x16x32_bf16 v[32:35], v[186:189], v[202:205], v[32:35]
	v_mfma_f32_16x16x32_bf16 v[32:35], v[190:193], v[206:209], v[32:35]
	v_mfma_f32_16x16x32_bf16 v[16:19], v[186:189], v[210:213], v[16:19]
	v_mfma_f32_16x16x32_bf16 v[16:19], v[190:193], v[214:217], v[16:19]
	v_mfma_f32_16x16x32_bf16 v[0:3], v[186:189], v[218:221], v[0:3]
	v_mfma_f32_16x16x32_bf16 v[0:3], v[190:193], v[222:225], v[0:3]
	s_setprio 0
	s_barrier
	s_add_i32 s56, 0, 0x18000
	v_add_u32_e32 v165, s56, v146
	s_add_i32 s57, 0, 0x1c000
	ds_read_b128 v[154:157], v165
	ds_read_b128 v[158:161], v165 offset:1024
	ds_read_b128 v[170:173], v165 offset:2048
	ds_read_b128 v[174:177], v165 offset:3072
	v_add_u32_e32 v165, s57, v146
	ds_read_b128 v[178:181], v165
	ds_read_b128 v[182:185], v165 offset:1024
	ds_read_b128 v[186:189], v165 offset:2048
	ds_read_b128 v[190:193], v165 offset:3072
	s_add_u32 s22, s22, 0x164000
	s_addc_u32 s23, s23, 0
	s_mov_b32 m0, s39
	v_lshl_add_u64 v[230:231], s[22:23], 0, v[128:129]
	ds_read_b128 v[194:197], v152 offset:32768
	ds_read_b128 v[198:201], v152 offset:33792
	ds_read_b128 v[202:205], v152 offset:34816
	ds_read_b128 v[206:209], v152 offset:35840
	ds_read_b128 v[210:213], v152 offset:36864
	ds_read_b128 v[214:217], v152 offset:37888
	ds_read_b128 v[218:221], v152 offset:38912
	ds_read_b128 v[222:225], v152 offset:39936
	global_load_lds_dwordx4 v[230:231], off
	v_lshl_add_u64 v[230:231], s[22:23], 0, v[132:133]
	s_mov_b32 m0, s40
	s_nop 0
	global_load_lds_dwordx4 v[230:231], off
	s_waitcnt vmcnt(8)
	s_waitcnt lgkmcnt(0)
	s_barrier
	s_setprio 1
	v_mfma_f32_16x16x32_bf16 v[124:127], v[154:157], v[194:197], v[124:127]
	v_mfma_f32_16x16x32_bf16 v[124:127], v[158:161], v[198:201], v[124:127]
	v_mfma_f32_16x16x32_bf16 v[108:111], v[154:157], v[202:205], v[108:111]
	v_mfma_f32_16x16x32_bf16 v[108:111], v[158:161], v[206:209], v[108:111]
	v_mfma_f32_16x16x32_bf16 v[92:95], v[154:157], v[210:213], v[92:95]
	v_mfma_f32_16x16x32_bf16 v[92:95], v[158:161], v[214:217], v[92:95]
	v_mfma_f32_16x16x32_bf16 v[76:79], v[154:157], v[218:221], v[76:79]
	v_mfma_f32_16x16x32_bf16 v[76:79], v[158:161], v[222:225], v[76:79]
	v_mfma_f32_16x16x32_bf16 v[120:123], v[170:173], v[194:197], v[120:123]
	v_mfma_f32_16x16x32_bf16 v[120:123], v[174:177], v[198:201], v[120:123]
	v_mfma_f32_16x16x32_bf16 v[104:107], v[170:173], v[202:205], v[104:107]
	v_mfma_f32_16x16x32_bf16 v[104:107], v[174:177], v[206:209], v[104:107]
	v_mfma_f32_16x16x32_bf16 v[88:91], v[170:173], v[210:213], v[88:91]
	v_mfma_f32_16x16x32_bf16 v[88:91], v[174:177], v[214:217], v[88:91]
	v_mfma_f32_16x16x32_bf16 v[72:75], v[170:173], v[218:221], v[72:75]
	v_mfma_f32_16x16x32_bf16 v[72:75], v[174:177], v[222:225], v[72:75]
	s_setprio 0
	s_setprio 1
	v_mfma_f32_16x16x32_bf16 v[116:119], v[178:181], v[194:197], v[116:119]
	v_mfma_f32_16x16x32_bf16 v[116:119], v[182:185], v[198:201], v[116:119]
	v_mfma_f32_16x16x32_bf16 v[100:103], v[178:181], v[202:205], v[100:103]
	v_mfma_f32_16x16x32_bf16 v[100:103], v[182:185], v[206:209], v[100:103]
	v_mfma_f32_16x16x32_bf16 v[84:87], v[178:181], v[210:213], v[84:87]
	v_mfma_f32_16x16x32_bf16 v[84:87], v[182:185], v[214:217], v[84:87]
	v_mfma_f32_16x16x32_bf16 v[68:71], v[178:181], v[218:221], v[68:71]
	v_mfma_f32_16x16x32_bf16 v[68:71], v[182:185], v[222:225], v[68:71]
	v_mfma_f32_16x16x32_bf16 v[112:115], v[186:189], v[194:197], v[112:115]
	v_mfma_f32_16x16x32_bf16 v[112:115], v[190:193], v[198:201], v[112:115]
	v_mfma_f32_16x16x32_bf16 v[96:99], v[186:189], v[202:205], v[96:99]
	v_mfma_f32_16x16x32_bf16 v[96:99], v[190:193], v[206:209], v[96:99]
	v_mfma_f32_16x16x32_bf16 v[80:83], v[186:189], v[210:213], v[80:83]
	v_mfma_f32_16x16x32_bf16 v[80:83], v[190:193], v[214:217], v[80:83]
	v_mfma_f32_16x16x32_bf16 v[64:67], v[186:189], v[218:221], v[64:67]
	v_mfma_f32_16x16x32_bf16 v[64:67], v[190:193], v[222:225], v[64:67]
	s_setprio 0
	s_barrier
; #define PG8_STAGE(bufoff, gbase, voff) do { _Pragma("unroll") for (int _i = 0; _i < 2; ++_i) \
;         __builtin_amdgcn_global_load_lds((const unsigned*)((const char*)(gbase) + (voff)[_i]), (LAS unsigned*)(lds + (bufoff) + ldsw + _i * 8192), 16, 0, 0); } while (0)
; #define PG8_LDA(dst, b, h) do { _Pragma("unroll") for (int m = 0; m < 4; ++m) _Pragma("unroll") for (int k = 0; k < 2; ++k) dst[m][k] = *(const LAS bf16x8*)(lds + PG8_SA(b, h) + aoff + m * 2048 + k * 1024); } while (0)
; #define PG8_MMA(ai, bj, At, Bt) do { __builtin_amdgcn_s_setprio(1); _Pragma("unroll") for (int m = 0; m < 4; ++m) _Pragma("unroll") for (int n = 0; n < 2; ++n) _Pragma("unroll") for (int k = 0; k < 2; ++k) \
;         acc[ai][bj][m][n] = __builtin_amdgcn_mfma_f32_16x16x32_bf16(Bt[n][k], At[m][k], acc[ai][bj][m][n], 0, 0, 0); __builtin_amdgcn_s_setprio(0); } while (0)
; #define PG8_WAIT_V(n) asm volatile("s_waitcnt vmcnt(" #n ")" ::: "memory")
; #define PG8_WAIT_L(n) asm volatile("s_waitcnt lgkmcnt(" #n ")" ::: "memory")
; #define PG8_BAR __builtin_amdgcn_s_barrier()
; #define PG8_SCHED __builtin_amdgcn_sched_barrier(0)
; template <class EpiT>
; __device__ __forceinline__ void gemm_phase(LAS unsigned char* lds, const Gemm g, const StaticOrder& S, const EpiT& E) {
;     ...
;             PG8_LDA(At, 1, 1); PG8_STAGE(PG8_SB(1, 0), b3, voffB); PG8_STAGE(PG8_SB(1, 1), b3 + hstepB, voffB); PG8_STAGE(PG8_SA(1, 0), a3, voffA);
;             PG8_WAIT_V(8); PG8_WAIT_L(0); PG8_BAR; PG8_MMA(1, 0, At, B0); PG8_MMA(1, 1, At, B1); PG8_BAR; PG8_SCHED;
;         }
;         if (wr == 0) PG8_BAR;
	s_add_i32 s22, s56, s36
	v_lshl_add_u64 v[162:163], v[162:163], 0, s[12:13]
	s_mov_b32 m0, s22
	ds_read_b128 v[194:197], v152 offset:49152
	ds_read_b128 v[198:201], v152 offset:50176
	ds_read_b128 v[202:205], v152 offset:51200
	ds_read_b128 v[206:209], v152 offset:52224
	ds_read_b128 v[210:213], v152 offset:53248
	ds_read_b128 v[214:217], v152 offset:54272
	ds_read_b128 v[218:221], v152 offset:55296
	ds_read_b128 v[222:225], v152 offset:56320
	global_load_lds_dwordx4 v[162:163], off
	s_add_i32 m0, s22, 0x2000
	s_add_u32 s20, s20, 0x164080
	v_lshl_add_u64 v[162:163], v[166:167], 0, s[12:13]
	s_addc_u32 s21, s21, 0
	s_add_i32 s22, s57, s36
	global_load_lds_dwordx4 v[162:163], off
	v_lshl_add_u64 v[162:163], s[20:21], 0, v[130:131]
	s_mov_b32 m0, s22
	s_nop 0
	global_load_lds_dwordx4 v[162:163], off
	v_lshl_add_u64 v[162:163], s[20:21], 0, v[134:135]
	s_add_i32 m0, s22, 0x2000
	s_nop 0
	global_load_lds_dwordx4 v[162:163], off
	v_lshl_add_u64 v[162:163], v[226:227], 0, s[12:13]
	s_mov_b32 m0, s42
	s_nop 0
	global_load_lds_dwordx4 v[162:163], off
	v_lshl_add_u64 v[162:163], v[228:229], 0, s[12:13]
	s_mov_b32 m0, s43
	s_nop 0
	global_load_lds_dwordx4 v[162:163], off
	s_waitcnt vmcnt(8)
	s_waitcnt lgkmcnt(0)
	s_barrier
	s_setprio 1
	v_mfma_f32_16x16x32_bf16 v[60:63], v[154:157], v[194:197], v[60:63]
	v_mfma_f32_16x16x32_bf16 v[60:63], v[158:161], v[198:201], v[60:63]
	v_mfma_f32_16x16x32_bf16 v[44:47], v[154:157], v[202:205], v[44:47]
	v_mfma_f32_16x16x32_bf16 v[44:47], v[158:161], v[206:209], v[44:47]
	v_mfma_f32_16x16x32_bf16 v[28:31], v[154:157], v[210:213], v[28:31]
	v_mfma_f32_16x16x32_bf16 v[28:31], v[158:161], v[214:217], v[28:31]
	v_mfma_f32_16x16x32_bf16 v[12:15], v[154:157], v[218:221], v[12:15]
	v_mfma_f32_16x16x32_bf16 v[12:15], v[158:161], v[222:225], v[12:15]
	v_mfma_f32_16x16x32_bf16 v[56:59], v[170:173], v[194:197], v[56:59]
	v_mfma_f32_16x16x32_bf16 v[56:59], v[174:177], v[198:201], v[56:59]
	v_mfma_f32_16x16x32_bf16 v[40:43], v[170:173], v[202:205], v[40:43]
	v_mfma_f32_16x16x32_bf16 v[40:43], v[174:177], v[206:209], v[40:43]
	v_mfma_f32_16x16x32_bf16 v[24:27], v[170:173], v[210:213], v[24:27]
	v_mfma_f32_16x16x32_bf16 v[24:27], v[174:177], v[214:217], v[24:27]
	v_mfma_f32_16x16x32_bf16 v[8:11], v[170:173], v[218:221], v[8:11]
	v_mfma_f32_16x16x32_bf16 v[8:11], v[174:177], v[222:225], v[8:11]
	s_setprio 0
	s_setprio 1
	v_mfma_f32_16x16x32_bf16 v[52:55], v[178:181], v[194:197], v[52:55]
	v_mfma_f32_16x16x32_bf16 v[52:55], v[182:185], v[198:201], v[52:55]
	v_mfma_f32_16x16x32_bf16 v[36:39], v[178:181], v[202:205], v[36:39]
	v_mfma_f32_16x16x32_bf16 v[36:39], v[182:185], v[206:209], v[36:39]
	v_mfma_f32_16x16x32_bf16 v[20:23], v[178:181], v[210:213], v[20:23]
	v_mfma_f32_16x16x32_bf16 v[20:23], v[182:185], v[214:217], v[20:23]
	v_mfma_f32_16x16x32_bf16 v[4:7], v[178:181], v[218:221], v[4:7]
	v_mfma_f32_16x16x32_bf16 v[4:7], v[182:185], v[222:225], v[4:7]
	v_mfma_f32_16x16x32_bf16 v[48:51], v[186:189], v[194:197], v[48:51]
	v_mfma_f32_16x16x32_bf16 v[48:51], v[190:193], v[198:201], v[48:51]
	v_mfma_f32_16x16x32_bf16 v[32:35], v[186:189], v[202:205], v[32:35]
	v_mfma_f32_16x16x32_bf16 v[32:35], v[190:193], v[206:209], v[32:35]
	v_mfma_f32_16x16x32_bf16 v[16:19], v[186:189], v[210:213], v[16:19]
	v_mfma_f32_16x16x32_bf16 v[16:19], v[190:193], v[214:217], v[16:19]
	v_mfma_f32_16x16x32_bf16 v[0:3], v[186:189], v[218:221], v[0:3]
	v_mfma_f32_16x16x32_bf16 v[0:3], v[190:193], v[222:225], v[0:3]
	s_setprio 0
	s_barrier
	s_add_i32 s55, s55, 2
	s_add_u32 s18, s18, 0x100
	s_addc_u32 s19, s19, 0
	s_add_u32 s53, s53, 0x100
	s_addc_u32 s54, s54, 0
	s_cmpk_gt_u32 s55, 0x55
	s_cbranch_scc0 .LBB0_595
	s_and_b64 vcc, exec, s[14:15]
	s_cbranch_vccz .LBB0_598
	s_barrier

; #define PG8_STAGE(bufoff, gbase, voff) do { _Pragma("unroll") for (int _i = 0; _i < 2; ++_i) \
;         __builtin_amdgcn_global_load_lds((const unsigned*)((const char*)(gbase) + (voff)[_i]), (LAS unsigned*)(lds + (bufoff) + ldsw + _i * 8192), 16, 0, 0); } while (0)
; #define PG8_LDA(dst, b, h) do { _Pragma("unroll") for (int m = 0; m < 4; ++m) _Pragma("unroll") for (int k = 0; k < 2; ++k) dst[m][k] = *(const LAS bf16x8*)(lds + PG8_SA(b, h) + aoff + m * 2048 + k * 1024); } while (0)
; #define PG8_LDB(dst, b, h) do { _Pragma("unroll") for (int n = 0; n < 2; ++n) _Pragma("unroll") for (int k = 0; k < 2; ++k) dst[n][k] = *(const LAS bf16x8*)(lds + PG8_SB(b, h) + boff + n * 2048 + k * 1024); } while (0)
; #define PG8_MMA(ai, bj, At, Bt) do { __builtin_amdgcn_s_setprio(1); _Pragma("unroll") for (int m = 0; m < 4; ++m) _Pragma("unroll") for (int n = 0; n < 2; ++n) _Pragma("unroll") for (int k = 0; k < 2; ++k) \
;         acc[ai][bj][m][n] = __builtin_amdgcn_mfma_f32_16x16x32_bf16(Bt[n][k], At[m][k], acc[ai][bj][m][n], 0, 0, 0); __builtin_amdgcn_s_setprio(0); } while (0)
; #define PG8_WAIT_V(n) asm volatile("s_waitcnt vmcnt(" #n ")" ::: "memory")
; #define PG8_WAIT_L(n) asm volatile("s_waitcnt lgkmcnt(" #n ")" ::: "memory")
; #define PG8_BAR __builtin_amdgcn_s_barrier()
; template <class EpiT>
; __device__ __forceinline__ void gemm_phase(LAS unsigned char* lds, const Gemm g, const StaticOrder& S, const EpiT& E) {
;     ...
;         const char* nA = has_next ? (const char*)g.A + (size_t)nxt.pm * tstepA + (size_t)nxt.pn * g.a_koff * 2 : cA; const char* nB = has_next ? (const char*)g.Bt + (size_t)nxt.pn * tstepB : cB;
;         for (int t = 0; t < nt; t += 2) {
;             const bool last = (t == nt - 2);
;             const char* a1 = cA + (size_t)(t + 1) * kstep;
;             const char* a2 = last ? nA : cA + (size_t)(t + 2) * kstep; const char* b2 = last ? nB : cB + (size_t)(t + 2) * kstep;
;             const char* a3 = a2 + kstep; const char* b3 = b2 + kstep;
;             PG8_LDB(B0, 0, 0); PG8_LDB(B1, 0, 1); PG8_SCHED; PG8_LDA(At, 0, 0); PG8_STAGE(PG8_SA(1, 1), a1 + hstepA, voffA);
;             PG8_WAIT_V(8); PG8_WAIT_L(0); PG8_BAR; PG8_MMA(0, 0, At, B0); PG8_MMA(0, 1, At, B1); PG8_BAR; PG8_SCHED;
;             PG8_LDA(At, 0, 1); PG8_STAGE(PG8_SB(0, 0), b2, voffB); PG8_STAGE(PG8_SB(0, 1), b2 + hstepB, voffB); PG8_STAGE(PG8_SA(0, 0), a2, voffA);
.LBB0_761:
	ds_read_b128 v[156:159], v160
	ds_read_b128 v[164:167], v160 offset:1024
	ds_read_b128 v[170:173], v160 offset:2048
	ds_read_b128 v[174:177], v160 offset:3072
	ds_read_b128 v[178:181], v161
	ds_read_b128 v[182:185], v161 offset:1024
	ds_read_b128 v[186:189], v161 offset:2048
	ds_read_b128 v[190:193], v161 offset:3072
	s_add_u32 s22, s20, 0xfff7c080
	s_addc_u32 s23, s21, -1
	s_cmp_eq_u32 s56, 28
	s_cselect_b32 s25, s5, s23
	s_cselect_b32 s24, s4, s22
	s_cselect_b32 s23, s19, s39
	s_cselect_b32 s22, s18, s8
	v_lshl_add_u64 v[226:227], s[20:21], 0, v[146:147]
	s_add_i32 m0, s40, 0xc000
	ds_read_b128 v[194:197], v162
	ds_read_b128 v[198:201], v162 offset:1024
	ds_read_b128 v[202:205], v162 offset:2048
	ds_read_b128 v[206:209], v162 offset:3072
	ds_read_b128 v[210:213], v162 offset:4096
	ds_read_b128 v[214:217], v162 offset:5120
	ds_read_b128 v[218:221], v162 offset:6144
	ds_read_b128 v[222:225], v162 offset:7168
	global_load_lds_dwordx4 v[226:227], off
	v_lshl_add_u64 v[226:227], s[20:21], 0, v[150:151]
	s_add_i32 m0, s40, 0xe000
	s_nop 0
	global_load_lds_dwordx4 v[226:227], off
	s_waitcnt vmcnt(8)
	s_waitcnt lgkmcnt(0)
	s_barrier
	s_setprio 1
	v_mfma_f32_16x16x32_bf16 v[124:127], v[156:159], v[194:197], v[124:127]
	v_mfma_f32_16x16x32_bf16 v[124:127], v[164:167], v[198:201], v[124:127]
	v_mfma_f32_16x16x32_bf16 v[108:111], v[156:159], v[202:205], v[108:111]
	v_mfma_f32_16x16x32_bf16 v[108:111], v[164:167], v[206:209], v[108:111]
	v_mfma_f32_16x16x32_bf16 v[92:95], v[156:159], v[210:213], v[92:95]
	v_mfma_f32_16x16x32_bf16 v[92:95], v[164:167], v[214:217], v[92:95]
	v_mfma_f32_16x16x32_bf16 v[76:79], v[156:159], v[218:221], v[76:79]
	v_mfma_f32_16x16x32_bf16 v[76:79], v[164:167], v[222:225], v[76:79]
	v_mfma_f32_16x16x32_bf16 v[120:123], v[170:173], v[194:197], v[120:123]
	v_mfma_f32_16x16x32_bf16 v[120:123], v[174:177], v[198:201], v[120:123]
	v_mfma_f32_16x16x32_bf16 v[104:107], v[170:173], v[202:205], v[104:107]
	v_mfma_f32_16x16x32_bf16 v[104:107], v[174:177], v[206:209], v[104:107]
	v_mfma_f32_16x16x32_bf16 v[88:91], v[170:173], v[210:213], v[88:91]
	v_mfma_f32_16x16x32_bf16 v[88:91], v[174:177], v[214:217], v[88:91]
	v_mfma_f32_16x16x32_bf16 v[72:75], v[170:173], v[218:221], v[72:75]
	v_mfma_f32_16x16x32_bf16 v[72:75], v[174:177], v[222:225], v[72:75]
	s_setprio 0
	s_setprio 1
	v_mfma_f32_16x16x32_bf16 v[116:119], v[178:181], v[194:197], v[116:119]
	v_mfma_f32_16x16x32_bf16 v[116:119], v[182:185], v[198:201], v[116:119]
	v_mfma_f32_16x16x32_bf16 v[100:103], v[178:181], v[202:205], v[100:103]
	v_mfma_f32_16x16x32_bf16 v[100:103], v[182:185], v[206:209], v[100:103]
	v_mfma_f32_16x16x32_bf16 v[84:87], v[178:181], v[210:213], v[84:87]
	v_mfma_f32_16x16x32_bf16 v[84:87], v[182:185], v[214:217], v[84:87]
	v_mfma_f32_16x16x32_bf16 v[68:71], v[178:181], v[218:221], v[68:71]
	v_mfma_f32_16x16x32_bf16 v[68:71], v[182:185], v[222:225], v[68:71]
	v_mfma_f32_16x16x32_bf16 v[112:115], v[186:189], v[194:197], v[112:115]
	v_mfma_f32_16x16x32_bf16 v[112:115], v[190:193], v[198:201], v[112:115]
	v_mfma_f32_16x16x32_bf16 v[96:99], v[186:189], v[202:205], v[96:99]
	v_mfma_f32_16x16x32_bf16 v[96:99], v[190:193], v[206:209], v[96:99]
	v_mfma_f32_16x16x32_bf16 v[80:83], v[186:189], v[210:213], v[80:83]
	v_mfma_f32_16x16x32_bf16 v[80:83], v[190:193], v[214:217], v[80:83]
	v_mfma_f32_16x16x32_bf16 v[64:67], v[186:189], v[218:221], v[64:67]
	v_mfma_f32_16x16x32_bf16 v[64:67], v[190:193], v[222:225], v[64:67]
	s_setprio 0
	s_barrier
	s_add_i32 s57, s49, s37
	v_lshl_add_u64 v[226:227], s[22:23], 0, v[130:131]
	s_mov_b32 m0, s57
	ds_read_b128 v[194:197], v162 offset:16384
	ds_read_b128 v[198:201], v162 offset:17408
	ds_read_b128 v[202:205], v162 offset:18432
	ds_read_b128 v[206:209], v162 offset:19456
	ds_read_b128 v[210:213], v162 offset:20480
	ds_read_b128 v[214:217], v162 offset:21504
	ds_read_b128 v[218:221], v162 offset:22528
	ds_read_b128 v[222:225], v162 offset:23552
	global_load_lds_dwordx4 v[226:227], off
	s_add_i32 m0, s57, 0x2000
	s_add_u32 s58, s22, 0x84000
	v_lshl_add_u64 v[228:229], s[22:23], 0, v[134:135]
	s_addc_u32 s59, s23, 0
	s_add_i32 s57, s50, s37
	global_load_lds_dwordx4 v[228:229], off
	v_lshl_add_u64 v[230:231], s[58:59], 0, v[130:131]
	s_mov_b32 m0, s57
	v_lshl_add_u64 v[232:233], s[24:25], 0, v[132:133]
	global_load_lds_dwordx4 v[230:231], off
	v_lshl_add_u64 v[230:231], s[58:59], 0, v[134:135]
	s_add_i32 m0, s57, 0x2000
	s_nop 0
	global_load_lds_dwordx4 v[230:231], off
	v_lshl_add_u64 v[230:231], s[24:25], 0, v[128:129]
	s_mov_b32 m0, s40
	s_nop 0
	global_load_lds_dwordx4 v[230:231], off
	s_mov_b32 m0, s41
	s_nop 0
	global_load_lds_dwordx4 v[232:233], off
	s_waitcnt vmcnt(8)
	s_waitcnt lgkmcnt(0)
	s_barrier
; #define PG8_STAGE(bufoff, gbase, voff) do { _Pragma("unroll") for (int _i = 0; _i < 2; ++_i) \
;         __builtin_amdgcn_global_load_lds((const unsigned*)((const char*)(gbase) + (voff)[_i]), (LAS unsigned*)(lds + (bufoff) + ldsw + _i * 8192), 16, 0, 0); } while (0)
; #define PG8_LDA(dst, b, h) do { _Pragma("unroll") for (int m = 0; m < 4; ++m) _Pragma("unroll") for (int k = 0; k < 2; ++k) dst[m][k] = *(const LAS bf16x8*)(lds + PG8_SA(b, h) + aoff + m * 2048 + k * 1024); } while (0)
; #define PG8_LDB(dst, b, h) do { _Pragma("unroll") for (int n = 0; n < 2; ++n) _Pragma("unroll") for (int k = 0; k < 2; ++k) dst[n][k] = *(const LAS bf16x8*)(lds + PG8_SB(b, h) + boff + n * 2048 + k * 1024); } while (0)
; #define PG8_MMA(ai, bj, At, Bt) do { __builtin_amdgcn_s_setprio(1); _Pragma("unroll") for (int m = 0; m < 4; ++m) _Pragma("unroll") for (int n = 0; n < 2; ++n) _Pragma("unroll") for (int k = 0; k < 2; ++k) \
;         acc[ai][bj][m][n] = __builtin_amdgcn_mfma_f32_16x16x32_bf16(Bt[n][k], At[m][k], acc[ai][bj][m][n], 0, 0, 0); __builtin_amdgcn_s_setprio(0); } while (0)
; #define PG8_WAIT_V(n) asm volatile("s_waitcnt vmcnt(" #n ")" ::: "memory")
; #define PG8_WAIT_L(n) asm volatile("s_waitcnt lgkmcnt(" #n ")" ::: "memory")
; #define PG8_BAR __builtin_amdgcn_s_barrier()
; #define PG8_SCHED __builtin_amdgcn_sched_barrier(0)
; template <class EpiT>
; __device__ __forceinline__ void gemm_phase(LAS unsigned char* lds, const Gemm g, const StaticOrder& S, const EpiT& E) {
;     ...
;             PG8_WAIT_V(8); PG8_WAIT_L(0); PG8_BAR; PG8_MMA(1, 0, At, B0); PG8_MMA(1, 1, At, B1); PG8_BAR; PG8_SCHED;
;             PG8_LDB(B0, 1, 0); PG8_LDB(B1, 1, 1); PG8_SCHED; PG8_LDA(At, 1, 0); PG8_STAGE(PG8_SA(0, 1), a2 + hstepA, voffA);
;             PG8_WAIT_V(8); PG8_WAIT_L(0); PG8_BAR; PG8_MMA(0, 0, At, B0); PG8_MMA(0, 1, At, B1); PG8_BAR; PG8_SCHED;
	s_setprio 1
	v_mfma_f32_16x16x32_bf16 v[60:63], v[156:159], v[194:197], v[60:63]
	v_mfma_f32_16x16x32_bf16 v[60:63], v[164:167], v[198:201], v[60:63]
	v_mfma_f32_16x16x32_bf16 v[44:47], v[156:159], v[202:205], v[44:47]
	v_mfma_f32_16x16x32_bf16 v[44:47], v[164:167], v[206:209], v[44:47]
	v_mfma_f32_16x16x32_bf16 v[28:31], v[156:159], v[210:213], v[28:31]
	v_mfma_f32_16x16x32_bf16 v[28:31], v[164:167], v[214:217], v[28:31]
	v_mfma_f32_16x16x32_bf16 v[12:15], v[156:159], v[218:221], v[12:15]
	v_mfma_f32_16x16x32_bf16 v[12:15], v[164:167], v[222:225], v[12:15]
	v_mfma_f32_16x16x32_bf16 v[56:59], v[170:173], v[194:197], v[56:59]
	v_mfma_f32_16x16x32_bf16 v[56:59], v[174:177], v[198:201], v[56:59]
	v_mfma_f32_16x16x32_bf16 v[40:43], v[170:173], v[202:205], v[40:43]
	v_mfma_f32_16x16x32_bf16 v[40:43], v[174:177], v[206:209], v[40:43]
	v_mfma_f32_16x16x32_bf16 v[24:27], v[170:173], v[210:213], v[24:27]
	v_mfma_f32_16x16x32_bf16 v[24:27], v[174:177], v[214:217], v[24:27]
	v_mfma_f32_16x16x32_bf16 v[8:11], v[170:173], v[218:221], v[8:11]
	v_mfma_f32_16x16x32_bf16 v[8:11], v[174:177], v[222:225], v[8:11]
	s_setprio 0
	s_setprio 1
	v_mfma_f32_16x16x32_bf16 v[52:55], v[178:181], v[194:197], v[52:55]
	v_mfma_f32_16x16x32_bf16 v[52:55], v[182:185], v[198:201], v[52:55]
	v_mfma_f32_16x16x32_bf16 v[36:39], v[178:181], v[202:205], v[36:39]
	v_mfma_f32_16x16x32_bf16 v[36:39], v[182:185], v[206:209], v[36:39]
	v_mfma_f32_16x16x32_bf16 v[20:23], v[178:181], v[210:213], v[20:23]
	v_mfma_f32_16x16x32_bf16 v[20:23], v[182:185], v[214:217], v[20:23]
	v_mfma_f32_16x16x32_bf16 v[4:7], v[178:181], v[218:221], v[4:7]
	v_mfma_f32_16x16x32_bf16 v[4:7], v[182:185], v[222:225], v[4:7]
	v_mfma_f32_16x16x32_bf16 v[48:51], v[186:189], v[194:197], v[48:51]
	v_mfma_f32_16x16x32_bf16 v[48:51], v[190:193], v[198:201], v[48:51]
	v_mfma_f32_16x16x32_bf16 v[32:35], v[186:189], v[202:205], v[32:35]
	v_mfma_f32_16x16x32_bf16 v[32:35], v[190:193], v[206:209], v[32:35]
	v_mfma_f32_16x16x32_bf16 v[16:19], v[186:189], v[210:213], v[16:19]
	v_mfma_f32_16x16x32_bf16 v[16:19], v[190:193], v[214:217], v[16:19]
	v_mfma_f32_16x16x32_bf16 v[0:3], v[186:189], v[218:221], v[0:3]
	v_mfma_f32_16x16x32_bf16 v[0:3], v[190:193], v[222:225], v[0:3]
	s_setprio 0
	s_barrier
	s_add_i32 s57, 0, 0x18000
	v_add_u32_e32 v136, s57, v149
	s_add_i32 s58, 0, 0x1c000
	ds_read_b128 v[156:159], v136
	ds_read_b128 v[164:167], v136 offset:1024
	ds_read_b128 v[170:173], v136 offset:2048
	ds_read_b128 v[174:177], v136 offset:3072
	v_add_u32_e32 v136, s58, v149
	ds_read_b128 v[178:181], v136
	ds_read_b128 v[182:185], v136 offset:1024
	ds_read_b128 v[186:189], v136 offset:2048
	ds_read_b128 v[190:193], v136 offset:3072
	s_add_u32 s24, s24, 0x84000
	s_addc_u32 s25, s25, 0
	s_mov_b32 m0, s42
	v_lshl_add_u64 v[234:235], s[24:25], 0, v[128:129]
	ds_read_b128 v[194:197], v162 offset:32768
	ds_read_b128 v[198:201], v162 offset:33792
	ds_read_b128 v[202:205], v162 offset:34816
	ds_read_b128 v[206:209], v162 offset:35840
	ds_read_b128 v[210:213], v162 offset:36864
	ds_read_b128 v[214:217], v162 offset:37888
	ds_read_b128 v[218:221], v162 offset:38912
	ds_read_b128 v[222:225], v162 offset:39936
	global_load_lds_dwordx4 v[234:235], off
	v_lshl_add_u64 v[234:235], s[24:25], 0, v[132:133]
	s_mov_b32 m0, s43
	s_nop 0
	global_load_lds_dwordx4 v[234:235], off
	s_waitcnt vmcnt(8)
	s_waitcnt lgkmcnt(0)
	s_barrier
	s_setprio 1
	v_mfma_f32_16x16x32_bf16 v[124:127], v[156:159], v[194:197], v[124:127]
	v_mfma_f32_16x16x32_bf16 v[124:127], v[164:167], v[198:201], v[124:127]
	v_mfma_f32_16x16x32_bf16 v[108:111], v[156:159], v[202:205], v[108:111]
	v_mfma_f32_16x16x32_bf16 v[108:111], v[164:167], v[206:209], v[108:111]
	v_mfma_f32_16x16x32_bf16 v[92:95], v[156:159], v[210:213], v[92:95]
	v_mfma_f32_16x16x32_bf16 v[92:95], v[164:167], v[214:217], v[92:95]
	v_mfma_f32_16x16x32_bf16 v[76:79], v[156:159], v[218:221], v[76:79]
	v_mfma_f32_16x16x32_bf16 v[76:79], v[164:167], v[222:225], v[76:79]
	v_mfma_f32_16x16x32_bf16 v[120:123], v[170:173], v[194:197], v[120:123]
	v_mfma_f32_16x16x32_bf16 v[120:123], v[174:177], v[198:201], v[120:123]
	v_mfma_f32_16x16x32_bf16 v[104:107], v[170:173], v[202:205], v[104:107]
	v_mfma_f32_16x16x32_bf16 v[104:107], v[174:177], v[206:209], v[104:107]
	v_mfma_f32_16x16x32_bf16 v[88:91], v[170:173], v[210:213], v[88:91]
	v_mfma_f32_16x16x32_bf16 v[88:91], v[174:177], v[214:217], v[88:91]
	v_mfma_f32_16x16x32_bf16 v[72:75], v[170:173], v[218:221], v[72:75]
	v_mfma_f32_16x16x32_bf16 v[72:75], v[174:177], v[222:225], v[72:75]
	s_setprio 0
	s_setprio 1
	v_mfma_f32_16x16x32_bf16 v[116:119], v[178:181], v[194:197], v[116:119]
	v_mfma_f32_16x16x32_bf16 v[116:119], v[182:185], v[198:201], v[116:119]
	v_mfma_f32_16x16x32_bf16 v[100:103], v[178:181], v[202:205], v[100:103]
	v_mfma_f32_16x16x32_bf16 v[100:103], v[182:185], v[206:209], v[100:103]
	v_mfma_f32_16x16x32_bf16 v[84:87], v[178:181], v[210:213], v[84:87]
	v_mfma_f32_16x16x32_bf16 v[84:87], v[182:185], v[214:217], v[84:87]
	v_mfma_f32_16x16x32_bf16 v[68:71], v[178:181], v[218:221], v[68:71]
	v_mfma_f32_16x16x32_bf16 v[68:71], v[182:185], v[222:225], v[68:71]
	v_mfma_f32_16x16x32_bf16 v[112:115], v[186:189], v[194:197], v[112:115]
	v_mfma_f32_16x16x32_bf16 v[112:115], v[190:193], v[198:201], v[112:115]
	v_mfma_f32_16x16x32_bf16 v[96:99], v[186:189], v[202:205], v[96:99]
	v_mfma_f32_16x16x32_bf16 v[96:99], v[190:193], v[206:209], v[96:99]
	v_mfma_f32_16x16x32_bf16 v[80:83], v[186:189], v[210:213], v[80:83]
	v_mfma_f32_16x16x32_bf16 v[80:83], v[190:193], v[214:217], v[80:83]
	v_mfma_f32_16x16x32_bf16 v[64:67], v[186:189], v[218:221], v[64:67]
	v_mfma_f32_16x16x32_bf16 v[64:67], v[190:193], v[222:225], v[64:67]
	s_setprio 0
	s_barrier
; #define PG8_STAGE(bufoff, gbase, voff) do { _Pragma("unroll") for (int _i = 0; _i < 2; ++_i) \
;         __builtin_amdgcn_global_load_lds((const unsigned*)((const char*)(gbase) + (voff)[_i]), (LAS unsigned*)(lds + (bufoff) + ldsw + _i * 8192), 16, 0, 0); } while (0)
; #define PG8_LDA(dst, b, h) do { _Pragma("unroll") for (int m = 0; m < 4; ++m) _Pragma("unroll") for (int k = 0; k < 2; ++k) dst[m][k] = *(const LAS bf16x8*)(lds + PG8_SA(b, h) + aoff + m * 2048 + k * 1024); } while (0)
; #define PG8_MMA(ai, bj, At, Bt) do { __builtin_amdgcn_s_setprio(1); _Pragma("unroll") for (int m = 0; m < 4; ++m) _Pragma("unroll") for (int n = 0; n < 2; ++n) _Pragma("unroll") for (int k = 0; k < 2; ++k) \
;         acc[ai][bj][m][n] = __builtin_amdgcn_mfma_f32_16x16x32_bf16(Bt[n][k], At[m][k], acc[ai][bj][m][n], 0, 0, 0); __builtin_amdgcn_s_setprio(0); } while (0)
; #define PG8_WAIT_V(n) asm volatile("s_waitcnt vmcnt(" #n ")" ::: "memory")
; #define PG8_WAIT_L(n) asm volatile("s_waitcnt lgkmcnt(" #n ")" ::: "memory")
; #define PG8_BAR __builtin_amdgcn_s_barrier()
; #define PG8_SCHED __builtin_amdgcn_sched_barrier(0)
; template <class EpiT>
; __device__ __forceinline__ void gemm_phase(LAS unsigned char* lds, const Gemm g, const StaticOrder& S, const EpiT& E) {
;     ...
;             PG8_LDA(At, 1, 1); PG8_STAGE(PG8_SB(1, 0), b3, voffB); PG8_STAGE(PG8_SB(1, 1), b3 + hstepB, voffB); PG8_STAGE(PG8_SA(1, 0), a3, voffA);
;             PG8_WAIT_V(8); PG8_WAIT_L(0); PG8_BAR; PG8_MMA(1, 0, At, B0); PG8_MMA(1, 1, At, B1); PG8_BAR; PG8_SCHED;
;         }
;         if (wr == 0) PG8_BAR;
	s_add_i32 s24, s57, s37
	v_lshl_add_u64 v[226:227], v[226:227], 0, s[14:15]
	s_mov_b32 m0, s24
	ds_read_b128 v[194:197], v162 offset:49152
	ds_read_b128 v[198:201], v162 offset:50176
	ds_read_b128 v[202:205], v162 offset:51200
	ds_read_b128 v[206:209], v162 offset:52224
	ds_read_b128 v[210:213], v162 offset:53248
	ds_read_b128 v[214:217], v162 offset:54272
	ds_read_b128 v[218:221], v162 offset:55296
	ds_read_b128 v[222:225], v162 offset:56320
	global_load_lds_dwordx4 v[226:227], off
	s_add_i32 m0, s24, 0x2000
	s_add_u32 s22, s22, 0x84080
	v_lshl_add_u64 v[226:227], v[228:229], 0, s[14:15]
	s_addc_u32 s23, s23, 0
	s_add_i32 s24, s58, s37
	global_load_lds_dwordx4 v[226:227], off
	v_lshl_add_u64 v[226:227], s[22:23], 0, v[130:131]
	s_mov_b32 m0, s24
	s_nop 0
	global_load_lds_dwordx4 v[226:227], off
	v_lshl_add_u64 v[226:227], s[22:23], 0, v[134:135]
	s_add_i32 m0, s24, 0x2000
	s_nop 0
	global_load_lds_dwordx4 v[226:227], off
	v_lshl_add_u64 v[226:227], v[230:231], 0, s[14:15]
	s_mov_b32 m0, s44
	s_nop 0
	global_load_lds_dwordx4 v[226:227], off
	v_lshl_add_u64 v[226:227], v[232:233], 0, s[14:15]
	s_mov_b32 m0, s45
	s_nop 0
	global_load_lds_dwordx4 v[226:227], off
	s_waitcnt vmcnt(8)
	s_waitcnt lgkmcnt(0)
	s_barrier
	s_setprio 1
	v_mfma_f32_16x16x32_bf16 v[60:63], v[156:159], v[194:197], v[60:63]
	v_mfma_f32_16x16x32_bf16 v[60:63], v[164:167], v[198:201], v[60:63]
	v_mfma_f32_16x16x32_bf16 v[44:47], v[156:159], v[202:205], v[44:47]
	v_mfma_f32_16x16x32_bf16 v[44:47], v[164:167], v[206:209], v[44:47]
	v_mfma_f32_16x16x32_bf16 v[28:31], v[156:159], v[210:213], v[28:31]
	v_mfma_f32_16x16x32_bf16 v[28:31], v[164:167], v[214:217], v[28:31]
	v_mfma_f32_16x16x32_bf16 v[12:15], v[156:159], v[218:221], v[12:15]
	v_mfma_f32_16x16x32_bf16 v[12:15], v[164:167], v[222:225], v[12:15]
	v_mfma_f32_16x16x32_bf16 v[56:59], v[170:173], v[194:197], v[56:59]
	v_mfma_f32_16x16x32_bf16 v[56:59], v[174:177], v[198:201], v[56:59]
	v_mfma_f32_16x16x32_bf16 v[40:43], v[170:173], v[202:205], v[40:43]
	v_mfma_f32_16x16x32_bf16 v[40:43], v[174:177], v[206:209], v[40:43]
	v_mfma_f32_16x16x32_bf16 v[24:27], v[170:173], v[210:213], v[24:27]
	v_mfma_f32_16x16x32_bf16 v[24:27], v[174:177], v[214:217], v[24:27]
	v_mfma_f32_16x16x32_bf16 v[8:11], v[170:173], v[218:221], v[8:11]
	v_mfma_f32_16x16x32_bf16 v[8:11], v[174:177], v[222:225], v[8:11]
	s_setprio 0
	s_setprio 1
	v_mfma_f32_16x16x32_bf16 v[52:55], v[178:181], v[194:197], v[52:55]
	v_mfma_f32_16x16x32_bf16 v[52:55], v[182:185], v[198:201], v[52:55]
	v_mfma_f32_16x16x32_bf16 v[36:39], v[178:181], v[202:205], v[36:39]
	v_mfma_f32_16x16x32_bf16 v[36:39], v[182:185], v[206:209], v[36:39]
	v_mfma_f32_16x16x32_bf16 v[20:23], v[178:181], v[210:213], v[20:23]
	v_mfma_f32_16x16x32_bf16 v[20:23], v[182:185], v[214:217], v[20:23]
	v_mfma_f32_16x16x32_bf16 v[4:7], v[178:181], v[218:221], v[4:7]
	v_mfma_f32_16x16x32_bf16 v[4:7], v[182:185], v[222:225], v[4:7]
	v_mfma_f32_16x16x32_bf16 v[48:51], v[186:189], v[194:197], v[48:51]
	v_mfma_f32_16x16x32_bf16 v[48:51], v[190:193], v[198:201], v[48:51]
	v_mfma_f32_16x16x32_bf16 v[32:35], v[186:189], v[202:205], v[32:35]
	v_mfma_f32_16x16x32_bf16 v[32:35], v[190:193], v[206:209], v[32:35]
	v_mfma_f32_16x16x32_bf16 v[16:19], v[186:189], v[210:213], v[16:19]
	v_mfma_f32_16x16x32_bf16 v[16:19], v[190:193], v[214:217], v[16:19]
	v_mfma_f32_16x16x32_bf16 v[0:3], v[186:189], v[218:221], v[0:3]
	v_mfma_f32_16x16x32_bf16 v[0:3], v[190:193], v[222:225], v[0:3]
	s_setprio 0
	s_barrier
	s_add_i32 s56, s56, 2
	s_add_u32 s20, s20, 0x100
	s_addc_u32 s21, s21, 0
	s_add_u32 s8, s8, 0x100
	s_addc_u32 s39, s39, 0
	s_cmp_gt_u32 s56, 29
	s_cbranch_scc0 .LBB0_761
	s_and_b64 vcc, exec, s[16:17]
	s_cbranch_vccz .LBB0_764
	s_barrier

; #define PG8_STAGE(bufoff, gbase, voff) do { _Pragma("unroll") for (int _i = 0; _i < 2; ++_i) \
;         __builtin_amdgcn_global_load_lds((const unsigned*)((const char*)(gbase) + (voff)[_i]), (LAS unsigned*)(lds + (bufoff) + ldsw + _i * 8192), 16, 0, 0); } while (0)
; #define PG8_LDA(dst, b, h) do { _Pragma("unroll") for (int m = 0; m < 4; ++m) _Pragma("unroll") for (int k = 0; k < 2; ++k) dst[m][k] = *(const LAS bf16x8*)(lds + PG8_SA(b, h) + aoff + m * 2048 + k * 1024); } while (0)
; #define PG8_LDB(dst, b, h) do { _Pragma("unroll") for (int n = 0; n < 2; ++n) _Pragma("unroll") for (int k = 0; k < 2; ++k) dst[n][k] = *(const LAS bf16x8*)(lds + PG8_SB(b, h) + boff + n * 2048 + k * 1024); } while (0)
; #define PG8_MMA(ai, bj, At, Bt) do { __builtin_amdgcn_s_setprio(1); _Pragma("unroll") for (int m = 0; m < 4; ++m) _Pragma("unroll") for (int n = 0; n < 2; ++n) _Pragma("unroll") for (int k = 0; k < 2; ++k) \
;         acc[ai][bj][m][n] = __builtin_amdgcn_mfma_f32_16x16x32_bf16(Bt[n][k], At[m][k], acc[ai][bj][m][n], 0, 0, 0); __builtin_amdgcn_s_setprio(0); } while (0)
; #define PG8_WAIT_V(n) asm volatile("s_waitcnt vmcnt(" #n ")" ::: "memory")
; #define PG8_WAIT_L(n) asm volatile("s_waitcnt lgkmcnt(" #n ")" ::: "memory")
; #define PG8_BAR __builtin_amdgcn_s_barrier()
; template <class EpiT>
; __device__ __forceinline__ void gemm_phase(LAS unsigned char* lds, const Gemm g, const StaticOrder& S, const EpiT& E) {
;     ...
;         const char* nA = has_next ? (const char*)g.A + (size_t)nxt.pm * tstepA + (size_t)nxt.pn * g.a_koff * 2 : cA; const char* nB = has_next ? (const char*)g.Bt + (size_t)nxt.pn * tstepB : cB;
;         for (int t = 0; t < nt; t += 2) {
;             const bool last = (t == nt - 2);
;             const char* a1 = cA + (size_t)(t + 1) * kstep;
;             const char* a2 = last ? nA : cA + (size_t)(t + 2) * kstep; const char* b2 = last ? nB : cB + (size_t)(t + 2) * kstep;
;             const char* a3 = a2 + kstep; const char* b3 = b2 + kstep;
;             PG8_LDB(B0, 0, 0); PG8_LDB(B1, 0, 1); PG8_SCHED; PG8_LDA(At, 0, 0); PG8_STAGE(PG8_SA(1, 1), a1 + hstepA, voffA);
;             PG8_WAIT_V(8); PG8_WAIT_L(0); PG8_BAR; PG8_MMA(0, 0, At, B0); PG8_MMA(0, 1, At, B1); PG8_BAR; PG8_SCHED;
;             PG8_LDA(At, 0, 1); PG8_STAGE(PG8_SB(0, 0), b2, voffB); PG8_STAGE(PG8_SB(0, 1), b2 + hstepB, voffB); PG8_STAGE(PG8_SA(0, 0), a2, voffA);
.LBB0_1032:
	ds_read_b128 v[154:157], v150
	ds_read_b128 v[158:161], v150 offset:1024
	ds_read_b128 v[162:165], v150 offset:2048
	ds_read_b128 v[170:173], v150 offset:3072
	ds_read_b128 v[174:177], v151
	ds_read_b128 v[178:181], v151 offset:1024
	ds_read_b128 v[182:185], v151 offset:2048
	ds_read_b128 v[186:189], v151 offset:3072
	s_add_u32 s20, s18, 0xfff7c080
	s_addc_u32 s21, s19, -1
	s_cmp_eq_u32 s55, 28
	s_cselect_b32 s23, s5, s21
	s_cselect_b32 s22, s4, s20
	s_cselect_b32 s21, s17, s54
	s_cselect_b32 s20, s16, s53
	v_lshl_add_u64 v[166:167], s[18:19], 0, v[138:139]
	s_add_i32 m0, s37, 0xc000
	ds_read_b128 v[190:193], v152
	ds_read_b128 v[194:197], v152 offset:1024
	ds_read_b128 v[198:201], v152 offset:2048
	ds_read_b128 v[202:205], v152 offset:3072
	ds_read_b128 v[206:209], v152 offset:4096
	ds_read_b128 v[210:213], v152 offset:5120
	ds_read_b128 v[214:217], v152 offset:6144
	ds_read_b128 v[218:221], v152 offset:7168
	global_load_lds_dwordx4 v[166:167], off
	v_lshl_add_u64 v[166:167], s[18:19], 0, v[140:141]
	s_add_i32 m0, s37, 0xe000
	s_nop 0
	global_load_lds_dwordx4 v[166:167], off
	s_waitcnt vmcnt(8)
	s_waitcnt lgkmcnt(0)
	s_barrier
	s_setprio 1
	v_mfma_f32_16x16x32_bf16 v[124:127], v[154:157], v[190:193], v[124:127]
	v_mfma_f32_16x16x32_bf16 v[124:127], v[158:161], v[194:197], v[124:127]
	v_mfma_f32_16x16x32_bf16 v[108:111], v[154:157], v[198:201], v[108:111]
	v_mfma_f32_16x16x32_bf16 v[108:111], v[158:161], v[202:205], v[108:111]
	v_mfma_f32_16x16x32_bf16 v[92:95], v[154:157], v[206:209], v[92:95]
	v_mfma_f32_16x16x32_bf16 v[92:95], v[158:161], v[210:213], v[92:95]
	v_mfma_f32_16x16x32_bf16 v[76:79], v[154:157], v[214:217], v[76:79]
	v_mfma_f32_16x16x32_bf16 v[76:79], v[158:161], v[218:221], v[76:79]
	v_mfma_f32_16x16x32_bf16 v[120:123], v[162:165], v[190:193], v[120:123]
	v_mfma_f32_16x16x32_bf16 v[120:123], v[170:173], v[194:197], v[120:123]
	v_mfma_f32_16x16x32_bf16 v[104:107], v[162:165], v[198:201], v[104:107]
	v_mfma_f32_16x16x32_bf16 v[104:107], v[170:173], v[202:205], v[104:107]
	v_mfma_f32_16x16x32_bf16 v[88:91], v[162:165], v[206:209], v[88:91]
	v_mfma_f32_16x16x32_bf16 v[88:91], v[170:173], v[210:213], v[88:91]
	v_mfma_f32_16x16x32_bf16 v[72:75], v[162:165], v[214:217], v[72:75]
	v_mfma_f32_16x16x32_bf16 v[72:75], v[170:173], v[218:221], v[72:75]
	s_setprio 0
	s_setprio 1
	v_mfma_f32_16x16x32_bf16 v[116:119], v[174:177], v[190:193], v[116:119]
	v_mfma_f32_16x16x32_bf16 v[116:119], v[178:181], v[194:197], v[116:119]
	v_mfma_f32_16x16x32_bf16 v[100:103], v[174:177], v[198:201], v[100:103]
	v_mfma_f32_16x16x32_bf16 v[100:103], v[178:181], v[202:205], v[100:103]
	v_mfma_f32_16x16x32_bf16 v[84:87], v[174:177], v[206:209], v[84:87]
	v_mfma_f32_16x16x32_bf16 v[84:87], v[178:181], v[210:213], v[84:87]
	v_mfma_f32_16x16x32_bf16 v[68:71], v[174:177], v[214:217], v[68:71]
	v_mfma_f32_16x16x32_bf16 v[68:71], v[178:181], v[218:221], v[68:71]
	v_mfma_f32_16x16x32_bf16 v[112:115], v[182:185], v[190:193], v[112:115]
	v_mfma_f32_16x16x32_bf16 v[112:115], v[186:189], v[194:197], v[112:115]
	v_mfma_f32_16x16x32_bf16 v[96:99], v[182:185], v[198:201], v[96:99]
	v_mfma_f32_16x16x32_bf16 v[96:99], v[186:189], v[202:205], v[96:99]
	v_mfma_f32_16x16x32_bf16 v[80:83], v[182:185], v[206:209], v[80:83]
	v_mfma_f32_16x16x32_bf16 v[80:83], v[186:189], v[210:213], v[80:83]
	v_mfma_f32_16x16x32_bf16 v[64:67], v[182:185], v[214:217], v[64:67]
	v_mfma_f32_16x16x32_bf16 v[64:67], v[186:189], v[218:221], v[64:67]
	s_setprio 0
	s_barrier
	s_add_i32 s56, s46, s36
	v_lshl_add_u64 v[166:167], s[20:21], 0, v[130:131]
	s_mov_b32 m0, s56
	ds_read_b128 v[190:193], v152 offset:16384
	ds_read_b128 v[194:197], v152 offset:17408
	ds_read_b128 v[198:201], v152 offset:18432
	ds_read_b128 v[202:205], v152 offset:19456
	ds_read_b128 v[206:209], v152 offset:20480
	ds_read_b128 v[210:213], v152 offset:21504
	ds_read_b128 v[214:217], v152 offset:22528
	ds_read_b128 v[218:221], v152 offset:23552
	global_load_lds_dwordx4 v[166:167], off
	s_add_i32 m0, s56, 0x2000
	s_add_u32 s56, s20, 0x84000
	v_lshl_add_u64 v[222:223], s[20:21], 0, v[134:135]
	s_addc_u32 s57, s21, 0
	s_add_i32 s58, s47, s36
	global_load_lds_dwordx4 v[222:223], off
	v_lshl_add_u64 v[224:225], s[56:57], 0, v[130:131]
	s_mov_b32 m0, s58
	v_lshl_add_u64 v[226:227], s[22:23], 0, v[132:133]
	global_load_lds_dwordx4 v[224:225], off
	v_lshl_add_u64 v[224:225], s[56:57], 0, v[134:135]
	s_add_i32 m0, s58, 0x2000
	s_nop 0
	global_load_lds_dwordx4 v[224:225], off
	v_lshl_add_u64 v[224:225], s[22:23], 0, v[128:129]
	s_mov_b32 m0, s37
	s_nop 0
	global_load_lds_dwordx4 v[224:225], off
	s_mov_b32 m0, s38
	s_nop 0
	global_load_lds_dwordx4 v[226:227], off
	s_waitcnt vmcnt(8)
	s_waitcnt lgkmcnt(0)
	s_barrier
; #define PG8_STAGE(bufoff, gbase, voff) do { _Pragma("unroll") for (int _i = 0; _i < 2; ++_i) \
;         __builtin_amdgcn_global_load_lds((const unsigned*)((const char*)(gbase) + (voff)[_i]), (LAS unsigned*)(lds + (bufoff) + ldsw + _i * 8192), 16, 0, 0); } while (0)
; #define PG8_LDA(dst, b, h) do { _Pragma("unroll") for (int m = 0; m < 4; ++m) _Pragma("unroll") for (int k = 0; k < 2; ++k) dst[m][k] = *(const LAS bf16x8*)(lds + PG8_SA(b, h) + aoff + m * 2048 + k * 1024); } while (0)
; #define PG8_LDB(dst, b, h) do { _Pragma("unroll") for (int n = 0; n < 2; ++n) _Pragma("unroll") for (int k = 0; k < 2; ++k) dst[n][k] = *(const LAS bf16x8*)(lds + PG8_SB(b, h) + boff + n * 2048 + k * 1024); } while (0)
; #define PG8_MMA(ai, bj, At, Bt) do { __builtin_amdgcn_s_setprio(1); _Pragma("unroll") for (int m = 0; m < 4; ++m) _Pragma("unroll") for (int n = 0; n < 2; ++n) _Pragma("unroll") for (int k = 0; k < 2; ++k) \
;         acc[ai][bj][m][n] = __builtin_amdgcn_mfma_f32_16x16x32_bf16(Bt[n][k], At[m][k], acc[ai][bj][m][n], 0, 0, 0); __builtin_amdgcn_s_setprio(0); } while (0)
; #define PG8_WAIT_V(n) asm volatile("s_waitcnt vmcnt(" #n ")" ::: "memory")
; #define PG8_WAIT_L(n) asm volatile("s_waitcnt lgkmcnt(" #n ")" ::: "memory")
; #define PG8_BAR __builtin_amdgcn_s_barrier()
; #define PG8_SCHED __builtin_amdgcn_sched_barrier(0)
; template <class EpiT>
; __device__ __forceinline__ void gemm_phase(LAS unsigned char* lds, const Gemm g, const StaticOrder& S, const EpiT& E) {
;     ...
;             PG8_WAIT_V(8); PG8_WAIT_L(0); PG8_BAR; PG8_MMA(1, 0, At, B0); PG8_MMA(1, 1, At, B1); PG8_BAR; PG8_SCHED;
;             PG8_LDB(B0, 1, 0); PG8_LDB(B1, 1, 1); PG8_SCHED; PG8_LDA(At, 1, 0); PG8_STAGE(PG8_SA(0, 1), a2 + hstepA, voffA);
;             PG8_WAIT_V(8); PG8_WAIT_L(0); PG8_BAR; PG8_MMA(0, 0, At, B0); PG8_MMA(0, 1, At, B1); PG8_BAR; PG8_SCHED;
	s_setprio 1
	v_mfma_f32_16x16x32_bf16 v[60:63], v[154:157], v[190:193], v[60:63]
	v_mfma_f32_16x16x32_bf16 v[60:63], v[158:161], v[194:197], v[60:63]
	v_mfma_f32_16x16x32_bf16 v[44:47], v[154:157], v[198:201], v[44:47]
	v_mfma_f32_16x16x32_bf16 v[44:47], v[158:161], v[202:205], v[44:47]
	v_mfma_f32_16x16x32_bf16 v[28:31], v[154:157], v[206:209], v[28:31]
	v_mfma_f32_16x16x32_bf16 v[28:31], v[158:161], v[210:213], v[28:31]
	v_mfma_f32_16x16x32_bf16 v[12:15], v[154:157], v[214:217], v[12:15]
	v_mfma_f32_16x16x32_bf16 v[12:15], v[158:161], v[218:221], v[12:15]
	v_mfma_f32_16x16x32_bf16 v[56:59], v[162:165], v[190:193], v[56:59]
	v_mfma_f32_16x16x32_bf16 v[56:59], v[170:173], v[194:197], v[56:59]
	v_mfma_f32_16x16x32_bf16 v[40:43], v[162:165], v[198:201], v[40:43]
	v_mfma_f32_16x16x32_bf16 v[40:43], v[170:173], v[202:205], v[40:43]
	v_mfma_f32_16x16x32_bf16 v[24:27], v[162:165], v[206:209], v[24:27]
	v_mfma_f32_16x16x32_bf16 v[24:27], v[170:173], v[210:213], v[24:27]
	v_mfma_f32_16x16x32_bf16 v[8:11], v[162:165], v[214:217], v[8:11]
	v_mfma_f32_16x16x32_bf16 v[8:11], v[170:173], v[218:221], v[8:11]
	s_setprio 0
	s_setprio 1
	v_mfma_f32_16x16x32_bf16 v[52:55], v[174:177], v[190:193], v[52:55]
	v_mfma_f32_16x16x32_bf16 v[52:55], v[178:181], v[194:197], v[52:55]
	v_mfma_f32_16x16x32_bf16 v[36:39], v[174:177], v[198:201], v[36:39]
	v_mfma_f32_16x16x32_bf16 v[36:39], v[178:181], v[202:205], v[36:39]
	v_mfma_f32_16x16x32_bf16 v[20:23], v[174:177], v[206:209], v[20:23]
	v_mfma_f32_16x16x32_bf16 v[20:23], v[178:181], v[210:213], v[20:23]
	v_mfma_f32_16x16x32_bf16 v[4:7], v[174:177], v[214:217], v[4:7]
	v_mfma_f32_16x16x32_bf16 v[4:7], v[178:181], v[218:221], v[4:7]
	v_mfma_f32_16x16x32_bf16 v[48:51], v[182:185], v[190:193], v[48:51]
	v_mfma_f32_16x16x32_bf16 v[48:51], v[186:189], v[194:197], v[48:51]
	v_mfma_f32_16x16x32_bf16 v[32:35], v[182:185], v[198:201], v[32:35]
	v_mfma_f32_16x16x32_bf16 v[32:35], v[186:189], v[202:205], v[32:35]
	v_mfma_f32_16x16x32_bf16 v[16:19], v[182:185], v[206:209], v[16:19]
	v_mfma_f32_16x16x32_bf16 v[16:19], v[186:189], v[210:213], v[16:19]
	v_mfma_f32_16x16x32_bf16 v[0:3], v[182:185], v[214:217], v[0:3]
	v_mfma_f32_16x16x32_bf16 v[0:3], v[186:189], v[218:221], v[0:3]
	s_setprio 0
	s_barrier
	s_add_i32 s56, 0, 0x18000
	s_add_i32 s57, 0, 0x1c000
	v_add_u32_e32 v170, s56, v146
	v_add_u32_e32 v186, s57, v146
	ds_read_b128 v[154:157], v170
	ds_read_b128 v[158:161], v170 offset:1024
	ds_read_b128 v[162:165], v170 offset:2048
	ds_read_b128 v[170:173], v170 offset:3072
	ds_read_b128 v[174:177], v186
	ds_read_b128 v[178:181], v186 offset:1024
	ds_read_b128 v[182:185], v186 offset:2048
	ds_read_b128 v[186:189], v186 offset:3072
	s_add_u32 s22, s22, 0x84000
	s_addc_u32 s23, s23, 0
	s_mov_b32 m0, s39
	v_lshl_add_u64 v[228:229], s[22:23], 0, v[128:129]
	ds_read_b128 v[190:193], v152 offset:32768
	ds_read_b128 v[194:197], v152 offset:33792
	ds_read_b128 v[198:201], v152 offset:34816
	ds_read_b128 v[202:205], v152 offset:35840
	ds_read_b128 v[206:209], v152 offset:36864
	ds_read_b128 v[210:213], v152 offset:37888
	ds_read_b128 v[214:217], v152 offset:38912
	ds_read_b128 v[218:221], v152 offset:39936
	global_load_lds_dwordx4 v[228:229], off
	v_lshl_add_u64 v[228:229], s[22:23], 0, v[132:133]
	s_mov_b32 m0, s40
	s_nop 0
	global_load_lds_dwordx4 v[228:229], off
	s_waitcnt vmcnt(8)
	s_waitcnt lgkmcnt(0)
	s_barrier
	s_setprio 1
	v_mfma_f32_16x16x32_bf16 v[124:127], v[154:157], v[190:193], v[124:127]
	v_mfma_f32_16x16x32_bf16 v[124:127], v[158:161], v[194:197], v[124:127]
	v_mfma_f32_16x16x32_bf16 v[108:111], v[154:157], v[198:201], v[108:111]
	v_mfma_f32_16x16x32_bf16 v[108:111], v[158:161], v[202:205], v[108:111]
	v_mfma_f32_16x16x32_bf16 v[92:95], v[154:157], v[206:209], v[92:95]
	v_mfma_f32_16x16x32_bf16 v[92:95], v[158:161], v[210:213], v[92:95]
	v_mfma_f32_16x16x32_bf16 v[76:79], v[154:157], v[214:217], v[76:79]
	v_mfma_f32_16x16x32_bf16 v[76:79], v[158:161], v[218:221], v[76:79]
	v_mfma_f32_16x16x32_bf16 v[120:123], v[162:165], v[190:193], v[120:123]
	v_mfma_f32_16x16x32_bf16 v[120:123], v[170:173], v[194:197], v[120:123]
	v_mfma_f32_16x16x32_bf16 v[104:107], v[162:165], v[198:201], v[104:107]
	v_mfma_f32_16x16x32_bf16 v[104:107], v[170:173], v[202:205], v[104:107]
	v_mfma_f32_16x16x32_bf16 v[88:91], v[162:165], v[206:209], v[88:91]
	v_mfma_f32_16x16x32_bf16 v[88:91], v[170:173], v[210:213], v[88:91]
	v_mfma_f32_16x16x32_bf16 v[72:75], v[162:165], v[214:217], v[72:75]
	v_mfma_f32_16x16x32_bf16 v[72:75], v[170:173], v[218:221], v[72:75]
	s_setprio 0
	s_setprio 1
	v_mfma_f32_16x16x32_bf16 v[116:119], v[174:177], v[190:193], v[116:119]
	v_mfma_f32_16x16x32_bf16 v[116:119], v[178:181], v[194:197], v[116:119]
	v_mfma_f32_16x16x32_bf16 v[100:103], v[174:177], v[198:201], v[100:103]
	v_mfma_f32_16x16x32_bf16 v[100:103], v[178:181], v[202:205], v[100:103]
	v_mfma_f32_16x16x32_bf16 v[84:87], v[174:177], v[206:209], v[84:87]
	v_mfma_f32_16x16x32_bf16 v[84:87], v[178:181], v[210:213], v[84:87]
	v_mfma_f32_16x16x32_bf16 v[68:71], v[174:177], v[214:217], v[68:71]
	v_mfma_f32_16x16x32_bf16 v[68:71], v[178:181], v[218:221], v[68:71]
	v_mfma_f32_16x16x32_bf16 v[112:115], v[182:185], v[190:193], v[112:115]
	v_mfma_f32_16x16x32_bf16 v[112:115], v[186:189], v[194:197], v[112:115]
	v_mfma_f32_16x16x32_bf16 v[96:99], v[182:185], v[198:201], v[96:99]
	v_mfma_f32_16x16x32_bf16 v[96:99], v[186:189], v[202:205], v[96:99]
	v_mfma_f32_16x16x32_bf16 v[80:83], v[182:185], v[206:209], v[80:83]
	v_mfma_f32_16x16x32_bf16 v[80:83], v[186:189], v[210:213], v[80:83]
	v_mfma_f32_16x16x32_bf16 v[64:67], v[182:185], v[214:217], v[64:67]
	v_mfma_f32_16x16x32_bf16 v[64:67], v[186:189], v[218:221], v[64:67]
	s_setprio 0
	s_barrier
; #define PG8_STAGE(bufoff, gbase, voff) do { _Pragma("unroll") for (int _i = 0; _i < 2; ++_i) \
;         __builtin_amdgcn_global_load_lds((const unsigned*)((const char*)(gbase) + (voff)[_i]), (LAS unsigned*)(lds + (bufoff) + ldsw + _i * 8192), 16, 0, 0); } while (0)
; #define PG8_LDA(dst, b, h) do { _Pragma("unroll") for (int m = 0; m < 4; ++m) _Pragma("unroll") for (int k = 0; k < 2; ++k) dst[m][k] = *(const LAS bf16x8*)(lds + PG8_SA(b, h) + aoff + m * 2048 + k * 1024); } while (0)
; #define PG8_MMA(ai, bj, At, Bt) do { __builtin_amdgcn_s_setprio(1); _Pragma("unroll") for (int m = 0; m < 4; ++m) _Pragma("unroll") for (int n = 0; n < 2; ++n) _Pragma("unroll") for (int k = 0; k < 2; ++k) \
;         acc[ai][bj][m][n] = __builtin_amdgcn_mfma_f32_16x16x32_bf16(Bt[n][k], At[m][k], acc[ai][bj][m][n], 0, 0, 0); __builtin_amdgcn_s_setprio(0); } while (0)
; #define PG8_WAIT_V(n) asm volatile("s_waitcnt vmcnt(" #n ")" ::: "memory")
; #define PG8_WAIT_L(n) asm volatile("s_waitcnt lgkmcnt(" #n ")" ::: "memory")
; #define PG8_BAR __builtin_amdgcn_s_barrier()
; #define PG8_SCHED __builtin_amdgcn_sched_barrier(0)
; template <class EpiT>
; __device__ __forceinline__ void gemm_phase(LAS unsigned char* lds, const Gemm g, const StaticOrder& S, const EpiT& E) {
;     ...
;             PG8_LDA(At, 1, 1); PG8_STAGE(PG8_SB(1, 0), b3, voffB); PG8_STAGE(PG8_SB(1, 1), b3 + hstepB, voffB); PG8_STAGE(PG8_SA(1, 0), a3, voffA);
;             PG8_WAIT_V(8); PG8_WAIT_L(0); PG8_BAR; PG8_MMA(1, 0, At, B0); PG8_MMA(1, 1, At, B1); PG8_BAR; PG8_SCHED;
;         }
;         if (wr == 0) PG8_BAR;
	s_add_i32 s22, s56, s36
	v_lshl_add_u64 v[166:167], v[166:167], 0, s[12:13]
	s_mov_b32 m0, s22
	ds_read_b128 v[190:193], v152 offset:49152
	ds_read_b128 v[194:197], v152 offset:50176
	ds_read_b128 v[198:201], v152 offset:51200
	ds_read_b128 v[202:205], v152 offset:52224
	ds_read_b128 v[206:209], v152 offset:53248
	ds_read_b128 v[210:213], v152 offset:54272
	ds_read_b128 v[214:217], v152 offset:55296
	ds_read_b128 v[218:221], v152 offset:56320
	global_load_lds_dwordx4 v[166:167], off
	s_add_i32 m0, s22, 0x2000
	s_add_u32 s20, s20, 0x84080
	v_lshl_add_u64 v[166:167], v[222:223], 0, s[12:13]
	s_addc_u32 s21, s21, 0
	s_add_i32 s22, s57, s36
	global_load_lds_dwordx4 v[166:167], off
	v_lshl_add_u64 v[166:167], s[20:21], 0, v[130:131]
	s_mov_b32 m0, s22
	s_nop 0
	global_load_lds_dwordx4 v[166:167], off
	v_lshl_add_u64 v[166:167], s[20:21], 0, v[134:135]
	s_add_i32 m0, s22, 0x2000
	s_nop 0
	global_load_lds_dwordx4 v[166:167], off
	v_lshl_add_u64 v[166:167], v[224:225], 0, s[12:13]
	s_mov_b32 m0, s42
	s_nop 0
	global_load_lds_dwordx4 v[166:167], off
	v_lshl_add_u64 v[166:167], v[226:227], 0, s[12:13]
	s_mov_b32 m0, s43
	s_nop 0
	global_load_lds_dwordx4 v[166:167], off
	s_waitcnt vmcnt(8)
	s_waitcnt lgkmcnt(0)
	s_barrier
	s_setprio 1
	v_mfma_f32_16x16x32_bf16 v[60:63], v[154:157], v[190:193], v[60:63]
	v_mfma_f32_16x16x32_bf16 v[60:63], v[158:161], v[194:197], v[60:63]
	v_mfma_f32_16x16x32_bf16 v[44:47], v[154:157], v[198:201], v[44:47]
	v_mfma_f32_16x16x32_bf16 v[44:47], v[158:161], v[202:205], v[44:47]
	v_mfma_f32_16x16x32_bf16 v[28:31], v[154:157], v[206:209], v[28:31]
	v_mfma_f32_16x16x32_bf16 v[28:31], v[158:161], v[210:213], v[28:31]
	v_mfma_f32_16x16x32_bf16 v[12:15], v[154:157], v[214:217], v[12:15]
	v_mfma_f32_16x16x32_bf16 v[12:15], v[158:161], v[218:221], v[12:15]
	v_mfma_f32_16x16x32_bf16 v[56:59], v[162:165], v[190:193], v[56:59]
	v_mfma_f32_16x16x32_bf16 v[56:59], v[170:173], v[194:197], v[56:59]
	v_mfma_f32_16x16x32_bf16 v[40:43], v[162:165], v[198:201], v[40:43]
	v_mfma_f32_16x16x32_bf16 v[40:43], v[170:173], v[202:205], v[40:43]
	v_mfma_f32_16x16x32_bf16 v[24:27], v[162:165], v[206:209], v[24:27]
	v_mfma_f32_16x16x32_bf16 v[24:27], v[170:173], v[210:213], v[24:27]
	v_mfma_f32_16x16x32_bf16 v[8:11], v[162:165], v[214:217], v[8:11]
	v_mfma_f32_16x16x32_bf16 v[8:11], v[170:173], v[218:221], v[8:11]
	s_setprio 0
	s_setprio 1
	v_mfma_f32_16x16x32_bf16 v[52:55], v[174:177], v[190:193], v[52:55]
	v_mfma_f32_16x16x32_bf16 v[52:55], v[178:181], v[194:197], v[52:55]
	v_mfma_f32_16x16x32_bf16 v[36:39], v[174:177], v[198:201], v[36:39]
	v_mfma_f32_16x16x32_bf16 v[36:39], v[178:181], v[202:205], v[36:39]
	v_mfma_f32_16x16x32_bf16 v[20:23], v[174:177], v[206:209], v[20:23]
	v_mfma_f32_16x16x32_bf16 v[20:23], v[178:181], v[210:213], v[20:23]
	v_mfma_f32_16x16x32_bf16 v[4:7], v[174:177], v[214:217], v[4:7]
	v_mfma_f32_16x16x32_bf16 v[4:7], v[178:181], v[218:221], v[4:7]
	v_mfma_f32_16x16x32_bf16 v[48:51], v[182:185], v[190:193], v[48:51]
	v_mfma_f32_16x16x32_bf16 v[48:51], v[186:189], v[194:197], v[48:51]
	v_mfma_f32_16x16x32_bf16 v[32:35], v[182:185], v[198:201], v[32:35]
	v_mfma_f32_16x16x32_bf16 v[32:35], v[186:189], v[202:205], v[32:35]
	v_mfma_f32_16x16x32_bf16 v[16:19], v[182:185], v[206:209], v[16:19]
	v_mfma_f32_16x16x32_bf16 v[16:19], v[186:189], v[210:213], v[16:19]
	v_mfma_f32_16x16x32_bf16 v[0:3], v[182:185], v[214:217], v[0:3]
	v_mfma_f32_16x16x32_bf16 v[0:3], v[186:189], v[218:221], v[0:3]
	s_setprio 0
	s_barrier
	s_add_i32 s55, s55, 2
	s_add_u32 s18, s18, 0x100
	s_addc_u32 s19, s19, 0
	s_add_u32 s53, s53, 0x100
	s_addc_u32 s54, s54, 0
	s_cmp_gt_u32 s55, 29
	s_cbranch_scc0 .LBB0_1032
	s_and_b64 vcc, exec, s[14:15]
	s_cbranch_vccz .LBB0_1035
	s_barrier

; #define PG8_STAGE(bufoff, gbase, voff) do { _Pragma("unroll") for (int _i = 0; _i < 2; ++_i) \
;         __builtin_amdgcn_global_load_lds((const unsigned*)((const char*)(gbase) + (voff)[_i]), (LAS unsigned*)(lds + (bufoff) + ldsw + _i * 8192), 16, 0, 0); } while (0)
; #define PG8_LDA(dst, b, h) do { _Pragma("unroll") for (int m = 0; m < 4; ++m) _Pragma("unroll") for (int k = 0; k < 2; ++k) dst[m][k] = *(const LAS bf16x8*)(lds + PG8_SA(b, h) + aoff + m * 2048 + k * 1024); } while (0)
; #define PG8_LDB(dst, b, h) do { _Pragma("unroll") for (int n = 0; n < 2; ++n) _Pragma("unroll") for (int k = 0; k < 2; ++k) dst[n][k] = *(const LAS bf16x8*)(lds + PG8_SB(b, h) + boff + n * 2048 + k * 1024); } while (0)
; #define PG8_MMA(ai, bj, At, Bt) do { __builtin_amdgcn_s_setprio(1); _Pragma("unroll") for (int m = 0; m < 4; ++m) _Pragma("unroll") for (int n = 0; n < 2; ++n) _Pragma("unroll") for (int k = 0; k < 2; ++k) \
;         acc[ai][bj][m][n] = __builtin_amdgcn_mfma_f32_16x16x32_bf16(Bt[n][k], At[m][k], acc[ai][bj][m][n], 0, 0, 0); __builtin_amdgcn_s_setprio(0); } while (0)
; #define PG8_WAIT_V(n) asm volatile("s_waitcnt vmcnt(" #n ")" ::: "memory")
; #define PG8_WAIT_L(n) asm volatile("s_waitcnt lgkmcnt(" #n ")" ::: "memory")
; #define PG8_BAR __builtin_amdgcn_s_barrier()
; template <class EpiT>
; __device__ __forceinline__ void gemm_phase(LAS unsigned char* lds, const Gemm g, const StaticOrder& S, const EpiT& E) {
;     ...
;         const char* nA = has_next ? (const char*)g.A + (size_t)nxt.pm * tstepA + (size_t)nxt.pn * g.a_koff * 2 : cA; const char* nB = has_next ? (const char*)g.Bt + (size_t)nxt.pn * tstepB : cB;
;         for (int t = 0; t < nt; t += 2) {
;             const bool last = (t == nt - 2);
;             const char* a1 = cA + (size_t)(t + 1) * kstep;
;             const char* a2 = last ? nA : cA + (size_t)(t + 2) * kstep; const char* b2 = last ? nB : cB + (size_t)(t + 2) * kstep;
;             const char* a3 = a2 + kstep; const char* b3 = b2 + kstep;
;             PG8_LDB(B0, 0, 0); PG8_LDB(B1, 0, 1); PG8_SCHED; PG8_LDA(At, 0, 0); PG8_STAGE(PG8_SA(1, 1), a1 + hstepA, voffA);
;             PG8_WAIT_V(8); PG8_WAIT_L(0); PG8_BAR; PG8_MMA(0, 0, At, B0); PG8_MMA(0, 1, At, B1); PG8_BAR; PG8_SCHED;
;             PG8_LDA(At, 0, 1); PG8_STAGE(PG8_SB(0, 0), b2, voffB); PG8_STAGE(PG8_SB(0, 1), b2 + hstepB, voffB); PG8_STAGE(PG8_SA(0, 0), a2, voffA);
.LBB0_1156:
	ds_read_b128 v[154:157], v150
	ds_read_b128 v[158:161], v150 offset:1024
	ds_read_b128 v[162:165], v150 offset:2048
	ds_read_b128 v[170:173], v150 offset:3072
	ds_read_b128 v[174:177], v151
	ds_read_b128 v[178:181], v151 offset:1024
	ds_read_b128 v[182:185], v151 offset:2048
	ds_read_b128 v[186:189], v151 offset:3072
	s_add_u32 s18, s16, 0xfff7c080
	s_addc_u32 s19, s17, -1
	s_cmp_eq_u32 s53, 28
	s_cselect_b32 s21, s3, s19
	s_cselect_b32 s20, s2, s18
	s_cselect_b32 s19, s15, s52
	s_cselect_b32 s18, s14, s51
	v_lshl_add_u64 v[144:145], s[16:17], 0, v[136:137]
	s_add_i32 m0, s36, 0xc000
	ds_read_b128 v[190:193], v152
	ds_read_b128 v[194:197], v152 offset:1024
	ds_read_b128 v[198:201], v152 offset:2048
	ds_read_b128 v[202:205], v152 offset:3072
	ds_read_b128 v[206:209], v152 offset:4096
	ds_read_b128 v[210:213], v152 offset:5120
	ds_read_b128 v[214:217], v152 offset:6144
	ds_read_b128 v[218:221], v152 offset:7168
	global_load_lds_dwordx4 v[144:145], off
	v_lshl_add_u64 v[144:145], s[16:17], 0, v[138:139]
	s_add_i32 m0, s36, 0xe000
	s_nop 0
	global_load_lds_dwordx4 v[144:145], off
	s_waitcnt vmcnt(8)
	s_waitcnt lgkmcnt(0)
	s_barrier
	s_setprio 1
	v_mfma_f32_16x16x32_bf16 v[124:127], v[154:157], v[190:193], v[124:127]
	v_mfma_f32_16x16x32_bf16 v[124:127], v[158:161], v[194:197], v[124:127]
	v_mfma_f32_16x16x32_bf16 v[108:111], v[154:157], v[198:201], v[108:111]
	v_mfma_f32_16x16x32_bf16 v[108:111], v[158:161], v[202:205], v[108:111]
	v_mfma_f32_16x16x32_bf16 v[92:95], v[154:157], v[206:209], v[92:95]
	v_mfma_f32_16x16x32_bf16 v[92:95], v[158:161], v[210:213], v[92:95]
	v_mfma_f32_16x16x32_bf16 v[76:79], v[154:157], v[214:217], v[76:79]
	v_mfma_f32_16x16x32_bf16 v[76:79], v[158:161], v[218:221], v[76:79]
	v_mfma_f32_16x16x32_bf16 v[120:123], v[162:165], v[190:193], v[120:123]
	v_mfma_f32_16x16x32_bf16 v[120:123], v[170:173], v[194:197], v[120:123]
	v_mfma_f32_16x16x32_bf16 v[104:107], v[162:165], v[198:201], v[104:107]
	v_mfma_f32_16x16x32_bf16 v[104:107], v[170:173], v[202:205], v[104:107]
	v_mfma_f32_16x16x32_bf16 v[88:91], v[162:165], v[206:209], v[88:91]
	v_mfma_f32_16x16x32_bf16 v[88:91], v[170:173], v[210:213], v[88:91]
	v_mfma_f32_16x16x32_bf16 v[72:75], v[162:165], v[214:217], v[72:75]
	v_mfma_f32_16x16x32_bf16 v[72:75], v[170:173], v[218:221], v[72:75]
	s_setprio 0
	s_setprio 1
	v_mfma_f32_16x16x32_bf16 v[116:119], v[174:177], v[190:193], v[116:119]
	v_mfma_f32_16x16x32_bf16 v[116:119], v[178:181], v[194:197], v[116:119]
	v_mfma_f32_16x16x32_bf16 v[100:103], v[174:177], v[198:201], v[100:103]
	v_mfma_f32_16x16x32_bf16 v[100:103], v[178:181], v[202:205], v[100:103]
	v_mfma_f32_16x16x32_bf16 v[84:87], v[174:177], v[206:209], v[84:87]
	v_mfma_f32_16x16x32_bf16 v[84:87], v[178:181], v[210:213], v[84:87]
	v_mfma_f32_16x16x32_bf16 v[68:71], v[174:177], v[214:217], v[68:71]
	v_mfma_f32_16x16x32_bf16 v[68:71], v[178:181], v[218:221], v[68:71]
	v_mfma_f32_16x16x32_bf16 v[112:115], v[182:185], v[190:193], v[112:115]
	v_mfma_f32_16x16x32_bf16 v[112:115], v[186:189], v[194:197], v[112:115]
	v_mfma_f32_16x16x32_bf16 v[96:99], v[182:185], v[198:201], v[96:99]
	v_mfma_f32_16x16x32_bf16 v[96:99], v[186:189], v[202:205], v[96:99]
	v_mfma_f32_16x16x32_bf16 v[80:83], v[182:185], v[206:209], v[80:83]
	v_mfma_f32_16x16x32_bf16 v[80:83], v[186:189], v[210:213], v[80:83]
	v_mfma_f32_16x16x32_bf16 v[64:67], v[182:185], v[214:217], v[64:67]
	v_mfma_f32_16x16x32_bf16 v[64:67], v[186:189], v[218:221], v[64:67]
	s_setprio 0
	s_barrier
	s_add_i32 s54, s44, s27
	v_lshl_add_u64 v[144:145], s[18:19], 0, v[132:133]
	s_mov_b32 m0, s54
	ds_read_b128 v[190:193], v152 offset:16384
	ds_read_b128 v[194:197], v152 offset:17408
	ds_read_b128 v[198:201], v152 offset:18432
	ds_read_b128 v[202:205], v152 offset:19456
	ds_read_b128 v[206:209], v152 offset:20480
	ds_read_b128 v[210:213], v152 offset:21504
	ds_read_b128 v[214:217], v152 offset:22528
	ds_read_b128 v[218:221], v152 offset:23552
	global_load_lds_dwordx4 v[144:145], off
	s_add_i32 m0, s54, 0x2000
	s_add_u32 s54, s18, 0x84000
	v_lshl_add_u64 v[166:167], s[18:19], 0, v[128:129]
	s_addc_u32 s55, s19, 0
	s_add_i32 s56, s45, s27
	global_load_lds_dwordx4 v[166:167], off
	v_lshl_add_u64 v[222:223], s[54:55], 0, v[132:133]
	s_mov_b32 m0, s56
	v_lshl_add_u64 v[224:225], s[20:21], 0, v[130:131]
	global_load_lds_dwordx4 v[222:223], off
	v_lshl_add_u64 v[222:223], s[54:55], 0, v[128:129]
	s_add_i32 m0, s56, 0x2000
	s_nop 0
	global_load_lds_dwordx4 v[222:223], off
	v_lshl_add_u64 v[222:223], s[20:21], 0, v[134:135]
	s_mov_b32 m0, s36
	s_nop 0
	global_load_lds_dwordx4 v[222:223], off
	s_mov_b32 m0, s37
	s_nop 0
	global_load_lds_dwordx4 v[224:225], off
	s_waitcnt vmcnt(8)
	s_waitcnt lgkmcnt(0)
	s_barrier
; #define PG8_STAGE(bufoff, gbase, voff) do { _Pragma("unroll") for (int _i = 0; _i < 2; ++_i) \
;         __builtin_amdgcn_global_load_lds((const unsigned*)((const char*)(gbase) + (voff)[_i]), (LAS unsigned*)(lds + (bufoff) + ldsw + _i * 8192), 16, 0, 0); } while (0)
; #define PG8_LDA(dst, b, h) do { _Pragma("unroll") for (int m = 0; m < 4; ++m) _Pragma("unroll") for (int k = 0; k < 2; ++k) dst[m][k] = *(const LAS bf16x8*)(lds + PG8_SA(b, h) + aoff + m * 2048 + k * 1024); } while (0)
; #define PG8_LDB(dst, b, h) do { _Pragma("unroll") for (int n = 0; n < 2; ++n) _Pragma("unroll") for (int k = 0; k < 2; ++k) dst[n][k] = *(const LAS bf16x8*)(lds + PG8_SB(b, h) + boff + n * 2048 + k * 1024); } while (0)
; #define PG8_MMA(ai, bj, At, Bt) do { __builtin_amdgcn_s_setprio(1); _Pragma("unroll") for (int m = 0; m < 4; ++m) _Pragma("unroll") for (int n = 0; n < 2; ++n) _Pragma("unroll") for (int k = 0; k < 2; ++k) \
;         acc[ai][bj][m][n] = __builtin_amdgcn_mfma_f32_16x16x32_bf16(Bt[n][k], At[m][k], acc[ai][bj][m][n], 0, 0, 0); __builtin_amdgcn_s_setprio(0); } while (0)
; #define PG8_WAIT_V(n) asm volatile("s_waitcnt vmcnt(" #n ")" ::: "memory")
; #define PG8_WAIT_L(n) asm volatile("s_waitcnt lgkmcnt(" #n ")" ::: "memory")
; #define PG8_BAR __builtin_amdgcn_s_barrier()
; #define PG8_SCHED __builtin_amdgcn_sched_barrier(0)
; template <class EpiT>
; __device__ __forceinline__ void gemm_phase(LAS unsigned char* lds, const Gemm g, const StaticOrder& S, const EpiT& E) {
;     ...
;             PG8_WAIT_V(8); PG8_WAIT_L(0); PG8_BAR; PG8_MMA(1, 0, At, B0); PG8_MMA(1, 1, At, B1); PG8_BAR; PG8_SCHED;
;             PG8_LDB(B0, 1, 0); PG8_LDB(B1, 1, 1); PG8_SCHED; PG8_LDA(At, 1, 0); PG8_STAGE(PG8_SA(0, 1), a2 + hstepA, voffA);
;             PG8_WAIT_V(8); PG8_WAIT_L(0); PG8_BAR; PG8_MMA(0, 0, At, B0); PG8_MMA(0, 1, At, B1); PG8_BAR; PG8_SCHED;
	s_setprio 1
	v_mfma_f32_16x16x32_bf16 v[60:63], v[154:157], v[190:193], v[60:63]
	v_mfma_f32_16x16x32_bf16 v[60:63], v[158:161], v[194:197], v[60:63]
	v_mfma_f32_16x16x32_bf16 v[44:47], v[154:157], v[198:201], v[44:47]
	v_mfma_f32_16x16x32_bf16 v[44:47], v[158:161], v[202:205], v[44:47]
	v_mfma_f32_16x16x32_bf16 v[28:31], v[154:157], v[206:209], v[28:31]
	v_mfma_f32_16x16x32_bf16 v[28:31], v[158:161], v[210:213], v[28:31]
	v_mfma_f32_16x16x32_bf16 v[12:15], v[154:157], v[214:217], v[12:15]
	v_mfma_f32_16x16x32_bf16 v[12:15], v[158:161], v[218:221], v[12:15]
	v_mfma_f32_16x16x32_bf16 v[56:59], v[162:165], v[190:193], v[56:59]
	v_mfma_f32_16x16x32_bf16 v[56:59], v[170:173], v[194:197], v[56:59]
	v_mfma_f32_16x16x32_bf16 v[40:43], v[162:165], v[198:201], v[40:43]
	v_mfma_f32_16x16x32_bf16 v[40:43], v[170:173], v[202:205], v[40:43]
	v_mfma_f32_16x16x32_bf16 v[24:27], v[162:165], v[206:209], v[24:27]
	v_mfma_f32_16x16x32_bf16 v[24:27], v[170:173], v[210:213], v[24:27]
	v_mfma_f32_16x16x32_bf16 v[8:11], v[162:165], v[214:217], v[8:11]
	v_mfma_f32_16x16x32_bf16 v[8:11], v[170:173], v[218:221], v[8:11]
	s_setprio 0
	s_setprio 1
	v_mfma_f32_16x16x32_bf16 v[52:55], v[174:177], v[190:193], v[52:55]
	v_mfma_f32_16x16x32_bf16 v[52:55], v[178:181], v[194:197], v[52:55]
	v_mfma_f32_16x16x32_bf16 v[36:39], v[174:177], v[198:201], v[36:39]
	v_mfma_f32_16x16x32_bf16 v[36:39], v[178:181], v[202:205], v[36:39]
	v_mfma_f32_16x16x32_bf16 v[20:23], v[174:177], v[206:209], v[20:23]
	v_mfma_f32_16x16x32_bf16 v[20:23], v[178:181], v[210:213], v[20:23]
	v_mfma_f32_16x16x32_bf16 v[4:7], v[174:177], v[214:217], v[4:7]
	v_mfma_f32_16x16x32_bf16 v[4:7], v[178:181], v[218:221], v[4:7]
	v_mfma_f32_16x16x32_bf16 v[48:51], v[182:185], v[190:193], v[48:51]
	v_mfma_f32_16x16x32_bf16 v[48:51], v[186:189], v[194:197], v[48:51]
	v_mfma_f32_16x16x32_bf16 v[32:35], v[182:185], v[198:201], v[32:35]
	v_mfma_f32_16x16x32_bf16 v[32:35], v[186:189], v[202:205], v[32:35]
	v_mfma_f32_16x16x32_bf16 v[16:19], v[182:185], v[206:209], v[16:19]
	v_mfma_f32_16x16x32_bf16 v[16:19], v[186:189], v[210:213], v[16:19]
	v_mfma_f32_16x16x32_bf16 v[0:3], v[182:185], v[214:217], v[0:3]
	v_mfma_f32_16x16x32_bf16 v[0:3], v[186:189], v[218:221], v[0:3]
	s_setprio 0
	s_barrier
	s_add_i32 s54, 0, 0x18000
	v_add_u32_e32 v153, s54, v147
	s_add_i32 s55, 0, 0x1c000
	ds_read_b128 v[154:157], v153
	ds_read_b128 v[158:161], v153 offset:1024
	ds_read_b128 v[162:165], v153 offset:2048
	ds_read_b128 v[170:173], v153 offset:3072
	v_add_u32_e32 v153, s55, v147
	ds_read_b128 v[174:177], v153
	ds_read_b128 v[178:181], v153 offset:1024
	ds_read_b128 v[182:185], v153 offset:2048
	ds_read_b128 v[186:189], v153 offset:3072
	s_add_u32 s20, s20, 0x84000
	s_addc_u32 s21, s21, 0
	s_mov_b32 m0, s38
	v_lshl_add_u64 v[226:227], s[20:21], 0, v[134:135]
	ds_read_b128 v[190:193], v152 offset:32768
	ds_read_b128 v[194:197], v152 offset:33792
	ds_read_b128 v[198:201], v152 offset:34816
	ds_read_b128 v[202:205], v152 offset:35840
	ds_read_b128 v[206:209], v152 offset:36864
	ds_read_b128 v[210:213], v152 offset:37888
	ds_read_b128 v[214:217], v152 offset:38912
	ds_read_b128 v[218:221], v152 offset:39936
	global_load_lds_dwordx4 v[226:227], off
	v_lshl_add_u64 v[226:227], s[20:21], 0, v[130:131]
	s_mov_b32 m0, s39
	s_nop 0
	global_load_lds_dwordx4 v[226:227], off
	s_waitcnt vmcnt(8)
	s_waitcnt lgkmcnt(0)
	s_barrier
	s_setprio 1
	v_mfma_f32_16x16x32_bf16 v[124:127], v[154:157], v[190:193], v[124:127]
	v_mfma_f32_16x16x32_bf16 v[124:127], v[158:161], v[194:197], v[124:127]
	v_mfma_f32_16x16x32_bf16 v[108:111], v[154:157], v[198:201], v[108:111]
	v_mfma_f32_16x16x32_bf16 v[108:111], v[158:161], v[202:205], v[108:111]
	v_mfma_f32_16x16x32_bf16 v[92:95], v[154:157], v[206:209], v[92:95]
	v_mfma_f32_16x16x32_bf16 v[92:95], v[158:161], v[210:213], v[92:95]
	v_mfma_f32_16x16x32_bf16 v[76:79], v[154:157], v[214:217], v[76:79]
	v_mfma_f32_16x16x32_bf16 v[76:79], v[158:161], v[218:221], v[76:79]
	v_mfma_f32_16x16x32_bf16 v[120:123], v[162:165], v[190:193], v[120:123]
	v_mfma_f32_16x16x32_bf16 v[120:123], v[170:173], v[194:197], v[120:123]
	v_mfma_f32_16x16x32_bf16 v[104:107], v[162:165], v[198:201], v[104:107]
	v_mfma_f32_16x16x32_bf16 v[104:107], v[170:173], v[202:205], v[104:107]
	v_mfma_f32_16x16x32_bf16 v[88:91], v[162:165], v[206:209], v[88:91]
	v_mfma_f32_16x16x32_bf16 v[88:91], v[170:173], v[210:213], v[88:91]
	v_mfma_f32_16x16x32_bf16 v[72:75], v[162:165], v[214:217], v[72:75]
	v_mfma_f32_16x16x32_bf16 v[72:75], v[170:173], v[218:221], v[72:75]
	s_setprio 0
	s_setprio 1
	v_mfma_f32_16x16x32_bf16 v[116:119], v[174:177], v[190:193], v[116:119]
	v_mfma_f32_16x16x32_bf16 v[116:119], v[178:181], v[194:197], v[116:119]
	v_mfma_f32_16x16x32_bf16 v[100:103], v[174:177], v[198:201], v[100:103]
	v_mfma_f32_16x16x32_bf16 v[100:103], v[178:181], v[202:205], v[100:103]
	v_mfma_f32_16x16x32_bf16 v[84:87], v[174:177], v[206:209], v[84:87]
	v_mfma_f32_16x16x32_bf16 v[84:87], v[178:181], v[210:213], v[84:87]
	v_mfma_f32_16x16x32_bf16 v[68:71], v[174:177], v[214:217], v[68:71]
	v_mfma_f32_16x16x32_bf16 v[68:71], v[178:181], v[218:221], v[68:71]
	v_mfma_f32_16x16x32_bf16 v[112:115], v[182:185], v[190:193], v[112:115]
	v_mfma_f32_16x16x32_bf16 v[112:115], v[186:189], v[194:197], v[112:115]
	v_mfma_f32_16x16x32_bf16 v[96:99], v[182:185], v[198:201], v[96:99]
	v_mfma_f32_16x16x32_bf16 v[96:99], v[186:189], v[202:205], v[96:99]
	v_mfma_f32_16x16x32_bf16 v[80:83], v[182:185], v[206:209], v[80:83]
	v_mfma_f32_16x16x32_bf16 v[80:83], v[186:189], v[210:213], v[80:83]
	v_mfma_f32_16x16x32_bf16 v[64:67], v[182:185], v[214:217], v[64:67]
	v_mfma_f32_16x16x32_bf16 v[64:67], v[186:189], v[218:221], v[64:67]
	s_setprio 0
	s_barrier
; #define PG8_STAGE(bufoff, gbase, voff) do { _Pragma("unroll") for (int _i = 0; _i < 2; ++_i) \
;         __builtin_amdgcn_global_load_lds((const unsigned*)((const char*)(gbase) + (voff)[_i]), (LAS unsigned*)(lds + (bufoff) + ldsw + _i * 8192), 16, 0, 0); } while (0)
; #define PG8_LDA(dst, b, h) do { _Pragma("unroll") for (int m = 0; m < 4; ++m) _Pragma("unroll") for (int k = 0; k < 2; ++k) dst[m][k] = *(const LAS bf16x8*)(lds + PG8_SA(b, h) + aoff + m * 2048 + k * 1024); } while (0)
; #define PG8_MMA(ai, bj, At, Bt) do { __builtin_amdgcn_s_setprio(1); _Pragma("unroll") for (int m = 0; m < 4; ++m) _Pragma("unroll") for (int n = 0; n < 2; ++n) _Pragma("unroll") for (int k = 0; k < 2; ++k) \
;         acc[ai][bj][m][n] = __builtin_amdgcn_mfma_f32_16x16x32_bf16(Bt[n][k], At[m][k], acc[ai][bj][m][n], 0, 0, 0); __builtin_amdgcn_s_setprio(0); } while (0)
; #define PG8_WAIT_V(n) asm volatile("s_waitcnt vmcnt(" #n ")" ::: "memory")
; #define PG8_WAIT_L(n) asm volatile("s_waitcnt lgkmcnt(" #n ")" ::: "memory")
; #define PG8_BAR __builtin_amdgcn_s_barrier()
; #define PG8_SCHED __builtin_amdgcn_sched_barrier(0)
; template <class EpiT>
; __device__ __forceinline__ void gemm_phase(LAS unsigned char* lds, const Gemm g, const StaticOrder& S, const EpiT& E) {
;     ...
;             PG8_LDA(At, 1, 1); PG8_STAGE(PG8_SB(1, 0), b3, voffB); PG8_STAGE(PG8_SB(1, 1), b3 + hstepB, voffB); PG8_STAGE(PG8_SA(1, 0), a3, voffA);
;             PG8_WAIT_V(8); PG8_WAIT_L(0); PG8_BAR; PG8_MMA(1, 0, At, B0); PG8_MMA(1, 1, At, B1); PG8_BAR; PG8_SCHED;
;         }
;         if (wr == 0) PG8_BAR;
	s_add_i32 s20, s54, s27
	v_lshl_add_u64 v[144:145], v[144:145], 0, s[10:11]
	s_mov_b32 m0, s20
	ds_read_b128 v[190:193], v152 offset:49152
	ds_read_b128 v[194:197], v152 offset:50176
	ds_read_b128 v[198:201], v152 offset:51200
	ds_read_b128 v[202:205], v152 offset:52224
	ds_read_b128 v[206:209], v152 offset:53248
	ds_read_b128 v[210:213], v152 offset:54272
	ds_read_b128 v[214:217], v152 offset:55296
	ds_read_b128 v[218:221], v152 offset:56320
	global_load_lds_dwordx4 v[144:145], off
	s_add_i32 m0, s20, 0x2000
	s_add_u32 s18, s18, 0x84080
	v_lshl_add_u64 v[144:145], v[166:167], 0, s[10:11]
	s_addc_u32 s19, s19, 0
	s_add_i32 s20, s55, s27
	global_load_lds_dwordx4 v[144:145], off
	v_lshl_add_u64 v[144:145], s[18:19], 0, v[132:133]
	s_mov_b32 m0, s20
	s_nop 0
	global_load_lds_dwordx4 v[144:145], off
	v_lshl_add_u64 v[144:145], s[18:19], 0, v[128:129]
	s_add_i32 m0, s20, 0x2000
	s_nop 0
	global_load_lds_dwordx4 v[144:145], off
	v_lshl_add_u64 v[144:145], v[222:223], 0, s[10:11]
	s_mov_b32 m0, s41
	s_nop 0
	global_load_lds_dwordx4 v[144:145], off
	v_lshl_add_u64 v[144:145], v[224:225], 0, s[10:11]
	s_mov_b32 m0, s42
	s_nop 0
	global_load_lds_dwordx4 v[144:145], off
	s_waitcnt vmcnt(8)
	s_waitcnt lgkmcnt(0)
	s_barrier
	s_setprio 1
	v_mfma_f32_16x16x32_bf16 v[60:63], v[154:157], v[190:193], v[60:63]
	v_mfma_f32_16x16x32_bf16 v[60:63], v[158:161], v[194:197], v[60:63]
	v_mfma_f32_16x16x32_bf16 v[44:47], v[154:157], v[198:201], v[44:47]
	v_mfma_f32_16x16x32_bf16 v[44:47], v[158:161], v[202:205], v[44:47]
	v_mfma_f32_16x16x32_bf16 v[28:31], v[154:157], v[206:209], v[28:31]
	v_mfma_f32_16x16x32_bf16 v[28:31], v[158:161], v[210:213], v[28:31]
	v_mfma_f32_16x16x32_bf16 v[12:15], v[154:157], v[214:217], v[12:15]
	v_mfma_f32_16x16x32_bf16 v[12:15], v[158:161], v[218:221], v[12:15]
	v_mfma_f32_16x16x32_bf16 v[56:59], v[162:165], v[190:193], v[56:59]
	v_mfma_f32_16x16x32_bf16 v[56:59], v[170:173], v[194:197], v[56:59]
	v_mfma_f32_16x16x32_bf16 v[40:43], v[162:165], v[198:201], v[40:43]
	v_mfma_f32_16x16x32_bf16 v[40:43], v[170:173], v[202:205], v[40:43]
	v_mfma_f32_16x16x32_bf16 v[24:27], v[162:165], v[206:209], v[24:27]
	v_mfma_f32_16x16x32_bf16 v[24:27], v[170:173], v[210:213], v[24:27]
	v_mfma_f32_16x16x32_bf16 v[8:11], v[162:165], v[214:217], v[8:11]
	v_mfma_f32_16x16x32_bf16 v[8:11], v[170:173], v[218:221], v[8:11]
	s_setprio 0
	s_setprio 1
	v_mfma_f32_16x16x32_bf16 v[52:55], v[174:177], v[190:193], v[52:55]
	v_mfma_f32_16x16x32_bf16 v[52:55], v[178:181], v[194:197], v[52:55]
	v_mfma_f32_16x16x32_bf16 v[36:39], v[174:177], v[198:201], v[36:39]
	v_mfma_f32_16x16x32_bf16 v[36:39], v[178:181], v[202:205], v[36:39]
	v_mfma_f32_16x16x32_bf16 v[20:23], v[174:177], v[206:209], v[20:23]
	v_mfma_f32_16x16x32_bf16 v[20:23], v[178:181], v[210:213], v[20:23]
	v_mfma_f32_16x16x32_bf16 v[4:7], v[174:177], v[214:217], v[4:7]
	v_mfma_f32_16x16x32_bf16 v[4:7], v[178:181], v[218:221], v[4:7]
	v_mfma_f32_16x16x32_bf16 v[48:51], v[182:185], v[190:193], v[48:51]
	v_mfma_f32_16x16x32_bf16 v[48:51], v[186:189], v[194:197], v[48:51]
	v_mfma_f32_16x16x32_bf16 v[32:35], v[182:185], v[198:201], v[32:35]
	v_mfma_f32_16x16x32_bf16 v[32:35], v[186:189], v[202:205], v[32:35]
	v_mfma_f32_16x16x32_bf16 v[16:19], v[182:185], v[206:209], v[16:19]
	v_mfma_f32_16x16x32_bf16 v[16:19], v[186:189], v[210:213], v[16:19]
	v_mfma_f32_16x16x32_bf16 v[0:3], v[182:185], v[214:217], v[0:3]
	v_mfma_f32_16x16x32_bf16 v[0:3], v[186:189], v[218:221], v[0:3]
	s_setprio 0
	s_barrier
	s_add_i32 s53, s53, 2
	s_add_u32 s16, s16, 0x100
	s_addc_u32 s17, s17, 0
	s_add_u32 s51, s51, 0x100
	s_addc_u32 s52, s52, 0
	s_cmp_gt_u32 s53, 29
	s_cbranch_scc0 .LBB0_1156
	s_and_b64 vcc, exec, s[12:13]
	s_cbranch_vccz .LBB0_1159
	s_barrier

; #define PG8_STAGE(bufoff, gbase, voff) do { _Pragma("unroll") for (int _i = 0; _i < 2; ++_i) \
;         __builtin_amdgcn_global_load_lds((const unsigned*)((const char*)(gbase) + (voff)[_i]), (LAS unsigned*)(lds + (bufoff) + ldsw + _i * 8192), 16, 0, 0); } while (0)
; #define PG8_LDA(dst, b, h) do { _Pragma("unroll") for (int m = 0; m < 4; ++m) _Pragma("unroll") for (int k = 0; k < 2; ++k) dst[m][k] = *(const LAS bf16x8*)(lds + PG8_SA(b, h) + aoff + m * 2048 + k * 1024); } while (0)
; #define PG8_LDB(dst, b, h) do { _Pragma("unroll") for (int n = 0; n < 2; ++n) _Pragma("unroll") for (int k = 0; k < 2; ++k) dst[n][k] = *(const LAS bf16x8*)(lds + PG8_SB(b, h) + boff + n * 2048 + k * 1024); } while (0)
; #define PG8_MMA(ai, bj, At, Bt) do { __builtin_amdgcn_s_setprio(1); _Pragma("unroll") for (int m = 0; m < 4; ++m) _Pragma("unroll") for (int n = 0; n < 2; ++n) _Pragma("unroll") for (int k = 0; k < 2; ++k) \
;         acc[ai][bj][m][n] = __builtin_amdgcn_mfma_f32_16x16x32_bf16(Bt[n][k], At[m][k], acc[ai][bj][m][n], 0, 0, 0); __builtin_amdgcn_s_setprio(0); } while (0)
; #define PG8_WAIT_V(n) asm volatile("s_waitcnt vmcnt(" #n ")" ::: "memory")
; #define PG8_WAIT_L(n) asm volatile("s_waitcnt lgkmcnt(" #n ")" ::: "memory")
; #define PG8_BAR __builtin_amdgcn_s_barrier()
; template <class EpiT>
; __device__ __forceinline__ void gemm_phase(LAS unsigned char* lds, const Gemm g, const StaticOrder& S, const EpiT& E) {
;     ...
;         const char* nA = has_next ? (const char*)g.A + (size_t)nxt.pm * tstepA + (size_t)nxt.pn * g.a_koff * 2 : cA; const char* nB = has_next ? (const char*)g.Bt + (size_t)nxt.pn * tstepB : cB;
;         for (int t = 0; t < nt; t += 2) {
;             const bool last = (t == nt - 2);
;             const char* a1 = cA + (size_t)(t + 1) * kstep;
;             const char* a2 = last ? nA : cA + (size_t)(t + 2) * kstep; const char* b2 = last ? nB : cB + (size_t)(t + 2) * kstep;
;             const char* a3 = a2 + kstep; const char* b3 = b2 + kstep;
;             PG8_LDB(B0, 0, 0); PG8_LDB(B1, 0, 1); PG8_SCHED; PG8_LDA(At, 0, 0); PG8_STAGE(PG8_SA(1, 1), a1 + hstepA, voffA);
;             PG8_WAIT_V(8); PG8_WAIT_L(0); PG8_BAR; PG8_MMA(0, 0, At, B0); PG8_MMA(0, 1, At, B1); PG8_BAR; PG8_SCHED;
;             PG8_LDA(At, 0, 1); PG8_STAGE(PG8_SB(0, 0), b2, voffB); PG8_STAGE(PG8_SB(0, 1), b2 + hstepB, voffB); PG8_STAGE(PG8_SA(0, 0), a2, voffA);
.LBB0_1235:
	ds_read_b128 v[154:157], v150
	ds_read_b128 v[158:161], v150 offset:1024
	ds_read_b128 v[162:165], v150 offset:2048
	ds_read_b128 v[170:173], v150 offset:3072
	ds_read_b128 v[174:177], v151
	ds_read_b128 v[178:181], v151 offset:1024
	ds_read_b128 v[182:185], v151 offset:2048
	ds_read_b128 v[186:189], v151 offset:3072
	s_add_u32 s20, s18, 0xffe9c080
	s_addc_u32 s21, s19, -1
	s_cmpk_eq_i32 s55, 0x54
	s_cselect_b32 s23, s5, s21
	s_cselect_b32 s22, s4, s20
	s_cselect_b32 s21, s17, s54
	s_cselect_b32 s20, s16, s53
	v_lshl_add_u64 v[166:167], s[18:19], 0, v[138:139]
	s_add_i32 m0, s37, 0xc000
	ds_read_b128 v[190:193], v152
	ds_read_b128 v[194:197], v152 offset:1024
	ds_read_b128 v[198:201], v152 offset:2048
	ds_read_b128 v[202:205], v152 offset:3072
	ds_read_b128 v[206:209], v152 offset:4096
	ds_read_b128 v[210:213], v152 offset:5120
	ds_read_b128 v[214:217], v152 offset:6144
	ds_read_b128 v[218:221], v152 offset:7168
	global_load_lds_dwordx4 v[166:167], off
	v_lshl_add_u64 v[166:167], s[18:19], 0, v[140:141]
	s_add_i32 m0, s37, 0xe000
	s_nop 0
	global_load_lds_dwordx4 v[166:167], off
	s_waitcnt vmcnt(8)
	s_waitcnt lgkmcnt(0)
	s_barrier
	s_setprio 1
	v_mfma_f32_16x16x32_bf16 v[124:127], v[154:157], v[190:193], v[124:127]
	v_mfma_f32_16x16x32_bf16 v[124:127], v[158:161], v[194:197], v[124:127]
	v_mfma_f32_16x16x32_bf16 v[108:111], v[154:157], v[198:201], v[108:111]
	v_mfma_f32_16x16x32_bf16 v[108:111], v[158:161], v[202:205], v[108:111]
	v_mfma_f32_16x16x32_bf16 v[92:95], v[154:157], v[206:209], v[92:95]
	v_mfma_f32_16x16x32_bf16 v[92:95], v[158:161], v[210:213], v[92:95]
	v_mfma_f32_16x16x32_bf16 v[76:79], v[154:157], v[214:217], v[76:79]
	v_mfma_f32_16x16x32_bf16 v[76:79], v[158:161], v[218:221], v[76:79]
	v_mfma_f32_16x16x32_bf16 v[120:123], v[162:165], v[190:193], v[120:123]
	v_mfma_f32_16x16x32_bf16 v[120:123], v[170:173], v[194:197], v[120:123]
	v_mfma_f32_16x16x32_bf16 v[104:107], v[162:165], v[198:201], v[104:107]
	v_mfma_f32_16x16x32_bf16 v[104:107], v[170:173], v[202:205], v[104:107]
	v_mfma_f32_16x16x32_bf16 v[88:91], v[162:165], v[206:209], v[88:91]
	v_mfma_f32_16x16x32_bf16 v[88:91], v[170:173], v[210:213], v[88:91]
	v_mfma_f32_16x16x32_bf16 v[72:75], v[162:165], v[214:217], v[72:75]
	v_mfma_f32_16x16x32_bf16 v[72:75], v[170:173], v[218:221], v[72:75]
	s_setprio 0
	s_setprio 1
	v_mfma_f32_16x16x32_bf16 v[116:119], v[174:177], v[190:193], v[116:119]
	v_mfma_f32_16x16x32_bf16 v[116:119], v[178:181], v[194:197], v[116:119]
	v_mfma_f32_16x16x32_bf16 v[100:103], v[174:177], v[198:201], v[100:103]
	v_mfma_f32_16x16x32_bf16 v[100:103], v[178:181], v[202:205], v[100:103]
	v_mfma_f32_16x16x32_bf16 v[84:87], v[174:177], v[206:209], v[84:87]
	v_mfma_f32_16x16x32_bf16 v[84:87], v[178:181], v[210:213], v[84:87]
	v_mfma_f32_16x16x32_bf16 v[68:71], v[174:177], v[214:217], v[68:71]
	v_mfma_f32_16x16x32_bf16 v[68:71], v[178:181], v[218:221], v[68:71]
	v_mfma_f32_16x16x32_bf16 v[112:115], v[182:185], v[190:193], v[112:115]
	v_mfma_f32_16x16x32_bf16 v[112:115], v[186:189], v[194:197], v[112:115]
	v_mfma_f32_16x16x32_bf16 v[96:99], v[182:185], v[198:201], v[96:99]
	v_mfma_f32_16x16x32_bf16 v[96:99], v[186:189], v[202:205], v[96:99]
	v_mfma_f32_16x16x32_bf16 v[80:83], v[182:185], v[206:209], v[80:83]
	v_mfma_f32_16x16x32_bf16 v[80:83], v[186:189], v[210:213], v[80:83]
	v_mfma_f32_16x16x32_bf16 v[64:67], v[182:185], v[214:217], v[64:67]
	v_mfma_f32_16x16x32_bf16 v[64:67], v[186:189], v[218:221], v[64:67]
	s_setprio 0
	s_barrier
	s_add_i32 s56, s46, s36
	v_lshl_add_u64 v[166:167], s[20:21], 0, v[130:131]
	s_mov_b32 m0, s56
	ds_read_b128 v[190:193], v152 offset:16384
	ds_read_b128 v[194:197], v152 offset:17408
	ds_read_b128 v[198:201], v152 offset:18432
	ds_read_b128 v[202:205], v152 offset:19456
	ds_read_b128 v[206:209], v152 offset:20480
	ds_read_b128 v[210:213], v152 offset:21504
	ds_read_b128 v[214:217], v152 offset:22528
	ds_read_b128 v[218:221], v152 offset:23552
	global_load_lds_dwordx4 v[166:167], off
	s_add_i32 m0, s56, 0x2000
	s_add_u32 s56, s20, 0x164000
	v_lshl_add_u64 v[222:223], s[20:21], 0, v[134:135]
	s_addc_u32 s57, s21, 0
	s_add_i32 s58, s47, s36
	global_load_lds_dwordx4 v[222:223], off
	v_lshl_add_u64 v[224:225], s[56:57], 0, v[130:131]
	s_mov_b32 m0, s58
	v_lshl_add_u64 v[226:227], s[22:23], 0, v[132:133]
	global_load_lds_dwordx4 v[224:225], off
	v_lshl_add_u64 v[224:225], s[56:57], 0, v[134:135]
	s_add_i32 m0, s58, 0x2000
	s_nop 0
	global_load_lds_dwordx4 v[224:225], off
	v_lshl_add_u64 v[224:225], s[22:23], 0, v[128:129]
	s_mov_b32 m0, s37
	s_nop 0
	global_load_lds_dwordx4 v[224:225], off
	s_mov_b32 m0, s38
	s_nop 0
	global_load_lds_dwordx4 v[226:227], off
	s_waitcnt vmcnt(8)
	s_waitcnt lgkmcnt(0)
	s_barrier
; #define PG8_STAGE(bufoff, gbase, voff) do { _Pragma("unroll") for (int _i = 0; _i < 2; ++_i) \
;         __builtin_amdgcn_global_load_lds((const unsigned*)((const char*)(gbase) + (voff)[_i]), (LAS unsigned*)(lds + (bufoff) + ldsw + _i * 8192), 16, 0, 0); } while (0)
; #define PG8_LDA(dst, b, h) do { _Pragma("unroll") for (int m = 0; m < 4; ++m) _Pragma("unroll") for (int k = 0; k < 2; ++k) dst[m][k] = *(const LAS bf16x8*)(lds + PG8_SA(b, h) + aoff + m * 2048 + k * 1024); } while (0)
; #define PG8_LDB(dst, b, h) do { _Pragma("unroll") for (int n = 0; n < 2; ++n) _Pragma("unroll") for (int k = 0; k < 2; ++k) dst[n][k] = *(const LAS bf16x8*)(lds + PG8_SB(b, h) + boff + n * 2048 + k * 1024); } while (0)
; #define PG8_MMA(ai, bj, At, Bt) do { __builtin_amdgcn_s_setprio(1); _Pragma("unroll") for (int m = 0; m < 4; ++m) _Pragma("unroll") for (int n = 0; n < 2; ++n) _Pragma("unroll") for (int k = 0; k < 2; ++k) \
;         acc[ai][bj][m][n] = __builtin_amdgcn_mfma_f32_16x16x32_bf16(Bt[n][k], At[m][k], acc[ai][bj][m][n], 0, 0, 0); __builtin_amdgcn_s_setprio(0); } while (0)
; #define PG8_WAIT_V(n) asm volatile("s_waitcnt vmcnt(" #n ")" ::: "memory")
; #define PG8_WAIT_L(n) asm volatile("s_waitcnt lgkmcnt(" #n ")" ::: "memory")
; #define PG8_BAR __builtin_amdgcn_s_barrier()
; #define PG8_SCHED __builtin_amdgcn_sched_barrier(0)
; template <class EpiT>
; __device__ __forceinline__ void gemm_phase(LAS unsigned char* lds, const Gemm g, const StaticOrder& S, const EpiT& E) {
;     ...
;             PG8_WAIT_V(8); PG8_WAIT_L(0); PG8_BAR; PG8_MMA(1, 0, At, B0); PG8_MMA(1, 1, At, B1); PG8_BAR; PG8_SCHED;
;             PG8_LDB(B0, 1, 0); PG8_LDB(B1, 1, 1); PG8_SCHED; PG8_LDA(At, 1, 0); PG8_STAGE(PG8_SA(0, 1), a2 + hstepA, voffA);
;             PG8_WAIT_V(8); PG8_WAIT_L(0); PG8_BAR; PG8_MMA(0, 0, At, B0); PG8_MMA(0, 1, At, B1); PG8_BAR; PG8_SCHED;
	s_setprio 1
	v_mfma_f32_16x16x32_bf16 v[60:63], v[154:157], v[190:193], v[60:63]
	v_mfma_f32_16x16x32_bf16 v[60:63], v[158:161], v[194:197], v[60:63]
	v_mfma_f32_16x16x32_bf16 v[44:47], v[154:157], v[198:201], v[44:47]
	v_mfma_f32_16x16x32_bf16 v[44:47], v[158:161], v[202:205], v[44:47]
	v_mfma_f32_16x16x32_bf16 v[28:31], v[154:157], v[206:209], v[28:31]
	v_mfma_f32_16x16x32_bf16 v[28:31], v[158:161], v[210:213], v[28:31]
	v_mfma_f32_16x16x32_bf16 v[12:15], v[154:157], v[214:217], v[12:15]
	v_mfma_f32_16x16x32_bf16 v[12:15], v[158:161], v[218:221], v[12:15]
	v_mfma_f32_16x16x32_bf16 v[56:59], v[162:165], v[190:193], v[56:59]
	v_mfma_f32_16x16x32_bf16 v[56:59], v[170:173], v[194:197], v[56:59]
	v_mfma_f32_16x16x32_bf16 v[40:43], v[162:165], v[198:201], v[40:43]
	v_mfma_f32_16x16x32_bf16 v[40:43], v[170:173], v[202:205], v[40:43]
	v_mfma_f32_16x16x32_bf16 v[24:27], v[162:165], v[206:209], v[24:27]
	v_mfma_f32_16x16x32_bf16 v[24:27], v[170:173], v[210:213], v[24:27]
	v_mfma_f32_16x16x32_bf16 v[8:11], v[162:165], v[214:217], v[8:11]
	v_mfma_f32_16x16x32_bf16 v[8:11], v[170:173], v[218:221], v[8:11]
	s_setprio 0
	s_setprio 1
	v_mfma_f32_16x16x32_bf16 v[52:55], v[174:177], v[190:193], v[52:55]
	v_mfma_f32_16x16x32_bf16 v[52:55], v[178:181], v[194:197], v[52:55]
	v_mfma_f32_16x16x32_bf16 v[36:39], v[174:177], v[198:201], v[36:39]
	v_mfma_f32_16x16x32_bf16 v[36:39], v[178:181], v[202:205], v[36:39]
	v_mfma_f32_16x16x32_bf16 v[20:23], v[174:177], v[206:209], v[20:23]
	v_mfma_f32_16x16x32_bf16 v[20:23], v[178:181], v[210:213], v[20:23]
	v_mfma_f32_16x16x32_bf16 v[4:7], v[174:177], v[214:217], v[4:7]
	v_mfma_f32_16x16x32_bf16 v[4:7], v[178:181], v[218:221], v[4:7]
	v_mfma_f32_16x16x32_bf16 v[48:51], v[182:185], v[190:193], v[48:51]
	v_mfma_f32_16x16x32_bf16 v[48:51], v[186:189], v[194:197], v[48:51]
	v_mfma_f32_16x16x32_bf16 v[32:35], v[182:185], v[198:201], v[32:35]
	v_mfma_f32_16x16x32_bf16 v[32:35], v[186:189], v[202:205], v[32:35]
	v_mfma_f32_16x16x32_bf16 v[16:19], v[182:185], v[206:209], v[16:19]
	v_mfma_f32_16x16x32_bf16 v[16:19], v[186:189], v[210:213], v[16:19]
	v_mfma_f32_16x16x32_bf16 v[0:3], v[182:185], v[214:217], v[0:3]
	v_mfma_f32_16x16x32_bf16 v[0:3], v[186:189], v[218:221], v[0:3]
	s_setprio 0
	s_barrier
	s_add_i32 s56, 0, 0x18000
	s_add_i32 s57, 0, 0x1c000
	v_add_u32_e32 v170, s56, v146
	v_add_u32_e32 v186, s57, v146
	ds_read_b128 v[154:157], v170
	ds_read_b128 v[158:161], v170 offset:1024
	ds_read_b128 v[162:165], v170 offset:2048
	ds_read_b128 v[170:173], v170 offset:3072
	ds_read_b128 v[174:177], v186
	ds_read_b128 v[178:181], v186 offset:1024
	ds_read_b128 v[182:185], v186 offset:2048
	ds_read_b128 v[186:189], v186 offset:3072
	s_add_u32 s22, s22, 0x164000
	s_addc_u32 s23, s23, 0
	s_mov_b32 m0, s39
	v_lshl_add_u64 v[228:229], s[22:23], 0, v[128:129]
	ds_read_b128 v[190:193], v152 offset:32768
	ds_read_b128 v[194:197], v152 offset:33792
	ds_read_b128 v[198:201], v152 offset:34816
	ds_read_b128 v[202:205], v152 offset:35840
	ds_read_b128 v[206:209], v152 offset:36864
	ds_read_b128 v[210:213], v152 offset:37888
	ds_read_b128 v[214:217], v152 offset:38912
	ds_read_b128 v[218:221], v152 offset:39936
	global_load_lds_dwordx4 v[228:229], off
	v_lshl_add_u64 v[228:229], s[22:23], 0, v[132:133]
	s_mov_b32 m0, s40
	s_nop 0
	global_load_lds_dwordx4 v[228:229], off
	s_waitcnt vmcnt(8)
	s_waitcnt lgkmcnt(0)
	s_barrier
	s_setprio 1
	v_mfma_f32_16x16x32_bf16 v[124:127], v[154:157], v[190:193], v[124:127]
	v_mfma_f32_16x16x32_bf16 v[124:127], v[158:161], v[194:197], v[124:127]
	v_mfma_f32_16x16x32_bf16 v[108:111], v[154:157], v[198:201], v[108:111]
	v_mfma_f32_16x16x32_bf16 v[108:111], v[158:161], v[202:205], v[108:111]
	v_mfma_f32_16x16x32_bf16 v[92:95], v[154:157], v[206:209], v[92:95]
	v_mfma_f32_16x16x32_bf16 v[92:95], v[158:161], v[210:213], v[92:95]
	v_mfma_f32_16x16x32_bf16 v[76:79], v[154:157], v[214:217], v[76:79]
	v_mfma_f32_16x16x32_bf16 v[76:79], v[158:161], v[218:221], v[76:79]
	v_mfma_f32_16x16x32_bf16 v[120:123], v[162:165], v[190:193], v[120:123]
	v_mfma_f32_16x16x32_bf16 v[120:123], v[170:173], v[194:197], v[120:123]
	v_mfma_f32_16x16x32_bf16 v[104:107], v[162:165], v[198:201], v[104:107]
	v_mfma_f32_16x16x32_bf16 v[104:107], v[170:173], v[202:205], v[104:107]
	v_mfma_f32_16x16x32_bf16 v[88:91], v[162:165], v[206:209], v[88:91]
	v_mfma_f32_16x16x32_bf16 v[88:91], v[170:173], v[210:213], v[88:91]
	v_mfma_f32_16x16x32_bf16 v[72:75], v[162:165], v[214:217], v[72:75]
	v_mfma_f32_16x16x32_bf16 v[72:75], v[170:173], v[218:221], v[72:75]
	s_setprio 0
	s_setprio 1
	v_mfma_f32_16x16x32_bf16 v[116:119], v[174:177], v[190:193], v[116:119]
	v_mfma_f32_16x16x32_bf16 v[116:119], v[178:181], v[194:197], v[116:119]
	v_mfma_f32_16x16x32_bf16 v[100:103], v[174:177], v[198:201], v[100:103]
	v_mfma_f32_16x16x32_bf16 v[100:103], v[178:181], v[202:205], v[100:103]
	v_mfma_f32_16x16x32_bf16 v[84:87], v[174:177], v[206:209], v[84:87]
	v_mfma_f32_16x16x32_bf16 v[84:87], v[178:181], v[210:213], v[84:87]
	v_mfma_f32_16x16x32_bf16 v[68:71], v[174:177], v[214:217], v[68:71]
	v_mfma_f32_16x16x32_bf16 v[68:71], v[178:181], v[218:221], v[68:71]
	v_mfma_f32_16x16x32_bf16 v[112:115], v[182:185], v[190:193], v[112:115]
	v_mfma_f32_16x16x32_bf16 v[112:115], v[186:189], v[194:197], v[112:115]
	v_mfma_f32_16x16x32_bf16 v[96:99], v[182:185], v[198:201], v[96:99]
	v_mfma_f32_16x16x32_bf16 v[96:99], v[186:189], v[202:205], v[96:99]
	v_mfma_f32_16x16x32_bf16 v[80:83], v[182:185], v[206:209], v[80:83]
	v_mfma_f32_16x16x32_bf16 v[80:83], v[186:189], v[210:213], v[80:83]
	v_mfma_f32_16x16x32_bf16 v[64:67], v[182:185], v[214:217], v[64:67]
	v_mfma_f32_16x16x32_bf16 v[64:67], v[186:189], v[218:221], v[64:67]
	s_setprio 0
	s_barrier
; #define PG8_STAGE(bufoff, gbase, voff) do { _Pragma("unroll") for (int _i = 0; _i < 2; ++_i) \
;         __builtin_amdgcn_global_load_lds((const unsigned*)((const char*)(gbase) + (voff)[_i]), (LAS unsigned*)(lds + (bufoff) + ldsw + _i * 8192), 16, 0, 0); } while (0)
; #define PG8_LDA(dst, b, h) do { _Pragma("unroll") for (int m = 0; m < 4; ++m) _Pragma("unroll") for (int k = 0; k < 2; ++k) dst[m][k] = *(const LAS bf16x8*)(lds + PG8_SA(b, h) + aoff + m * 2048 + k * 1024); } while (0)
; #define PG8_MMA(ai, bj, At, Bt) do { __builtin_amdgcn_s_setprio(1); _Pragma("unroll") for (int m = 0; m < 4; ++m) _Pragma("unroll") for (int n = 0; n < 2; ++n) _Pragma("unroll") for (int k = 0; k < 2; ++k) \
;         acc[ai][bj][m][n] = __builtin_amdgcn_mfma_f32_16x16x32_bf16(Bt[n][k], At[m][k], acc[ai][bj][m][n], 0, 0, 0); __builtin_amdgcn_s_setprio(0); } while (0)
; #define PG8_WAIT_V(n) asm volatile("s_waitcnt vmcnt(" #n ")" ::: "memory")
; #define PG8_WAIT_L(n) asm volatile("s_waitcnt lgkmcnt(" #n ")" ::: "memory")
; #define PG8_BAR __builtin_amdgcn_s_barrier()
; #define PG8_SCHED __builtin_amdgcn_sched_barrier(0)
; template <class EpiT>
; __device__ __forceinline__ void gemm_phase(LAS unsigned char* lds, const Gemm g, const StaticOrder& S, const EpiT& E) {
;     ...
;             PG8_LDA(At, 1, 1); PG8_STAGE(PG8_SB(1, 0), b3, voffB); PG8_STAGE(PG8_SB(1, 1), b3 + hstepB, voffB); PG8_STAGE(PG8_SA(1, 0), a3, voffA);
;             PG8_WAIT_V(8); PG8_WAIT_L(0); PG8_BAR; PG8_MMA(1, 0, At, B0); PG8_MMA(1, 1, At, B1); PG8_BAR; PG8_SCHED;
;         }
;         if (wr == 0) PG8_BAR;
	s_add_i32 s22, s56, s36
	v_lshl_add_u64 v[166:167], v[166:167], 0, s[12:13]
	s_mov_b32 m0, s22
	ds_read_b128 v[190:193], v152 offset:49152
	ds_read_b128 v[194:197], v152 offset:50176
	ds_read_b128 v[198:201], v152 offset:51200
	ds_read_b128 v[202:205], v152 offset:52224
	ds_read_b128 v[206:209], v152 offset:53248
	ds_read_b128 v[210:213], v152 offset:54272
	ds_read_b128 v[214:217], v152 offset:55296
	ds_read_b128 v[218:221], v152 offset:56320
	global_load_lds_dwordx4 v[166:167], off
	s_add_i32 m0, s22, 0x2000
	s_add_u32 s20, s20, 0x164080
	v_lshl_add_u64 v[166:167], v[222:223], 0, s[12:13]
	s_addc_u32 s21, s21, 0
	s_add_i32 s22, s57, s36
	global_load_lds_dwordx4 v[166:167], off
	v_lshl_add_u64 v[166:167], s[20:21], 0, v[130:131]
	s_mov_b32 m0, s22
	s_nop 0
	global_load_lds_dwordx4 v[166:167], off
	v_lshl_add_u64 v[166:167], s[20:21], 0, v[134:135]
	s_add_i32 m0, s22, 0x2000
	s_nop 0
	global_load_lds_dwordx4 v[166:167], off
	v_lshl_add_u64 v[166:167], v[224:225], 0, s[12:13]
	s_mov_b32 m0, s42
	s_nop 0
	global_load_lds_dwordx4 v[166:167], off
	v_lshl_add_u64 v[166:167], v[226:227], 0, s[12:13]
	s_mov_b32 m0, s43
	s_nop 0
	global_load_lds_dwordx4 v[166:167], off
	s_waitcnt vmcnt(8)
	s_waitcnt lgkmcnt(0)
	s_barrier
	s_setprio 1
	v_mfma_f32_16x16x32_bf16 v[60:63], v[154:157], v[190:193], v[60:63]
	v_mfma_f32_16x16x32_bf16 v[60:63], v[158:161], v[194:197], v[60:63]
	v_mfma_f32_16x16x32_bf16 v[44:47], v[154:157], v[198:201], v[44:47]
	v_mfma_f32_16x16x32_bf16 v[44:47], v[158:161], v[202:205], v[44:47]
	v_mfma_f32_16x16x32_bf16 v[28:31], v[154:157], v[206:209], v[28:31]
	v_mfma_f32_16x16x32_bf16 v[28:31], v[158:161], v[210:213], v[28:31]
	v_mfma_f32_16x16x32_bf16 v[12:15], v[154:157], v[214:217], v[12:15]
	v_mfma_f32_16x16x32_bf16 v[12:15], v[158:161], v[218:221], v[12:15]
	v_mfma_f32_16x16x32_bf16 v[56:59], v[162:165], v[190:193], v[56:59]
	v_mfma_f32_16x16x32_bf16 v[56:59], v[170:173], v[194:197], v[56:59]
	v_mfma_f32_16x16x32_bf16 v[40:43], v[162:165], v[198:201], v[40:43]
	v_mfma_f32_16x16x32_bf16 v[40:43], v[170:173], v[202:205], v[40:43]
	v_mfma_f32_16x16x32_bf16 v[24:27], v[162:165], v[206:209], v[24:27]
	v_mfma_f32_16x16x32_bf16 v[24:27], v[170:173], v[210:213], v[24:27]
	v_mfma_f32_16x16x32_bf16 v[8:11], v[162:165], v[214:217], v[8:11]
	v_mfma_f32_16x16x32_bf16 v[8:11], v[170:173], v[218:221], v[8:11]
	s_setprio 0
	s_setprio 1
	v_mfma_f32_16x16x32_bf16 v[52:55], v[174:177], v[190:193], v[52:55]
	v_mfma_f32_16x16x32_bf16 v[52:55], v[178:181], v[194:197], v[52:55]
	v_mfma_f32_16x16x32_bf16 v[36:39], v[174:177], v[198:201], v[36:39]
	v_mfma_f32_16x16x32_bf16 v[36:39], v[178:181], v[202:205], v[36:39]
	v_mfma_f32_16x16x32_bf16 v[20:23], v[174:177], v[206:209], v[20:23]
	v_mfma_f32_16x16x32_bf16 v[20:23], v[178:181], v[210:213], v[20:23]
	v_mfma_f32_16x16x32_bf16 v[4:7], v[174:177], v[214:217], v[4:7]
	v_mfma_f32_16x16x32_bf16 v[4:7], v[178:181], v[218:221], v[4:7]
	v_mfma_f32_16x16x32_bf16 v[48:51], v[182:185], v[190:193], v[48:51]
	v_mfma_f32_16x16x32_bf16 v[48:51], v[186:189], v[194:197], v[48:51]
	v_mfma_f32_16x16x32_bf16 v[32:35], v[182:185], v[198:201], v[32:35]
	v_mfma_f32_16x16x32_bf16 v[32:35], v[186:189], v[202:205], v[32:35]
	v_mfma_f32_16x16x32_bf16 v[16:19], v[182:185], v[206:209], v[16:19]
	v_mfma_f32_16x16x32_bf16 v[16:19], v[186:189], v[210:213], v[16:19]
	v_mfma_f32_16x16x32_bf16 v[0:3], v[182:185], v[214:217], v[0:3]
	v_mfma_f32_16x16x32_bf16 v[0:3], v[186:189], v[218:221], v[0:3]
	s_setprio 0
	s_barrier
	s_add_i32 s55, s55, 2
	s_add_u32 s18, s18, 0x100
	s_addc_u32 s19, s19, 0
	s_add_u32 s53, s53, 0x100
	s_addc_u32 s54, s54, 0
	s_cmpk_gt_u32 s55, 0x55
	s_cbranch_scc0 .LBB0_1235
	s_and_b64 vcc, exec, s[14:15]
	s_cbranch_vccz .LBB0_1238
	s_barrier
